# hyena: merged twin pk_fma constant-twiddle pairs (39 sites), SD8 coefficient load hoisted beside SD loads, address-xor filler nops removed
# speedup vs baseline: 1.0110x; 1.0110x over previous
; #define LAS __attribute__((address_space(3)))
; template <bool INV, bool HALFIN = false> __device__ __forceinline__ void dft16(cf (&x)[16]) {
; #pragma unroll
;     for (int m2 = 0; m2 < 4; ++m2) {
;         if (HALFIN) { const cf a0 = x[m2], a1 = x[4 + m2]; x[m2] = a0 + a1; x[8 + m2] = a0 - a1; x[4 + m2] = add_mib(a0, a1); x[12 + m2] = add_pib(a0, a1); }
;         else dft4<INV>(x[m2], x[4 + m2], x[8 + m2], x[12 + m2]);
;     }
;     constexpr float C1 = 0.9238795325112867f, S1 = 0.3826834323650898f, C2 = 0.7071067811865476f;
;     x[4 * 1 + 1] = tw16<INV>(x[5], C1, S1);  x[4 * 1 + 2] = tw16<INV>(x[6], C2, C2);   x[4 * 1 + 3] = tw16<INV>(x[7], S1, C1);
;     x[4 * 2 + 1] = tw16<INV>(x[9], C2, C2);  x[4 * 2 + 2] = tw16<INV>(x[10], 0.f, 1.f); x[4 * 2 + 3] = tw16<INV>(x[11], -C2, C2);
;     x[4 * 3 + 1] = tw16<INV>(x[13], S1, C1); x[4 * 3 + 2] = tw16<INV>(x[14], -C2, C2); x[4 * 3 + 3] = tw16<INV>(x[15], -C1, -S1);
; #pragma unroll
;     for (int q1 = 0; q1 < 4; ++q1) dft4<INV>(x[4 * q1], x[4 * q1 + 1], x[4 * q1 + 2], x[4 * q1 + 3]);
; }
; template <int LST> __device__ __forceinline__ int pass_pos(int base, int phb, int m) {
;     if (LST == 10) return phb + (m << 10);
;     if (LST == 6) return (base ^ (m << 2)) + (m << 6);
;     return PH(base + (m << LST));
; }
; template <bool INV, int LST, bool HALF = false> __device__ __forceinline__ void fft_pass16(LAS cf* z, const LAS cf* Thi, const LAS cf* Tlo, int tid) {
;     constexpr int st = 1 << LST;
;     cf w[16];
; #pragma unroll 1
;     for (int it = 0; it < 2; ++it) {
;         const int g = tid + 512 * it; const int j0 = g & (st - 1); const int base = ((g >> LST) << (LST + 4)) + j0; const int phb = PH(base);
;         if (LST == 10 || it == 0) {
;             const int e1 = j0 << (10 - LST);
;             w[1] = cmul(Thi[e1 >> 7], Tlo[e1 & 127]);
;             w[2] = cmul(w[1], w[1]); w[3] = cmul(w[2], w[1]); w[4] = cmul(w[2], w[2]); w[5] = cmul(w[4], w[1]); w[6] = cmul(w[3], w[3]); w[7] = cmul(w[4], w[3]); w[8] = cmul(w[4], w[4]);
; #pragma unroll
;             for (int q = 9; q < 16; ++q) w[q] = cmul(w[8], w[q - 8]);
;         }
;         cf x[16];
;         if (!INV) {
; #pragma unroll
;             for (int m = 0; m < 16; ++m) { if (HALF && m >= 8) x[m] = (cf){0.f, 0.f}; else x[m] = z[pass_pos<LST>(base, phb, m)]; }
;             dft16<false, HALF>(x);
; #pragma unroll
.LBB0_300:
	v_add_u32_e32 v16, s47, v152
	v_and_b32_e32 v17, 0x3ff, v16
	v_lshlrev_b32_e32 v18, 4, v16
	v_lshrrev_b32_e32 v16, 4, v16
	v_and_b32_e32 v18, 0x4000, v18
	v_and_b32_e32 v19, 60, v16
	v_and_b32_e32 v16, 56, v16
	v_bitop3_b32 v17, v18, v19, v17 bitop3:0x36
	v_add_u32_e32 v16, 0, v16
	v_lshl_add_u32 v86, v17, 3, 0
	v_add_u32_e32 v32, 0x20000, v16
	ds_read2st64_b64 v[16:19], v86 offset1:16
	ds_read2st64_b64 v[20:23], v86 offset0:32 offset1:48
	ds_read2st64_b64 v[24:27], v86 offset0:64 offset1:80
	ds_read2st64_b64 v[28:31], v86 offset0:96 offset1:112
	v_add_u32_e32 v87, 0x10000, v86
	v_add_u32_e32 v88, 0x12000, v86
	v_add_u32_e32 v89, 0x14000, v86
	v_add_u32_e32 v90, 0x16000, v86
	v_add_u32_e32 v91, 0x18000, v86
	v_add_u32_e32 v92, 0x1a000, v86
	v_add_u32_e32 v93, 0x1c000, v86
	v_add_u32_e32 v94, 0x1e000, v86
	ds_read_b64 v[32:33], v32
	ds_read_b64 v[34:35], v87
	ds_read_b64 v[36:37], v88
	ds_read_b64 v[38:39], v158
	ds_read_b64 v[40:41], v89
	ds_read_b64 v[42:43], v90
	ds_read_b64 v[44:45], v91
	ds_read_b64 v[46:47], v92
	ds_read_b64 v[48:49], v93
	ds_read_b64 v[50:51], v94
	s_waitcnt lgkmcnt(8)
	v_pk_add_f32 v[54:55], v[16:17], v[34:35]
	v_pk_add_f32 v[16:17], v[16:17], v[34:35] neg_lo:[0,1] neg_hi:[0,1]
	s_waitcnt lgkmcnt(3)
	v_pk_add_f32 v[34:35], v[24:25], v[44:45]
	v_pk_add_f32 v[24:25], v[24:25], v[44:45] neg_lo:[0,1] neg_hi:[0,1]
	v_pk_add_f32 v[44:45], v[18:19], v[36:37]
	v_pk_add_f32 v[18:19], v[18:19], v[36:37] neg_lo:[0,1] neg_hi:[0,1]
	s_waitcnt lgkmcnt(2)
	v_pk_add_f32 v[36:37], v[26:27], v[46:47]
	v_pk_add_f32 v[26:27], v[26:27], v[46:47] neg_lo:[0,1] neg_hi:[0,1]
	v_pk_add_f32 v[46:47], v[20:21], v[40:41]
	v_pk_add_f32 v[20:21], v[20:21], v[40:41] neg_lo:[0,1] neg_hi:[0,1]
	s_waitcnt lgkmcnt(1)
	v_pk_add_f32 v[40:41], v[28:29], v[48:49]
	v_pk_mul_f32 v[52:53], v[32:33], v[38:39] op_sel:[0,0] op_sel_hi:[0,1]
	v_pk_add_f32 v[28:29], v[28:29], v[48:49] neg_lo:[0,1] neg_hi:[0,1]
	v_pk_add_f32 v[48:49], v[22:23], v[42:43]
	v_pk_add_f32 v[22:23], v[22:23], v[42:43] neg_lo:[0,1] neg_hi:[0,1]
	s_waitcnt lgkmcnt(0)
	v_pk_add_f32 v[42:43], v[30:31], v[50:51]
	v_pk_add_f32 v[30:31], v[30:31], v[50:51] neg_lo:[0,1] neg_hi:[0,1]
	v_pk_add_f32 v[50:51], v[16:17], v[24:25] op_sel:[0,1] op_sel_hi:[1,0] neg_hi:[0,1]
	v_pk_add_f32 v[16:17], v[16:17], v[24:25] op_sel:[0,1] op_sel_hi:[1,0] neg_lo:[0,1]
	v_pk_add_f32 v[24:25], v[44:45], v[36:37]
	v_pk_add_f32 v[36:37], v[44:45], v[36:37] neg_lo:[0,1] neg_hi:[0,1]
	v_pk_add_f32 v[44:45], v[18:19], v[26:27] op_sel:[0,1] op_sel_hi:[1,0] neg_hi:[0,1]
	v_pk_add_f32 v[18:19], v[18:19], v[26:27] op_sel:[0,1] op_sel_hi:[1,0] neg_lo:[0,1]
	v_pk_add_f32 v[26:27], v[46:47], v[40:41]
	v_pk_add_f32 v[40:41], v[46:47], v[40:41] neg_lo:[0,1] neg_hi:[0,1]
	v_pk_fma_f32 v[32:33], v[32:33], v[38:39], v[52:53] op_sel:[1,1,0] op_sel_hi:[1,0,1] neg_lo:[1,0,0]
	v_pk_add_f32 v[38:39], v[54:55], v[34:35]
	v_pk_add_f32 v[34:35], v[54:55], v[34:35] neg_lo:[0,1] neg_hi:[0,1]
	v_pk_add_f32 v[46:47], v[20:21], v[28:29] op_sel:[0,1] op_sel_hi:[1,0] neg_hi:[0,1]
	v_pk_add_f32 v[20:21], v[20:21], v[28:29] op_sel:[0,1] op_sel_hi:[1,0] neg_lo:[0,1]
	v_pk_add_f32 v[28:29], v[48:49], v[42:43]
	v_pk_add_f32 v[42:43], v[48:49], v[42:43] neg_lo:[0,1] neg_hi:[0,1]
	v_pk_add_f32 v[48:49], v[22:23], v[30:31] op_sel:[0,1] op_sel_hi:[1,0] neg_hi:[0,1]
	v_pk_add_f32 v[22:23], v[22:23], v[30:31] op_sel:[0,1] op_sel_hi:[1,0] neg_lo:[0,1]
	v_pk_mul_f32 v[30:31], v[32:33], v[32:33] op_sel:[0,0] op_sel_hi:[0,1]
	v_pk_mul_f32 v[52:53], v[44:45], s[24:25] op_sel_hi:[1,0]
	v_pk_mul_f32 v[54:55], v[46:47], s[38:39] op_sel_hi:[1,0]
	v_pk_mul_f32 v[56:57], v[48:49], s[22:23] op_sel_hi:[1,0]
	v_pk_fma_f32 v[60:61], v[40:41], 0, v[40:41] op_sel:[0,0,1] op_sel_hi:[1,0,0]
	v_pk_fma_f32 v[40:41], v[40:41], 0, v[40:41] op_sel:[0,0,1] op_sel_hi:[1,0,0] neg_lo:[0,0,1] neg_hi:[0,0,1]
	v_pk_mul_f32 v[58:59], v[36:37], s[38:39] op_sel_hi:[1,0]
	v_mul_f32_e32 v40, 0x3f3504f3, v42
	v_pk_mul_f32 v[62:63], v[18:19], s[22:23] op_sel_hi:[1,0]
	v_pk_add_f32 v[68:69], v[38:39], v[26:27]
	v_pk_add_f32 v[26:27], v[38:39], v[26:27] neg_lo:[0,1] neg_hi:[0,1]
	v_pk_add_f32 v[38:39], v[24:25], v[28:29]
	v_pk_add_f32 v[24:25], v[24:25], v[28:29] neg_lo:[0,1] neg_hi:[0,1]
	v_pk_fma_f32 v[28:29], v[32:33], v[32:33], v[30:31] op_sel:[1,1,0] op_sel_hi:[1,0,1] neg_lo:[1,0,0]
	v_pk_fma_f32 v[30:31], v[44:45], s[22:23], v[52:53] op_sel:[0,0,1] op_sel_hi:[1,0,0] neg_hi:[0,0,1]
	v_pk_fma_f32 v[52:53], v[46:47], s[38:39], v[54:55] op_sel:[0,0,1] op_sel_hi:[1,0,0] neg_hi:[0,0,1]
	v_pk_fma_f32 v[54:55], v[48:49], s[24:25], v[56:57] op_sel:[0,0,1] op_sel_hi:[1,0,0] neg_hi:[0,0,1]
	s_mov_b32 s54, s43
	s_mov_b32 s55, s24
	v_mul_f32_e32 v64, 0x3f3504f3, v20
	v_pk_mul_f32 v[66:67], v[22:23], s[42:43] op_sel:[1,0]
	v_pk_fma_f32 v[56:57], v[36:37], s[38:39], v[58:59] op_sel:[0,0,1] op_sel_hi:[1,0,0] neg_hi:[0,0,1]
	v_mov_b32_e32 v61, v41
	v_pk_fma_f32 v[40:41], v[42:43], s[38:39], v[40:41] op_sel:[1,0,0] op_sel_hi:[1,1,0] neg_lo:[0,0,1] neg_hi:[0,0,1]
	v_pk_fma_f32 v[42:43], v[18:19], s[24:25], v[62:63] op_sel:[0,0,1] op_sel_hi:[1,0,0] neg_hi:[0,0,1]
	v_pk_fma_f32 v[20:21], v[20:21], s[38:39], v[64:65] op_sel:[1,0,0] op_sel_hi:[1,1,0] neg_lo:[0,0,1] neg_hi:[0,0,1]
	v_pk_fma_f32 v[22:23], v[22:23], s[54:55], v[66:67] op_sel_hi:[0,1,1]
	v_pk_add_f32 v[58:59], v[68:69], v[38:39] neg_lo:[0,1] neg_hi:[0,1]
	v_pk_add_f32 v[62:63], v[26:27], v[24:25] op_sel:[0,1] op_sel_hi:[1,0] neg_hi:[0,1]
	v_pk_add_f32 v[24:25], v[26:27], v[24:25] op_sel:[0,1] op_sel_hi:[1,0] neg_lo:[0,1]
	v_pk_add_f32 v[26:27], v[68:69], v[38:39]
	v_pk_mul_f32 v[38:39], v[28:29], v[32:33] op_sel:[0,0] op_sel_hi:[0,1]
; template <bool INV, int LST, bool HALF = false> __device__ __forceinline__ void fft_pass16(LAS cf* z, const LAS cf* Thi, const LAS cf* Tlo, int tid) {
;     ...
;         const int g = tid + 512 * it; const int j0 = g & (st - 1); const int base = ((g >> LST) << (LST + 4)) + j0; const int phb = PH(base);
;         if (LST == 10 || it == 0) {
;             const int e1 = j0 << (10 - LST);
;             w[1] = cmul(Thi[e1 >> 7], Tlo[e1 & 127]);
;             w[2] = cmul(w[1], w[1]); w[3] = cmul(w[2], w[1]); w[4] = cmul(w[2], w[2]); w[5] = cmul(w[4], w[1]); w[6] = cmul(w[3], w[3]); w[7] = cmul(w[4], w[3]); w[8] = cmul(w[4], w[4]);
; #pragma unroll
;             for (int q = 9; q < 16; ++q) w[q] = cmul(w[8], w[q - 8]);
;         }
;         cf x[16];
;         if (!INV) {
; #pragma unroll
;             for (int m = 0; m < 16; ++m) { if (HALF && m >= 8) x[m] = (cf){0.f, 0.f}; else x[m] = z[pass_pos<LST>(base, phb, m)]; }
;             dft16<false, HALF>(x);
; #pragma unroll
;             for (int q = 0; q < 16; ++q) { cf y = x[4 * (q & 3) + (q >> 2)]; if (q) y = cmul(y, w[q]); z[pass_pos<LST>(base, phb, q)] = y; }
	v_pk_mul_f32 v[64:65], v[28:29], v[28:29] op_sel:[0,0] op_sel_hi:[0,1]
	v_pk_add_f32 v[44:45], v[50:51], v[52:53]
	v_pk_add_f32 v[48:49], v[30:31], v[54:55]
	v_pk_add_f32 v[18:19], v[34:35], v[60:61]
	v_pk_add_f32 v[34:35], v[34:35], v[60:61] neg_lo:[0,1] neg_hi:[0,1]
	v_pk_add_f32 v[36:37], v[16:17], v[20:21]
	v_pk_add_f32 v[16:17], v[16:17], v[20:21] neg_lo:[0,1] neg_hi:[0,1]
	v_pk_fma_f32 v[20:21], v[28:29], v[32:33], v[38:39] op_sel:[1,1,0] op_sel_hi:[1,0,1] neg_lo:[1,0,0]
	v_pk_fma_f32 v[38:39], v[28:29], v[28:29], v[64:65] op_sel:[1,1,0] op_sel_hi:[1,0,1] neg_lo:[1,0,0]
	v_pk_add_f32 v[46:47], v[50:51], v[52:53] neg_lo:[0,1] neg_hi:[0,1]
	v_pk_add_f32 v[30:31], v[30:31], v[54:55] neg_lo:[0,1] neg_hi:[0,1]
	v_pk_add_f32 v[50:51], v[56:57], v[40:41]
	v_pk_add_f32 v[40:41], v[56:57], v[40:41] neg_lo:[0,1] neg_hi:[0,1]
	v_pk_add_f32 v[52:53], v[42:43], v[22:23]
	v_pk_add_f32 v[22:23], v[42:43], v[22:23] neg_lo:[0,1] neg_hi:[0,1]
	v_pk_add_f32 v[64:65], v[44:45], v[48:49]
	v_pk_mul_f32 v[42:43], v[38:39], v[32:33] op_sel:[0,0] op_sel_hi:[0,1]
	v_pk_mul_f32 v[60:61], v[38:39], v[38:39] op_sel:[0,0] op_sel_hi:[0,1]
	v_pk_add_f32 v[44:45], v[44:45], v[48:49] neg_lo:[0,1] neg_hi:[0,1]
	v_pk_add_f32 v[48:49], v[46:47], v[30:31] op_sel:[0,1] op_sel_hi:[1,0] neg_hi:[0,1]
	v_pk_add_f32 v[30:31], v[46:47], v[30:31] op_sel:[0,1] op_sel_hi:[1,0] neg_lo:[0,1]
	v_pk_add_f32 v[46:47], v[18:19], v[50:51]
	v_pk_add_f32 v[18:19], v[18:19], v[50:51] neg_lo:[0,1] neg_hi:[0,1]
	v_pk_add_f32 v[50:51], v[34:35], v[40:41] op_sel:[0,1] op_sel_hi:[1,0] neg_hi:[0,1]
	v_pk_add_f32 v[34:35], v[34:35], v[40:41] op_sel:[0,1] op_sel_hi:[1,0] neg_lo:[0,1]
	v_pk_add_f32 v[40:41], v[36:37], v[52:53]
	v_pk_add_f32 v[36:37], v[36:37], v[52:53] neg_lo:[0,1] neg_hi:[0,1]
	v_pk_add_f32 v[52:53], v[16:17], v[22:23] op_sel:[0,1] op_sel_hi:[1,0] neg_hi:[0,1]
	v_pk_add_f32 v[16:17], v[16:17], v[22:23] op_sel:[0,1] op_sel_hi:[1,0] neg_lo:[0,1]
	v_pk_mul_f32 v[22:23], v[62:63], v[38:39] op_sel:[0,0] op_sel_hi:[0,1]
	v_pk_mul_f32 v[66:67], v[64:65], v[32:33] op_sel:[0,0] op_sel_hi:[0,1]
	v_pk_mul_f32 v[54:55], v[20:21], v[20:21] op_sel:[0,0] op_sel_hi:[0,1]
	v_pk_mul_f32 v[56:57], v[38:39], v[20:21] op_sel:[0,0] op_sel_hi:[0,1]
	v_pk_fma_f32 v[42:43], v[38:39], v[32:33], v[42:43] op_sel:[1,1,0] op_sel_hi:[1,0,1] neg_lo:[1,0,0]
	v_pk_fma_f32 v[60:61], v[38:39], v[38:39], v[60:61] op_sel:[1,1,0] op_sel_hi:[1,0,1] neg_lo:[1,0,0]
	v_pk_mul_f32 v[68:69], v[46:47], v[28:29] op_sel:[0,0] op_sel_hi:[0,1]
	s_nop 0
	v_pk_fma_f32 v[64:65], v[64:65], v[32:33], v[66:67] op_sel:[1,1,0] op_sel_hi:[1,0,1] neg_lo:[1,0,0]
	v_pk_mul_f32 v[70:71], v[40:41], v[20:21] op_sel:[0,0] op_sel_hi:[0,1]
	v_pk_fma_f32 v[22:23], v[62:63], v[38:39], v[22:23] op_sel:[1,1,0] op_sel_hi:[1,0,1] neg_lo:[1,0,0]
	v_pk_mul_f32 v[66:67], v[48:49], v[42:43] op_sel:[0,0] op_sel_hi:[0,1]
	v_pk_mul_f32 v[62:63], v[60:61], v[32:33] op_sel:[0,0] op_sel_hi:[0,1]
	v_pk_fma_f32 v[46:47], v[46:47], v[28:29], v[68:69] op_sel:[1,1,0] op_sel_hi:[1,0,1] neg_lo:[1,0,0]
	v_pk_fma_f32 v[54:55], v[20:21], v[20:21], v[54:55] op_sel:[1,1,0] op_sel_hi:[1,0,1] neg_lo:[1,0,0]
	s_nop 0
	v_pk_fma_f32 v[40:41], v[40:41], v[20:21], v[70:71] op_sel:[1,1,0] op_sel_hi:[1,0,1] neg_lo:[1,0,0]
	ds_write2st64_b64 v86, v[26:27], v[64:65] offset1:16
	ds_write2st64_b64 v86, v[46:47], v[40:41] offset0:32 offset1:48
	v_pk_fma_f32 v[26:27], v[48:49], v[42:43], v[66:67] op_sel:[1,1,0] op_sel_hi:[1,0,1] neg_lo:[1,0,0]
	v_pk_fma_f32 v[56:57], v[38:39], v[20:21], v[56:57] op_sel:[1,1,0] op_sel_hi:[1,0,1] neg_lo:[1,0,0]
	v_pk_mul_f32 v[78:79], v[60:61], v[42:43] op_sel:[0,0] op_sel_hi:[0,1]
	v_pk_mul_f32 v[68:69], v[50:51], v[54:55] op_sel:[0,0] op_sel_hi:[0,1]
	v_pk_mul_f32 v[84:85], v[58:59], v[60:61] op_sel:[0,0] op_sel_hi:[0,1]
	v_pk_fma_f32 v[32:33], v[60:61], v[32:33], v[62:63] op_sel:[1,1,0] op_sel_hi:[1,0,1] neg_lo:[1,0,0]
	s_movk_i32 s47, 0x200
	v_pk_mul_f32 v[70:71], v[52:53], v[56:57] op_sel:[0,0] op_sel_hi:[0,1]
	v_pk_fma_f32 v[62:63], v[60:61], v[42:43], v[78:79] op_sel:[1,1,0] op_sel_hi:[1,0,1] neg_lo:[1,0,0]
	v_pk_fma_f32 v[40:41], v[50:51], v[54:55], v[68:69] op_sel:[1,1,0] op_sel_hi:[1,0,1] neg_lo:[1,0,0]
	v_pk_fma_f32 v[46:47], v[58:59], v[60:61], v[84:85] op_sel:[1,1,0] op_sel_hi:[1,0,1] neg_lo:[1,0,0]
	s_and_b64 vcc, exec, s[52:53]
	v_pk_fma_f32 v[42:43], v[52:53], v[56:57], v[70:71] op_sel:[1,1,0] op_sel_hi:[1,0,1] neg_lo:[1,0,0]
	ds_write2st64_b64 v86, v[22:23], v[26:27] offset0:64 offset1:80
	ds_write2st64_b64 v86, v[40:41], v[42:43] offset0:96 offset1:112
	ds_write_b64 v87, v[46:47]
	v_pk_mul_f32 v[22:23], v[44:45], v[32:33] op_sel:[0,0] op_sel_hi:[0,1]
	s_mov_b64 s[52:53], 0
	v_pk_mul_f32 v[72:73], v[60:61], v[28:29] op_sel:[0,0] op_sel_hi:[0,1]
	v_pk_mul_f32 v[74:75], v[60:61], v[20:21] op_sel:[0,0] op_sel_hi:[0,1]
	v_pk_fma_f32 v[22:23], v[44:45], v[32:33], v[22:23] op_sel:[1,1,0] op_sel_hi:[1,0,1] neg_lo:[1,0,0]
	v_pk_mul_f32 v[76:77], v[60:61], v[38:39] op_sel:[0,0] op_sel_hi:[0,1]
	v_pk_mul_f32 v[80:81], v[60:61], v[54:55] op_sel:[0,0] op_sel_hi:[0,1]
	v_pk_mul_f32 v[82:83], v[60:61], v[56:57] op_sel:[0,0] op_sel_hi:[0,1]
	s_nop 0
	v_pk_fma_f32 v[28:29], v[60:61], v[28:29], v[72:73] op_sel:[1,1,0] op_sel_hi:[1,0,1] neg_lo:[1,0,0]
	v_pk_fma_f32 v[20:21], v[60:61], v[20:21], v[74:75] op_sel:[1,1,0] op_sel_hi:[1,0,1] neg_lo:[1,0,0]
	v_pk_mul_f32 v[46:47], v[30:31], v[62:63] op_sel:[0,0] op_sel_hi:[0,1]
	v_pk_fma_f32 v[38:39], v[60:61], v[38:39], v[76:77] op_sel:[1,1,0] op_sel_hi:[1,0,1] neg_lo:[1,0,0]
	v_pk_fma_f32 v[72:73], v[60:61], v[54:55], v[80:81] op_sel:[1,1,0] op_sel_hi:[1,0,1] neg_lo:[1,0,0]
	v_pk_fma_f32 v[74:75], v[60:61], v[56:57], v[82:83] op_sel:[1,1,0] op_sel_hi:[1,0,1] neg_lo:[1,0,0]
	s_nop 0
	v_pk_mul_f32 v[26:27], v[18:19], v[28:29] op_sel:[0,0] op_sel_hi:[0,1]
	v_pk_mul_f32 v[40:41], v[36:37], v[20:21] op_sel:[0,0] op_sel_hi:[0,1]
	v_pk_mul_f32 v[42:43], v[24:25], v[38:39] op_sel:[0,0] op_sel_hi:[0,1]
	v_pk_mul_f32 v[48:49], v[34:35], v[72:73] op_sel:[0,0] op_sel_hi:[0,1]
	v_pk_mul_f32 v[50:51], v[16:17], v[74:75] op_sel:[0,0] op_sel_hi:[0,1]
	s_nop 0
	v_pk_fma_f32 v[18:19], v[18:19], v[28:29], v[26:27] op_sel:[1,1,0] op_sel_hi:[1,0,1] neg_lo:[1,0,0]
	v_pk_fma_f32 v[20:21], v[36:37], v[20:21], v[40:41] op_sel:[1,1,0] op_sel_hi:[1,0,1] neg_lo:[1,0,0]
	v_pk_fma_f32 v[26:27], v[30:31], v[62:63], v[46:47] op_sel:[1,1,0] op_sel_hi:[1,0,1] neg_lo:[1,0,0]
	v_pk_fma_f32 v[24:25], v[24:25], v[38:39], v[42:43] op_sel:[1,1,0] op_sel_hi:[1,0,1] neg_lo:[1,0,0]
	v_pk_fma_f32 v[28:29], v[34:35], v[72:73], v[48:49] op_sel:[1,1,0] op_sel_hi:[1,0,1] neg_lo:[1,0,0]
	v_pk_fma_f32 v[16:17], v[16:17], v[74:75], v[50:51] op_sel:[1,1,0] op_sel_hi:[1,0,1] neg_lo:[1,0,0]
	ds_write_b64 v88, v[22:23]
	ds_write_b64 v89, v[18:19]
	ds_write_b64 v90, v[20:21]
	ds_write_b64 v91, v[24:25]
	ds_write_b64 v92, v[26:27]
	ds_write_b64 v93, v[28:29]
	ds_write_b64 v94, v[16:17]
	s_cbranch_vccnz .LBB0_300
	s_mov_b32 s47, 0
	s_mov_b64 s[52:53], -1
	s_waitcnt lgkmcnt(0)
	s_barrier
	s_branch .LBB0_303
; #define LAS __attribute__((address_space(3)))
; template <bool INV, bool HALFIN = false> __device__ __forceinline__ void dft16(cf (&x)[16]) {
; #pragma unroll
;     for (int m2 = 0; m2 < 4; ++m2) {
;         if (HALFIN) { const cf a0 = x[m2], a1 = x[4 + m2]; x[m2] = a0 + a1; x[8 + m2] = a0 - a1; x[4 + m2] = add_mib(a0, a1); x[12 + m2] = add_pib(a0, a1); }
;         else dft4<INV>(x[m2], x[4 + m2], x[8 + m2], x[12 + m2]);
;     }
;     constexpr float C1 = 0.9238795325112867f, S1 = 0.3826834323650898f, C2 = 0.7071067811865476f;
;     x[4 * 1 + 1] = tw16<INV>(x[5], C1, S1);  x[4 * 1 + 2] = tw16<INV>(x[6], C2, C2);   x[4 * 1 + 3] = tw16<INV>(x[7], S1, C1);
;     x[4 * 2 + 1] = tw16<INV>(x[9], C2, C2);  x[4 * 2 + 2] = tw16<INV>(x[10], 0.f, 1.f); x[4 * 2 + 3] = tw16<INV>(x[11], -C2, C2);
;     x[4 * 3 + 1] = tw16<INV>(x[13], S1, C1); x[4 * 3 + 2] = tw16<INV>(x[14], -C2, C2); x[4 * 3 + 3] = tw16<INV>(x[15], -C1, -S1);
; #pragma unroll
;     for (int q1 = 0; q1 < 4; ++q1) dft4<INV>(x[4 * q1], x[4 * q1 + 1], x[4 * q1 + 2], x[4 * q1 + 3]);
; }
; template <int LST> __device__ __forceinline__ int pass_pos(int base, int phb, int m) {
;     if (LST == 10) return phb + (m << 10);
;     if (LST == 6) return (base ^ (m << 2)) + (m << 6);
;     return PH(base + (m << LST));
; }
; template <bool INV, int LST, bool HALF = false> __device__ __forceinline__ void fft_pass16(LAS cf* z, const LAS cf* Thi, const LAS cf* Tlo, int tid) {
;     constexpr int st = 1 << LST;
;     cf w[16];
; #pragma unroll 1
;     for (int it = 0; it < 2; ++it) {
;         const int g = tid + 512 * it; const int j0 = g & (st - 1); const int base = ((g >> LST) << (LST + 4)) + j0; const int phb = PH(base);
;         if (LST == 10 || it == 0) {
;             const int e1 = j0 << (10 - LST);
;             w[1] = cmul(Thi[e1 >> 7], Tlo[e1 & 127]);
;             w[2] = cmul(w[1], w[1]); w[3] = cmul(w[2], w[1]); w[4] = cmul(w[2], w[2]); w[5] = cmul(w[4], w[1]); w[6] = cmul(w[3], w[3]); w[7] = cmul(w[4], w[3]); w[8] = cmul(w[4], w[4]);
; #pragma unroll
;             for (int q = 9; q < 16; ++q) w[q] = cmul(w[8], w[q - 8]);
;         }
;         cf x[16];
;         if (!INV) {
; #pragma unroll
;             for (int m = 0; m < 16; ++m) { if (HALF && m >= 8) x[m] = (cf){0.f, 0.f}; else x[m] = z[pass_pos<LST>(base, phb, m)]; }
;             dft16<false, HALF>(x);
; #pragma unroll
.LBB0_302:
	v_add_u32_e32 v46, s47, v159
	v_and_b32_e32 v70, 0x7c00, v46
	v_or_b32_e32 v46, v70, v153
	v_bitop3_b32 v54, v70, 16, v153 bitop3:0x36
	v_bitop3_b32 v62, v70, 32, v153 bitop3:0x36
	v_lshl_add_u32 v84, v46, 3, 0
	v_bitop3_b32 v46, v70, 4, v153 bitop3:0x36
	v_lshl_add_u32 v88, v54, 3, 0
	v_bitop3_b32 v54, v70, 20, v153 bitop3:0x36
	v_lshl_add_u32 v92, v62, 3, 0
	v_bitop3_b32 v62, v70, 36, v153 bitop3:0x36
	v_bitop3_b32 v71, v70, 48, v153 bitop3:0x36
	v_lshl_add_u32 v85, v46, 3, 0
	v_bitop3_b32 v46, v70, 8, v153 bitop3:0x36
	v_lshl_add_u32 v89, v54, 3, 0
	v_bitop3_b32 v54, v70, 24, v153 bitop3:0x36
	v_lshl_add_u32 v93, v62, 3, 0
	v_bitop3_b32 v62, v70, 40, v153 bitop3:0x36
	v_lshl_add_u32 v96, v71, 3, 0
	v_bitop3_b32 v71, v70, 52, v153 bitop3:0x36
	v_lshl_add_u32 v86, v46, 3, 0
	v_bitop3_b32 v46, v70, 12, v153 bitop3:0x36
	v_lshl_add_u32 v90, v54, 3, 0
	v_bitop3_b32 v54, v70, 28, v153 bitop3:0x36
	v_lshl_add_u32 v94, v62, 3, 0
	v_bitop3_b32 v62, v70, 44, v153 bitop3:0x36
	v_lshl_add_u32 v97, v71, 3, 0
	v_bitop3_b32 v71, v70, 56, v153 bitop3:0x36
	v_bitop3_b32 v70, v70, 60, v153 bitop3:0x36
	v_lshl_add_u32 v87, v46, 3, 0
	ds_read_b64 v[46:47], v84
	ds_read_b64 v[48:49], v85 offset:512
	ds_read_b64 v[50:51], v86 offset:1024
	ds_read_b64 v[52:53], v87 offset:1536
	v_lshl_add_u32 v91, v54, 3, 0
	ds_read_b64 v[54:55], v88 offset:2048
	ds_read_b64 v[56:57], v89 offset:2560
	ds_read_b64 v[58:59], v90 offset:3072
	ds_read_b64 v[60:61], v91 offset:3584
	v_lshl_add_u32 v95, v62, 3, 0
	ds_read_b64 v[62:63], v92 offset:4096
	ds_read_b64 v[64:65], v93 offset:4608
	ds_read_b64 v[66:67], v94 offset:5120
	ds_read_b64 v[68:69], v95 offset:5632
	v_lshl_add_u32 v98, v71, 3, 0
	v_lshl_add_u32 v99, v70, 3, 0
	ds_read_b64 v[70:71], v96 offset:6144
	ds_read_b64 v[72:73], v97 offset:6656
	ds_read_b64 v[74:75], v98 offset:7168
	ds_read_b64 v[76:77], v99 offset:7680
	s_waitcnt lgkmcnt(7)
	v_pk_add_f32 v[78:79], v[46:47], v[62:63]
	v_pk_add_f32 v[46:47], v[46:47], v[62:63] neg_lo:[0,1] neg_hi:[0,1]
	s_waitcnt lgkmcnt(3)
	v_pk_add_f32 v[62:63], v[54:55], v[70:71]
	v_pk_add_f32 v[54:55], v[54:55], v[70:71] neg_lo:[0,1] neg_hi:[0,1]
	v_pk_add_f32 v[70:71], v[78:79], v[62:63]
	v_pk_add_f32 v[62:63], v[78:79], v[62:63] neg_lo:[0,1] neg_hi:[0,1]
	v_pk_add_f32 v[78:79], v[46:47], v[54:55] op_sel:[0,1] op_sel_hi:[1,0] neg_hi:[0,1]
	v_pk_add_f32 v[46:47], v[46:47], v[54:55] op_sel:[0,1] op_sel_hi:[1,0] neg_lo:[0,1]
	v_pk_add_f32 v[54:55], v[48:49], v[64:65]
	v_pk_add_f32 v[48:49], v[48:49], v[64:65] neg_lo:[0,1] neg_hi:[0,1]
	s_waitcnt lgkmcnt(2)
	v_pk_add_f32 v[64:65], v[56:57], v[72:73]
	v_pk_add_f32 v[56:57], v[56:57], v[72:73] neg_lo:[0,1] neg_hi:[0,1]
	v_pk_add_f32 v[72:73], v[54:55], v[64:65]
	v_pk_add_f32 v[54:55], v[54:55], v[64:65] neg_lo:[0,1] neg_hi:[0,1]
	v_pk_add_f32 v[64:65], v[48:49], v[56:57] op_sel:[0,1] op_sel_hi:[1,0] neg_hi:[0,1]
	v_pk_add_f32 v[48:49], v[48:49], v[56:57] op_sel:[0,1] op_sel_hi:[1,0] neg_lo:[0,1]
	v_pk_add_f32 v[56:57], v[50:51], v[66:67]
	v_pk_add_f32 v[50:51], v[50:51], v[66:67] neg_lo:[0,1] neg_hi:[0,1]
	s_waitcnt lgkmcnt(1)
	v_pk_add_f32 v[66:67], v[58:59], v[74:75]
	v_pk_add_f32 v[58:59], v[58:59], v[74:75] neg_lo:[0,1] neg_hi:[0,1]
	v_pk_add_f32 v[74:75], v[56:57], v[66:67]
	v_pk_add_f32 v[56:57], v[56:57], v[66:67] neg_lo:[0,1] neg_hi:[0,1]
	v_pk_add_f32 v[66:67], v[50:51], v[58:59] op_sel:[0,1] op_sel_hi:[1,0] neg_hi:[0,1]
	v_pk_add_f32 v[50:51], v[50:51], v[58:59] op_sel:[0,1] op_sel_hi:[1,0] neg_lo:[0,1]
	v_pk_add_f32 v[58:59], v[52:53], v[68:69]
	v_pk_add_f32 v[52:53], v[52:53], v[68:69] neg_lo:[0,1] neg_hi:[0,1]
	s_waitcnt lgkmcnt(0)
	v_pk_add_f32 v[68:69], v[60:61], v[76:77]
	v_pk_add_f32 v[60:61], v[60:61], v[76:77] neg_lo:[0,1] neg_hi:[0,1]
	v_pk_add_f32 v[76:77], v[58:59], v[68:69]
	v_pk_add_f32 v[58:59], v[58:59], v[68:69] neg_lo:[0,1] neg_hi:[0,1]
	v_pk_add_f32 v[68:69], v[52:53], v[60:61] op_sel:[0,1] op_sel_hi:[1,0] neg_hi:[0,1]
	v_pk_add_f32 v[52:53], v[52:53], v[60:61] op_sel:[0,1] op_sel_hi:[1,0] neg_lo:[0,1]
	v_pk_mul_f32 v[60:61], v[64:65], s[24:25] op_sel_hi:[1,0]
	s_mov_b32 s54, s43
	v_pk_fma_f32 v[80:81], v[64:65], s[22:23], v[60:61] op_sel:[0,0,1] op_sel_hi:[1,0,0] neg_hi:[0,0,1]
	s_mov_b32 s55, s24
	v_pk_mul_f32 v[60:61], v[66:67], s[38:39] op_sel_hi:[1,0]
	s_movk_i32 s47, 0x2000
	v_pk_fma_f32 v[64:65], v[66:67], s[38:39], v[60:61] op_sel:[0,0,1] op_sel_hi:[1,0,0] neg_hi:[0,0,1]
	v_pk_mul_f32 v[66:67], v[68:69], s[22:23] op_sel_hi:[1,0]
	s_nop 0
	v_pk_fma_f32 v[82:83], v[68:69], s[24:25], v[66:67] op_sel:[0,0,1] op_sel_hi:[1,0,0] neg_hi:[0,0,1]
	v_pk_add_f32 v[60:61], v[78:79], v[64:65]
	v_pk_mul_f32 v[66:67], v[54:55], s[38:39] op_sel_hi:[1,0]
	v_pk_add_f32 v[64:65], v[78:79], v[64:65] neg_lo:[0,1] neg_hi:[0,1]
	v_pk_fma_f32 v[68:69], v[54:55], s[38:39], v[66:67] op_sel:[0,0,1] op_sel_hi:[1,0,0] neg_hi:[0,0,1]
	v_pk_add_f32 v[78:79], v[80:81], v[82:83] neg_lo:[0,1] neg_hi:[0,1]
	v_pk_fma_f32 v[54:55], v[56:57], 0, v[56:57] op_sel:[0,0,1] op_sel_hi:[1,0,0]
	v_pk_fma_f32 v[56:57], v[56:57], 0, v[56:57] op_sel:[0,0,1] op_sel_hi:[1,0,0] neg_lo:[0,0,1] neg_hi:[0,0,1]
	s_andn2_b64 vcc, exec, s[52:53]
	v_mul_f32_e32 v56, 0x3f3504f3, v58
	v_mov_b32_e32 v55, v57
	v_pk_fma_f32 v[56:57], v[58:59], s[38:39], v[56:57] op_sel:[1,0,0] op_sel_hi:[1,1,0] neg_lo:[0,0,1] neg_hi:[0,0,1]
	v_pk_mul_f32 v[58:59], v[48:49], s[22:23] op_sel_hi:[1,0]
	s_mov_b64 s[52:53], 0
	v_pk_fma_f32 v[66:67], v[48:49], s[24:25], v[58:59] op_sel:[0,0,1] op_sel_hi:[1,0,0]
	v_pk_fma_f32 v[48:49], v[48:49], s[24:25], v[58:59] op_sel:[0,0,1] op_sel_hi:[1,0,0] neg_lo:[0,0,1] neg_hi:[0,0,1]
; #define LAS __attribute__((address_space(3)))
; template <bool INV, bool HALFIN = false> __device__ __forceinline__ void dft16(cf (&x)[16]) {
; #pragma unroll
;     for (int m2 = 0; m2 < 4; ++m2) {
;         if (HALFIN) { const cf a0 = x[m2], a1 = x[4 + m2]; x[m2] = a0 + a1; x[8 + m2] = a0 - a1; x[4 + m2] = add_mib(a0, a1); x[12 + m2] = add_pib(a0, a1); }
;         else dft4<INV>(x[m2], x[4 + m2], x[8 + m2], x[12 + m2]);
;     }
;     constexpr float C1 = 0.9238795325112867f, S1 = 0.3826834323650898f, C2 = 0.7071067811865476f;
;     x[4 * 1 + 1] = tw16<INV>(x[5], C1, S1);  x[4 * 1 + 2] = tw16<INV>(x[6], C2, C2);   x[4 * 1 + 3] = tw16<INV>(x[7], S1, C1);
;     x[4 * 2 + 1] = tw16<INV>(x[9], C2, C2);  x[4 * 2 + 2] = tw16<INV>(x[10], 0.f, 1.f); x[4 * 2 + 3] = tw16<INV>(x[11], -C2, C2);
;     x[4 * 3 + 1] = tw16<INV>(x[13], S1, C1); x[4 * 3 + 2] = tw16<INV>(x[14], -C2, C2); x[4 * 3 + 3] = tw16<INV>(x[15], -C1, -S1);
; #pragma unroll
;     for (int q1 = 0; q1 < 4; ++q1) dft4<INV>(x[4 * q1], x[4 * q1 + 1], x[4 * q1 + 2], x[4 * q1 + 3]);
; }
; template <int LST> __device__ __forceinline__ int pass_pos(int base, int phb, int m) {
;     if (LST == 10) return phb + (m << 10);
;     if (LST == 6) return (base ^ (m << 2)) + (m << 6);
;     return PH(base + (m << LST));
; }
; template <bool INV, int LST, bool HALF = false> __device__ __forceinline__ void fft_pass16(LAS cf* z, const LAS cf* Thi, const LAS cf* Tlo, int tid) {
;     constexpr int st = 1 << LST;
;     cf w[16];
; #pragma unroll 1
;     for (int it = 0; it < 2; ++it) {
;         const int g = tid + 512 * it; const int j0 = g & (st - 1); const int base = ((g >> LST) << (LST + 4)) + j0; const int phb = PH(base);
;         if (LST == 10 || it == 0) {
;             const int e1 = j0 << (10 - LST);
;             w[1] = cmul(Thi[e1 >> 7], Tlo[e1 & 127]);
;             w[2] = cmul(w[1], w[1]); w[3] = cmul(w[2], w[1]); w[4] = cmul(w[2], w[2]); w[5] = cmul(w[4], w[1]); w[6] = cmul(w[3], w[3]); w[7] = cmul(w[4], w[3]); w[8] = cmul(w[4], w[4]);
; #pragma unroll
;             for (int q = 9; q < 16; ++q) w[q] = cmul(w[8], w[q - 8]);
;         }
;         cf x[16];
;         if (!INV) {
; #pragma unroll
;             for (int m = 0; m < 16; ++m) { if (HALF && m >= 8) x[m] = (cf){0.f, 0.f}; else x[m] = z[pass_pos<LST>(base, phb, m)]; }
;             dft16<false, HALF>(x);
; #pragma unroll
	v_pk_add_f32 v[58:59], v[70:71], v[74:75] neg_lo:[0,1] neg_hi:[0,1]
	v_mul_f32_e32 v48, 0x3f3504f3, v50
	v_mov_b32_e32 v67, v49
	v_pk_fma_f32 v[48:49], v[50:51], s[38:39], v[48:49] op_sel:[1,0,0] op_sel_hi:[1,1,0] neg_lo:[0,0,1] neg_hi:[0,0,1]
	v_pk_mul_f32 v[50:51], v[52:53], s[42:43] op_sel:[1,0]
	s_nop 0
	v_pk_fma_f32 v[50:51], v[52:53], s[54:55], v[50:51] op_sel_hi:[0,1,1]
	v_pk_add_f32 v[52:53], v[70:71], v[74:75]
	v_pk_add_f32 v[70:71], v[72:73], v[76:77]
	v_pk_add_f32 v[72:73], v[72:73], v[76:77] neg_lo:[0,1] neg_hi:[0,1]
	v_pk_add_f32 v[74:75], v[52:53], v[70:71] neg_lo:[0,1] neg_hi:[0,1]
	v_pk_add_f32 v[76:77], v[58:59], v[72:73] op_sel:[0,1] op_sel_hi:[1,0] neg_hi:[0,1]
	v_pk_add_f32 v[58:59], v[58:59], v[72:73] op_sel:[0,1] op_sel_hi:[1,0] neg_lo:[0,1]
	v_pk_add_f32 v[72:73], v[80:81], v[82:83]
	s_nop 0
	v_pk_add_f32 v[80:81], v[60:61], v[72:73]
	v_pk_add_f32 v[60:61], v[60:61], v[72:73] neg_lo:[0,1] neg_hi:[0,1]
	v_pk_add_f32 v[72:73], v[64:65], v[78:79] op_sel:[0,1] op_sel_hi:[1,0] neg_hi:[0,1]
	v_pk_add_f32 v[64:65], v[64:65], v[78:79] op_sel:[0,1] op_sel_hi:[1,0] neg_lo:[0,1]
	v_pk_add_f32 v[78:79], v[62:63], v[54:55]
	v_pk_add_f32 v[54:55], v[62:63], v[54:55] neg_lo:[0,1] neg_hi:[0,1]
	v_pk_add_f32 v[62:63], v[68:69], v[56:57]
	v_pk_add_f32 v[56:57], v[68:69], v[56:57] neg_lo:[0,1] neg_hi:[0,1]
	v_pk_add_f32 v[68:69], v[78:79], v[62:63]
	v_pk_add_f32 v[62:63], v[78:79], v[62:63] neg_lo:[0,1] neg_hi:[0,1]
	v_pk_add_f32 v[78:79], v[54:55], v[56:57] op_sel:[0,1] op_sel_hi:[1,0] neg_hi:[0,1]
	v_pk_add_f32 v[54:55], v[54:55], v[56:57] op_sel:[0,1] op_sel_hi:[1,0] neg_lo:[0,1]
	v_pk_add_f32 v[56:57], v[46:47], v[48:49]
	v_pk_add_f32 v[46:47], v[46:47], v[48:49] neg_lo:[0,1] neg_hi:[0,1]
	v_pk_add_f32 v[48:49], v[66:67], v[50:51]
	v_pk_add_f32 v[50:51], v[66:67], v[50:51] neg_lo:[0,1] neg_hi:[0,1]
	v_pk_add_f32 v[66:67], v[56:57], v[48:49]
	v_pk_add_f32 v[48:49], v[56:57], v[48:49] neg_lo:[0,1] neg_hi:[0,1]
	v_pk_add_f32 v[56:57], v[46:47], v[50:51] op_sel:[0,1] op_sel_hi:[1,0] neg_hi:[0,1]
	v_pk_add_f32 v[46:47], v[46:47], v[50:51] op_sel:[0,1] op_sel_hi:[1,0] neg_lo:[0,1]
	v_pk_add_f32 v[50:51], v[52:53], v[70:71]
	ds_write_b64 v84, v[50:51]
	v_pk_mul_f32 v[50:51], v[80:81], v[16:17] op_sel:[0,0] op_sel_hi:[0,1]
	s_nop 0
	v_pk_fma_f32 v[50:51], v[80:81], v[16:17], v[50:51] op_sel:[1,1,0] op_sel_hi:[1,0,1] neg_lo:[1,0,0]
	ds_write_b64 v85, v[50:51] offset:512
	v_pk_mul_f32 v[50:51], v[68:69], v[18:19] op_sel:[0,0] op_sel_hi:[0,1]
	s_nop 0
	v_pk_fma_f32 v[50:51], v[68:69], v[18:19], v[50:51] op_sel:[1,1,0] op_sel_hi:[1,0,1] neg_lo:[1,0,0]
	ds_write_b64 v86, v[50:51] offset:1024
	v_pk_mul_f32 v[50:51], v[66:67], v[20:21] op_sel:[0,0] op_sel_hi:[0,1]
	s_nop 0
	v_pk_fma_f32 v[50:51], v[66:67], v[20:21], v[50:51] op_sel:[1,1,0] op_sel_hi:[1,0,1] neg_lo:[1,0,0]
	ds_write_b64 v87, v[50:51] offset:1536
	v_pk_mul_f32 v[50:51], v[76:77], v[22:23] op_sel:[0,0] op_sel_hi:[0,1]
	s_nop 0
	v_pk_fma_f32 v[50:51], v[76:77], v[22:23], v[50:51] op_sel:[1,1,0] op_sel_hi:[1,0,1] neg_lo:[1,0,0]
	ds_write_b64 v88, v[50:51] offset:2048
	v_pk_mul_f32 v[50:51], v[72:73], v[24:25] op_sel:[0,0] op_sel_hi:[0,1]
	s_nop 0
	v_pk_fma_f32 v[50:51], v[72:73], v[24:25], v[50:51] op_sel:[1,1,0] op_sel_hi:[1,0,1] neg_lo:[1,0,0]
	ds_write_b64 v89, v[50:51] offset:2560
	v_pk_mul_f32 v[50:51], v[78:79], v[26:27] op_sel:[0,0] op_sel_hi:[0,1]
	s_nop 0
	v_pk_fma_f32 v[50:51], v[78:79], v[26:27], v[50:51] op_sel:[1,1,0] op_sel_hi:[1,0,1] neg_lo:[1,0,0]
	ds_write_b64 v90, v[50:51] offset:3072
	v_pk_mul_f32 v[50:51], v[56:57], v[28:29] op_sel:[0,0] op_sel_hi:[0,1]
	s_nop 0
	v_pk_fma_f32 v[50:51], v[56:57], v[28:29], v[50:51] op_sel:[1,1,0] op_sel_hi:[1,0,1] neg_lo:[1,0,0]
	ds_write_b64 v91, v[50:51] offset:3584
	v_pk_mul_f32 v[50:51], v[74:75], v[30:31] op_sel:[0,0] op_sel_hi:[0,1]
	s_nop 0
	v_pk_fma_f32 v[50:51], v[74:75], v[30:31], v[50:51] op_sel:[1,1,0] op_sel_hi:[1,0,1] neg_lo:[1,0,0]
	ds_write_b64 v92, v[50:51] offset:4096
	v_pk_mul_f32 v[50:51], v[60:61], v[32:33] op_sel:[0,0] op_sel_hi:[0,1]
	s_nop 0
	v_pk_fma_f32 v[50:51], v[60:61], v[32:33], v[50:51] op_sel:[1,1,0] op_sel_hi:[1,0,1] neg_lo:[1,0,0]
	ds_write_b64 v93, v[50:51] offset:4608
	v_pk_mul_f32 v[50:51], v[62:63], v[34:35] op_sel:[0,0] op_sel_hi:[0,1]
	s_nop 0
	v_pk_fma_f32 v[50:51], v[62:63], v[34:35], v[50:51] op_sel:[1,1,0] op_sel_hi:[1,0,1] neg_lo:[1,0,0]
	ds_write_b64 v94, v[50:51] offset:5120
	v_pk_mul_f32 v[50:51], v[48:49], v[36:37] op_sel:[0,0] op_sel_hi:[0,1]
	s_nop 0
	v_pk_fma_f32 v[48:49], v[48:49], v[36:37], v[50:51] op_sel:[1,1,0] op_sel_hi:[1,0,1] neg_lo:[1,0,0]
	ds_write_b64 v95, v[48:49] offset:5632
	v_pk_mul_f32 v[48:49], v[58:59], v[38:39] op_sel:[0,0] op_sel_hi:[0,1]
	s_nop 0
	v_pk_fma_f32 v[48:49], v[58:59], v[38:39], v[48:49] op_sel:[1,1,0] op_sel_hi:[1,0,1] neg_lo:[1,0,0]
	ds_write_b64 v96, v[48:49] offset:6144
	v_pk_mul_f32 v[48:49], v[64:65], v[40:41] op_sel:[0,0] op_sel_hi:[0,1]
	s_nop 0
	v_pk_fma_f32 v[48:49], v[64:65], v[40:41], v[48:49] op_sel:[1,1,0] op_sel_hi:[1,0,1] neg_lo:[1,0,0]
	ds_write_b64 v97, v[48:49] offset:6656
	v_pk_mul_f32 v[48:49], v[54:55], v[42:43] op_sel:[0,0] op_sel_hi:[0,1]
	s_nop 0
	v_pk_fma_f32 v[48:49], v[54:55], v[42:43], v[48:49] op_sel:[1,1,0] op_sel_hi:[1,0,1] neg_lo:[1,0,0]
	ds_write_b64 v98, v[48:49] offset:7168
	v_pk_mul_f32 v[48:49], v[46:47], v[44:45] op_sel:[0,0] op_sel_hi:[0,1]
	s_nop 0
	v_pk_fma_f32 v[46:47], v[46:47], v[44:45], v[48:49] op_sel:[1,1,0] op_sel_hi:[1,0,1] neg_lo:[1,0,0]
	ds_write_b64 v99, v[46:47] offset:7680
	s_cbranch_vccz .LBB0_305

; #define LAS __attribute__((address_space(3)))
; template <bool INV, bool HALFIN = false> __device__ __forceinline__ void dft16(cf (&x)[16]) {
; #pragma unroll
;     for (int m2 = 0; m2 < 4; ++m2) {
;         if (HALFIN) { const cf a0 = x[m2], a1 = x[4 + m2]; x[m2] = a0 + a1; x[8 + m2] = a0 - a1; x[4 + m2] = add_mib(a0, a1); x[12 + m2] = add_pib(a0, a1); }
;         else dft4<INV>(x[m2], x[4 + m2], x[8 + m2], x[12 + m2]);
;     }
;     constexpr float C1 = 0.9238795325112867f, S1 = 0.3826834323650898f, C2 = 0.7071067811865476f;
;     x[4 * 1 + 1] = tw16<INV>(x[5], C1, S1);  x[4 * 1 + 2] = tw16<INV>(x[6], C2, C2);   x[4 * 1 + 3] = tw16<INV>(x[7], S1, C1);
;     x[4 * 2 + 1] = tw16<INV>(x[9], C2, C2);  x[4 * 2 + 2] = tw16<INV>(x[10], 0.f, 1.f); x[4 * 2 + 3] = tw16<INV>(x[11], -C2, C2);
;     x[4 * 3 + 1] = tw16<INV>(x[13], S1, C1); x[4 * 3 + 2] = tw16<INV>(x[14], -C2, C2); x[4 * 3 + 3] = tw16<INV>(x[15], -C1, -S1);
; #pragma unroll
;     for (int q1 = 0; q1 < 4; ++q1) dft4<INV>(x[4 * q1], x[4 * q1 + 1], x[4 * q1 + 2], x[4 * q1 + 3]);
; }
; template <int LST> __device__ __forceinline__ int pass_pos(int base, int phb, int m) {
;     if (LST == 10) return phb + (m << 10);
;     if (LST == 6) return (base ^ (m << 2)) + (m << 6);
;     return PH(base + (m << LST));
; }
; template <bool INV, int LST, bool HALF = false> __device__ __forceinline__ void fft_pass16(LAS cf* z, const LAS cf* Thi, const LAS cf* Tlo, int tid) {
;     constexpr int st = 1 << LST;
;     cf w[16];
; #pragma unroll 1
;     for (int it = 0; it < 2; ++it) {
;         const int g = tid + 512 * it; const int j0 = g & (st - 1); const int base = ((g >> LST) << (LST + 4)) + j0; const int phb = PH(base);
;         if (LST == 10 || it == 0) {
;             const int e1 = j0 << (10 - LST);
;             w[1] = cmul(Thi[e1 >> 7], Tlo[e1 & 127]);
;             w[2] = cmul(w[1], w[1]); w[3] = cmul(w[2], w[1]); w[4] = cmul(w[2], w[2]); w[5] = cmul(w[4], w[1]); w[6] = cmul(w[3], w[3]); w[7] = cmul(w[4], w[3]); w[8] = cmul(w[4], w[4]);
; #pragma unroll
;             for (int q = 9; q < 16; ++q) w[q] = cmul(w[8], w[q - 8]);
;         }
;         cf x[16];
;         if (!INV) {
; #pragma unroll
;             for (int m = 0; m < 16; ++m) { if (HALF && m >= 8) x[m] = (cf){0.f, 0.f}; else x[m] = z[pass_pos<LST>(base, phb, m)]; }
;             dft16<false, HALF>(x);
; #pragma unroll
.LBB0_306:
	v_add_u32_e32 v46, s47, v159
	v_and_or_b32 v70, v46, s87, v155
	v_bitop3_b32 v54, v70, v162, 16 bitop3:0x36
	v_bitop3_b32 v62, v70, v162, 32 bitop3:0x36
	v_bitop3_b32 v46, v70, v162, 4 bitop3:0x36
	v_lshl_add_u32 v88, v54, 3, 0
	v_bitop3_b32 v54, v70, v162, 20 bitop3:0x36
	v_lshl_add_u32 v92, v62, 3, 0
	v_bitop3_b32 v62, v70, v162, 36 bitop3:0x36
	v_bitop3_b32 v71, v70, v162, 48 bitop3:0x36
	v_lshl_add_u32 v85, v46, 3, 0
	v_bitop3_b32 v46, v70, v162, 8 bitop3:0x36
	v_lshl_add_u32 v89, v54, 3, 0
	v_bitop3_b32 v54, v70, v162, 24 bitop3:0x36
	v_lshl_add_u32 v93, v62, 3, 0
	v_bitop3_b32 v62, v70, v162, 40 bitop3:0x36
	v_lshl_add_u32 v96, v71, 3, 0
	v_bitop3_b32 v71, v70, v162, 52 bitop3:0x36
	v_lshl_add_u32 v84, v70, 3, v163
	v_lshl_add_u32 v86, v46, 3, 0
	v_bitop3_b32 v46, v70, v162, 12 bitop3:0x36
	v_lshl_add_u32 v90, v54, 3, 0
	v_bitop3_b32 v54, v70, v162, 28 bitop3:0x36
	v_lshl_add_u32 v94, v62, 3, 0
	v_bitop3_b32 v62, v70, v162, 44 bitop3:0x36
	v_lshl_add_u32 v97, v71, 3, 0
	v_bitop3_b32 v71, v70, v162, 56 bitop3:0x36
	v_bitop3_b32 v70, v70, v162, 60 bitop3:0x36
	v_lshl_add_u32 v87, v46, 3, 0
	ds_read_b64 v[46:47], v84
	ds_read_b64 v[48:49], v85
	ds_read_b64 v[50:51], v86
	ds_read_b64 v[52:53], v87
	v_lshl_add_u32 v91, v54, 3, 0
	ds_read_b64 v[54:55], v88
	ds_read_b64 v[56:57], v89
	ds_read_b64 v[58:59], v90
	ds_read_b64 v[60:61], v91
	v_lshl_add_u32 v95, v62, 3, 0
	ds_read_b64 v[62:63], v92
	ds_read_b64 v[64:65], v93
	ds_read_b64 v[66:67], v94
	ds_read_b64 v[68:69], v95
	v_lshl_add_u32 v98, v71, 3, 0
	v_lshl_add_u32 v99, v70, 3, 0
	ds_read_b64 v[70:71], v96
	ds_read_b64 v[72:73], v97
	ds_read_b64 v[74:75], v98
	ds_read_b64 v[76:77], v99
	s_waitcnt lgkmcnt(7)
	v_pk_add_f32 v[78:79], v[46:47], v[62:63]
	v_pk_add_f32 v[46:47], v[46:47], v[62:63] neg_lo:[0,1] neg_hi:[0,1]
	s_waitcnt lgkmcnt(3)
	v_pk_add_f32 v[62:63], v[54:55], v[70:71]
	v_pk_add_f32 v[54:55], v[54:55], v[70:71] neg_lo:[0,1] neg_hi:[0,1]
	v_pk_add_f32 v[70:71], v[78:79], v[62:63]
	v_pk_add_f32 v[62:63], v[78:79], v[62:63] neg_lo:[0,1] neg_hi:[0,1]
	v_pk_add_f32 v[78:79], v[46:47], v[54:55] op_sel:[0,1] op_sel_hi:[1,0] neg_hi:[0,1]
	v_pk_add_f32 v[46:47], v[46:47], v[54:55] op_sel:[0,1] op_sel_hi:[1,0] neg_lo:[0,1]
	v_pk_add_f32 v[54:55], v[48:49], v[64:65]
	v_pk_add_f32 v[48:49], v[48:49], v[64:65] neg_lo:[0,1] neg_hi:[0,1]
	s_waitcnt lgkmcnt(2)
	v_pk_add_f32 v[64:65], v[56:57], v[72:73]
	v_pk_add_f32 v[56:57], v[56:57], v[72:73] neg_lo:[0,1] neg_hi:[0,1]
	v_pk_add_f32 v[72:73], v[54:55], v[64:65]
	v_pk_add_f32 v[54:55], v[54:55], v[64:65] neg_lo:[0,1] neg_hi:[0,1]
	v_pk_add_f32 v[64:65], v[48:49], v[56:57] op_sel:[0,1] op_sel_hi:[1,0] neg_hi:[0,1]
	v_pk_add_f32 v[48:49], v[48:49], v[56:57] op_sel:[0,1] op_sel_hi:[1,0] neg_lo:[0,1]
	v_pk_add_f32 v[56:57], v[50:51], v[66:67]
	v_pk_add_f32 v[50:51], v[50:51], v[66:67] neg_lo:[0,1] neg_hi:[0,1]
	s_waitcnt lgkmcnt(1)
	v_pk_add_f32 v[66:67], v[58:59], v[74:75]
	v_pk_add_f32 v[58:59], v[58:59], v[74:75] neg_lo:[0,1] neg_hi:[0,1]
	v_pk_add_f32 v[74:75], v[56:57], v[66:67]
	v_pk_add_f32 v[56:57], v[56:57], v[66:67] neg_lo:[0,1] neg_hi:[0,1]
	v_pk_add_f32 v[66:67], v[50:51], v[58:59] op_sel:[0,1] op_sel_hi:[1,0] neg_hi:[0,1]
	v_pk_add_f32 v[50:51], v[50:51], v[58:59] op_sel:[0,1] op_sel_hi:[1,0] neg_lo:[0,1]
	v_pk_add_f32 v[58:59], v[52:53], v[68:69]
	v_pk_add_f32 v[52:53], v[52:53], v[68:69] neg_lo:[0,1] neg_hi:[0,1]
	s_waitcnt lgkmcnt(0)
	v_pk_add_f32 v[68:69], v[60:61], v[76:77]
	v_pk_add_f32 v[60:61], v[60:61], v[76:77] neg_lo:[0,1] neg_hi:[0,1]
	v_pk_add_f32 v[76:77], v[58:59], v[68:69]
	v_pk_add_f32 v[58:59], v[58:59], v[68:69] neg_lo:[0,1] neg_hi:[0,1]
	v_pk_add_f32 v[68:69], v[52:53], v[60:61] op_sel:[0,1] op_sel_hi:[1,0] neg_hi:[0,1]
	v_pk_add_f32 v[52:53], v[52:53], v[60:61] op_sel:[0,1] op_sel_hi:[1,0] neg_lo:[0,1]
	v_pk_mul_f32 v[60:61], v[64:65], s[24:25] op_sel_hi:[1,0]
	s_mov_b32 s54, s43
	v_pk_fma_f32 v[80:81], v[64:65], s[22:23], v[60:61] op_sel:[0,0,1] op_sel_hi:[1,0,0] neg_hi:[0,0,1]
	s_mov_b32 s55, s24
	v_pk_mul_f32 v[60:61], v[66:67], s[38:39] op_sel_hi:[1,0]
	s_movk_i32 s47, 0x2000
	v_pk_fma_f32 v[64:65], v[66:67], s[38:39], v[60:61] op_sel:[0,0,1] op_sel_hi:[1,0,0] neg_hi:[0,0,1]
	v_pk_mul_f32 v[66:67], v[68:69], s[22:23] op_sel_hi:[1,0]
	s_nop 0
	v_pk_fma_f32 v[82:83], v[68:69], s[24:25], v[66:67] op_sel:[0,0,1] op_sel_hi:[1,0,0] neg_hi:[0,0,1]
	v_pk_add_f32 v[60:61], v[78:79], v[64:65]
	v_pk_mul_f32 v[66:67], v[54:55], s[38:39] op_sel_hi:[1,0]
	v_pk_add_f32 v[64:65], v[78:79], v[64:65] neg_lo:[0,1] neg_hi:[0,1]
	v_pk_fma_f32 v[68:69], v[54:55], s[38:39], v[66:67] op_sel:[0,0,1] op_sel_hi:[1,0,0] neg_hi:[0,0,1]
	v_pk_add_f32 v[78:79], v[80:81], v[82:83] neg_lo:[0,1] neg_hi:[0,1]
	v_pk_fma_f32 v[54:55], v[56:57], 0, v[56:57] op_sel:[0,0,1] op_sel_hi:[1,0,0]
	v_pk_fma_f32 v[56:57], v[56:57], 0, v[56:57] op_sel:[0,0,1] op_sel_hi:[1,0,0] neg_lo:[0,0,1] neg_hi:[0,0,1]
	s_andn2_b64 vcc, exec, s[52:53]
	v_mul_f32_e32 v56, 0x3f3504f3, v58
	v_mov_b32_e32 v55, v57
	v_pk_fma_f32 v[56:57], v[58:59], s[38:39], v[56:57] op_sel:[1,0,0] op_sel_hi:[1,1,0] neg_lo:[0,0,1] neg_hi:[0,0,1]
	v_pk_mul_f32 v[58:59], v[48:49], s[22:23] op_sel_hi:[1,0]
	s_mov_b64 s[52:53], 0
	v_pk_fma_f32 v[66:67], v[48:49], s[24:25], v[58:59] op_sel:[0,0,1] op_sel_hi:[1,0,0]
	v_pk_fma_f32 v[48:49], v[48:49], s[24:25], v[58:59] op_sel:[0,0,1] op_sel_hi:[1,0,0] neg_lo:[0,0,1] neg_hi:[0,0,1]
; #define LAS __attribute__((address_space(3)))
; template <bool INV, bool HALFIN = false> __device__ __forceinline__ void dft16(cf (&x)[16]) {
; #pragma unroll
;     for (int m2 = 0; m2 < 4; ++m2) {
;         if (HALFIN) { const cf a0 = x[m2], a1 = x[4 + m2]; x[m2] = a0 + a1; x[8 + m2] = a0 - a1; x[4 + m2] = add_mib(a0, a1); x[12 + m2] = add_pib(a0, a1); }
;         else dft4<INV>(x[m2], x[4 + m2], x[8 + m2], x[12 + m2]);
;     }
;     constexpr float C1 = 0.9238795325112867f, S1 = 0.3826834323650898f, C2 = 0.7071067811865476f;
;     x[4 * 1 + 1] = tw16<INV>(x[5], C1, S1);  x[4 * 1 + 2] = tw16<INV>(x[6], C2, C2);   x[4 * 1 + 3] = tw16<INV>(x[7], S1, C1);
;     x[4 * 2 + 1] = tw16<INV>(x[9], C2, C2);  x[4 * 2 + 2] = tw16<INV>(x[10], 0.f, 1.f); x[4 * 2 + 3] = tw16<INV>(x[11], -C2, C2);
;     x[4 * 3 + 1] = tw16<INV>(x[13], S1, C1); x[4 * 3 + 2] = tw16<INV>(x[14], -C2, C2); x[4 * 3 + 3] = tw16<INV>(x[15], -C1, -S1);
; #pragma unroll
;     for (int q1 = 0; q1 < 4; ++q1) dft4<INV>(x[4 * q1], x[4 * q1 + 1], x[4 * q1 + 2], x[4 * q1 + 3]);
; }
; template <int LST> __device__ __forceinline__ int pass_pos(int base, int phb, int m) {
;     if (LST == 10) return phb + (m << 10);
;     if (LST == 6) return (base ^ (m << 2)) + (m << 6);
;     return PH(base + (m << LST));
; }
; template <bool INV, int LST, bool HALF = false> __device__ __forceinline__ void fft_pass16(LAS cf* z, const LAS cf* Thi, const LAS cf* Tlo, int tid) {
;     constexpr int st = 1 << LST;
;     cf w[16];
; #pragma unroll 1
;     for (int it = 0; it < 2; ++it) {
;         const int g = tid + 512 * it; const int j0 = g & (st - 1); const int base = ((g >> LST) << (LST + 4)) + j0; const int phb = PH(base);
;         if (LST == 10 || it == 0) {
;             const int e1 = j0 << (10 - LST);
;             w[1] = cmul(Thi[e1 >> 7], Tlo[e1 & 127]);
;             w[2] = cmul(w[1], w[1]); w[3] = cmul(w[2], w[1]); w[4] = cmul(w[2], w[2]); w[5] = cmul(w[4], w[1]); w[6] = cmul(w[3], w[3]); w[7] = cmul(w[4], w[3]); w[8] = cmul(w[4], w[4]);
; #pragma unroll
;             for (int q = 9; q < 16; ++q) w[q] = cmul(w[8], w[q - 8]);
;         }
;         cf x[16];
;         if (!INV) {
; #pragma unroll
;             for (int m = 0; m < 16; ++m) { if (HALF && m >= 8) x[m] = (cf){0.f, 0.f}; else x[m] = z[pass_pos<LST>(base, phb, m)]; }
;             dft16<false, HALF>(x);
; #pragma unroll
	v_pk_add_f32 v[58:59], v[70:71], v[74:75] neg_lo:[0,1] neg_hi:[0,1]
	v_mul_f32_e32 v48, 0x3f3504f3, v50
	v_mov_b32_e32 v67, v49
	v_pk_fma_f32 v[48:49], v[50:51], s[38:39], v[48:49] op_sel:[1,0,0] op_sel_hi:[1,1,0] neg_lo:[0,0,1] neg_hi:[0,0,1]
	v_pk_mul_f32 v[50:51], v[52:53], s[42:43] op_sel:[1,0]
	s_nop 0
	v_pk_fma_f32 v[50:51], v[52:53], s[54:55], v[50:51] op_sel_hi:[0,1,1]
	v_pk_add_f32 v[52:53], v[70:71], v[74:75]
	v_pk_add_f32 v[70:71], v[72:73], v[76:77]
	v_pk_add_f32 v[72:73], v[72:73], v[76:77] neg_lo:[0,1] neg_hi:[0,1]
	v_pk_add_f32 v[74:75], v[52:53], v[70:71] neg_lo:[0,1] neg_hi:[0,1]
	v_pk_add_f32 v[76:77], v[58:59], v[72:73] op_sel:[0,1] op_sel_hi:[1,0] neg_hi:[0,1]
	v_pk_add_f32 v[58:59], v[58:59], v[72:73] op_sel:[0,1] op_sel_hi:[1,0] neg_lo:[0,1]
	v_pk_add_f32 v[72:73], v[80:81], v[82:83]
	s_nop 0
	v_pk_add_f32 v[80:81], v[60:61], v[72:73]
	v_pk_add_f32 v[60:61], v[60:61], v[72:73] neg_lo:[0,1] neg_hi:[0,1]
	v_pk_add_f32 v[72:73], v[64:65], v[78:79] op_sel:[0,1] op_sel_hi:[1,0] neg_hi:[0,1]
	v_pk_add_f32 v[64:65], v[64:65], v[78:79] op_sel:[0,1] op_sel_hi:[1,0] neg_lo:[0,1]
	v_pk_add_f32 v[78:79], v[62:63], v[54:55]
	v_pk_add_f32 v[54:55], v[62:63], v[54:55] neg_lo:[0,1] neg_hi:[0,1]
	v_pk_add_f32 v[62:63], v[68:69], v[56:57]
	v_pk_add_f32 v[56:57], v[68:69], v[56:57] neg_lo:[0,1] neg_hi:[0,1]
	v_pk_add_f32 v[68:69], v[78:79], v[62:63]
	v_pk_add_f32 v[62:63], v[78:79], v[62:63] neg_lo:[0,1] neg_hi:[0,1]
	v_pk_add_f32 v[78:79], v[54:55], v[56:57] op_sel:[0,1] op_sel_hi:[1,0] neg_hi:[0,1]
	v_pk_add_f32 v[54:55], v[54:55], v[56:57] op_sel:[0,1] op_sel_hi:[1,0] neg_lo:[0,1]
	v_pk_add_f32 v[56:57], v[46:47], v[48:49]
	v_pk_add_f32 v[46:47], v[46:47], v[48:49] neg_lo:[0,1] neg_hi:[0,1]
	v_pk_add_f32 v[48:49], v[66:67], v[50:51]
	v_pk_add_f32 v[50:51], v[66:67], v[50:51] neg_lo:[0,1] neg_hi:[0,1]
	v_pk_add_f32 v[66:67], v[56:57], v[48:49]
	v_pk_add_f32 v[48:49], v[56:57], v[48:49] neg_lo:[0,1] neg_hi:[0,1]
	v_pk_add_f32 v[56:57], v[46:47], v[50:51] op_sel:[0,1] op_sel_hi:[1,0] neg_hi:[0,1]
	v_pk_add_f32 v[46:47], v[46:47], v[50:51] op_sel:[0,1] op_sel_hi:[1,0] neg_lo:[0,1]
	v_pk_add_f32 v[50:51], v[52:53], v[70:71]
	ds_write_b64 v84, v[50:51]
	v_pk_mul_f32 v[50:51], v[80:81], v[16:17] op_sel:[0,0] op_sel_hi:[0,1]
	s_nop 0
	v_pk_fma_f32 v[50:51], v[80:81], v[16:17], v[50:51] op_sel:[1,1,0] op_sel_hi:[1,0,1] neg_lo:[1,0,0]
	ds_write_b64 v85, v[50:51]
	v_pk_mul_f32 v[50:51], v[68:69], v[18:19] op_sel:[0,0] op_sel_hi:[0,1]
	s_nop 0
	v_pk_fma_f32 v[50:51], v[68:69], v[18:19], v[50:51] op_sel:[1,1,0] op_sel_hi:[1,0,1] neg_lo:[1,0,0]
	ds_write_b64 v86, v[50:51]
	v_pk_mul_f32 v[50:51], v[66:67], v[20:21] op_sel:[0,0] op_sel_hi:[0,1]
	s_nop 0
	v_pk_fma_f32 v[50:51], v[66:67], v[20:21], v[50:51] op_sel:[1,1,0] op_sel_hi:[1,0,1] neg_lo:[1,0,0]
	ds_write_b64 v87, v[50:51]
	v_pk_mul_f32 v[50:51], v[76:77], v[22:23] op_sel:[0,0] op_sel_hi:[0,1]
	s_nop 0
	v_pk_fma_f32 v[50:51], v[76:77], v[22:23], v[50:51] op_sel:[1,1,0] op_sel_hi:[1,0,1] neg_lo:[1,0,0]
	ds_write_b64 v88, v[50:51]
	v_pk_mul_f32 v[50:51], v[72:73], v[24:25] op_sel:[0,0] op_sel_hi:[0,1]
	s_nop 0
	v_pk_fma_f32 v[50:51], v[72:73], v[24:25], v[50:51] op_sel:[1,1,0] op_sel_hi:[1,0,1] neg_lo:[1,0,0]
	ds_write_b64 v89, v[50:51]
	v_pk_mul_f32 v[50:51], v[78:79], v[26:27] op_sel:[0,0] op_sel_hi:[0,1]
	s_nop 0
	v_pk_fma_f32 v[50:51], v[78:79], v[26:27], v[50:51] op_sel:[1,1,0] op_sel_hi:[1,0,1] neg_lo:[1,0,0]
	ds_write_b64 v90, v[50:51]
	v_pk_mul_f32 v[50:51], v[56:57], v[28:29] op_sel:[0,0] op_sel_hi:[0,1]
	s_nop 0
	v_pk_fma_f32 v[50:51], v[56:57], v[28:29], v[50:51] op_sel:[1,1,0] op_sel_hi:[1,0,1] neg_lo:[1,0,0]
	ds_write_b64 v91, v[50:51]
	v_pk_mul_f32 v[50:51], v[74:75], v[30:31] op_sel:[0,0] op_sel_hi:[0,1]
	s_nop 0
	v_pk_fma_f32 v[50:51], v[74:75], v[30:31], v[50:51] op_sel:[1,1,0] op_sel_hi:[1,0,1] neg_lo:[1,0,0]
	ds_write_b64 v92, v[50:51]
	v_pk_mul_f32 v[50:51], v[60:61], v[32:33] op_sel:[0,0] op_sel_hi:[0,1]
	s_nop 0
	v_pk_fma_f32 v[50:51], v[60:61], v[32:33], v[50:51] op_sel:[1,1,0] op_sel_hi:[1,0,1] neg_lo:[1,0,0]
	ds_write_b64 v93, v[50:51]
	v_pk_mul_f32 v[50:51], v[62:63], v[34:35] op_sel:[0,0] op_sel_hi:[0,1]
	s_nop 0
	v_pk_fma_f32 v[50:51], v[62:63], v[34:35], v[50:51] op_sel:[1,1,0] op_sel_hi:[1,0,1] neg_lo:[1,0,0]
	ds_write_b64 v94, v[50:51]
	v_pk_mul_f32 v[50:51], v[48:49], v[36:37] op_sel:[0,0] op_sel_hi:[0,1]
	s_nop 0
	v_pk_fma_f32 v[48:49], v[48:49], v[36:37], v[50:51] op_sel:[1,1,0] op_sel_hi:[1,0,1] neg_lo:[1,0,0]
	ds_write_b64 v95, v[48:49]
	v_pk_mul_f32 v[48:49], v[58:59], v[38:39] op_sel:[0,0] op_sel_hi:[0,1]
	s_nop 0
	v_pk_fma_f32 v[48:49], v[58:59], v[38:39], v[48:49] op_sel:[1,1,0] op_sel_hi:[1,0,1] neg_lo:[1,0,0]
	ds_write_b64 v96, v[48:49]
	v_pk_mul_f32 v[48:49], v[64:65], v[40:41] op_sel:[0,0] op_sel_hi:[0,1]
	s_nop 0
	v_pk_fma_f32 v[48:49], v[64:65], v[40:41], v[48:49] op_sel:[1,1,0] op_sel_hi:[1,0,1] neg_lo:[1,0,0]
	ds_write_b64 v97, v[48:49]
	v_pk_mul_f32 v[48:49], v[54:55], v[42:43] op_sel:[0,0] op_sel_hi:[0,1]
	s_nop 0
	v_pk_fma_f32 v[48:49], v[54:55], v[42:43], v[48:49] op_sel:[1,1,0] op_sel_hi:[1,0,1] neg_lo:[1,0,0]
	ds_write_b64 v98, v[48:49]
	v_pk_mul_f32 v[48:49], v[46:47], v[44:45] op_sel:[0,0] op_sel_hi:[0,1]
	s_nop 0
	v_pk_fma_f32 v[46:47], v[46:47], v[44:45], v[48:49] op_sel:[1,1,0] op_sel_hi:[1,0,1] neg_lo:[1,0,0]
	ds_write_b64 v99, v[46:47]
	s_cbranch_vccz .LBB0_309

; #define LAS __attribute__((address_space(3)))
; template <bool INV, bool HALFIN = false> __device__ __forceinline__ void dft16(cf (&x)[16]) {
; #pragma unroll
;     for (int m2 = 0; m2 < 4; ++m2) {
;         if (HALFIN) { const cf a0 = x[m2], a1 = x[4 + m2]; x[m2] = a0 + a1; x[8 + m2] = a0 - a1; x[4 + m2] = add_mib(a0, a1); x[12 + m2] = add_pib(a0, a1); }
;         else dft4<INV>(x[m2], x[4 + m2], x[8 + m2], x[12 + m2]);
;     }
;     constexpr float C1 = 0.9238795325112867f, S1 = 0.3826834323650898f, C2 = 0.7071067811865476f;
;     x[4 * 1 + 1] = tw16<INV>(x[5], C1, S1);  x[4 * 1 + 2] = tw16<INV>(x[6], C2, C2);   x[4 * 1 + 3] = tw16<INV>(x[7], S1, C1);
;     x[4 * 2 + 1] = tw16<INV>(x[9], C2, C2);  x[4 * 2 + 2] = tw16<INV>(x[10], 0.f, 1.f); x[4 * 2 + 3] = tw16<INV>(x[11], -C2, C2);
;     x[4 * 3 + 1] = tw16<INV>(x[13], S1, C1); x[4 * 3 + 2] = tw16<INV>(x[14], -C2, C2); x[4 * 3 + 3] = tw16<INV>(x[15], -C1, -S1);
; #pragma unroll
;     for (int q1 = 0; q1 < 4; ++q1) dft4<INV>(x[4 * q1], x[4 * q1 + 1], x[4 * q1 + 2], x[4 * q1 + 3]);
; }
; template <int LST> __device__ __forceinline__ int pass_pos(int base, int phb, int m) {
;     if (LST == 10) return phb + (m << 10);
;     if (LST == 6) return (base ^ (m << 2)) + (m << 6);
;     return PH(base + (m << LST));
; }
; template <bool INV, int LST, bool HALF = false> __device__ __forceinline__ void fft_pass16(LAS cf* z, const LAS cf* Thi, const LAS cf* Tlo, int tid) {
;     constexpr int st = 1 << LST;
;     cf w[16];
; #pragma unroll 1
;     for (int it = 0; it < 2; ++it) {
;         const int g = tid + 512 * it; const int j0 = g & (st - 1); const int base = ((g >> LST) << (LST + 4)) + j0; const int phb = PH(base);
;         if (LST == 10 || it == 0) {
;             const int e1 = j0 << (10 - LST);
;             w[1] = cmul(Thi[e1 >> 7], Tlo[e1 & 127]);
;             w[2] = cmul(w[1], w[1]); w[3] = cmul(w[2], w[1]); w[4] = cmul(w[2], w[2]); w[5] = cmul(w[4], w[1]); w[6] = cmul(w[3], w[3]); w[7] = cmul(w[4], w[3]); w[8] = cmul(w[4], w[4]);
; #pragma unroll
;             for (int q = 9; q < 16; ++q) w[q] = cmul(w[8], w[q - 8]);
;         }
;         cf x[16];
;         if (!INV) {
; #pragma unroll
;             for (int m = 0; m < 16; ++m) { if (HALF && m >= 8) x[m] = (cf){0.f, 0.f}; else x[m] = z[pass_pos<LST>(base, phb, m)]; }
;             dft16<false, HALF>(x);
; #pragma unroll
.LBB0_1020:
	v_add_u32_e32 v21, s21, v152
	v_and_b32_e32 v22, 0x3ff, v21
	v_lshlrev_b32_e32 v23, 4, v21
	v_lshrrev_b32_e32 v21, 4, v21
	v_and_b32_e32 v29, 60, v21
	v_and_b32_e32 v21, 56, v21
	v_and_b32_e32 v23, 0x4000, v23
	v_add_u32_e32 v21, 0, v21
	v_bitop3_b32 v22, v23, v29, v22 bitop3:0x36
	v_add_u32_e32 v21, 0x20000, v21
	v_lshl_add_u32 v29, v22, 3, 0
	ds_read_b64 v[22:23], v21
	ds_read_b64 v[30:31], v120
	ds_read2st64_b64 v[48:51], v29 offset1:16
	ds_read2st64_b64 v[52:55], v29 offset0:32 offset1:48
	ds_read2st64_b64 v[56:59], v29 offset0:64 offset1:80
	ds_read2st64_b64 v[60:63], v29 offset0:96 offset1:112
	s_movk_i32 s21, 0x200
	s_waitcnt lgkmcnt(4)
	v_pk_mul_f32 v[38:39], v[22:23], v[30:31] op_sel:[0,0] op_sel_hi:[0,1]
	s_waitcnt lgkmcnt(1)
	v_pk_add_f32 v[66:67], v[48:49], v[56:57] op_sel:[0,1] op_sel_hi:[1,0] neg_hi:[0,1]
	s_waitcnt lgkmcnt(0)
	v_pk_add_f32 v[72:73], v[52:53], v[60:61] neg_lo:[0,1] neg_hi:[0,1]
	v_pk_add_f32 v[68:69], v[50:51], v[58:59] neg_lo:[0,1] neg_hi:[0,1]
	v_pk_add_f32 v[76:77], v[54:55], v[62:63] neg_lo:[0,1] neg_hi:[0,1]
	v_pk_fma_f32 v[82:83], v[72:73], 0, v[72:73] op_sel:[0,0,1] op_sel_hi:[1,0,0]
	v_pk_fma_f32 v[72:73], v[72:73], 0, v[72:73] op_sel:[0,0,1] op_sel_hi:[1,0,0] neg_lo:[0,0,1] neg_hi:[0,0,1]
	v_pk_add_f32 v[42:43], v[48:49], v[56:57]
	v_pk_add_f32 v[64:65], v[48:49], v[56:57] neg_lo:[0,1] neg_hi:[0,1]
	v_pk_add_f32 v[48:49], v[48:49], v[56:57] op_sel:[0,1] op_sel_hi:[1,0] neg_lo:[0,1]
	v_pk_add_f32 v[56:57], v[50:51], v[58:59]
	v_pk_add_f32 v[70:71], v[50:51], v[58:59] op_sel:[0,1] op_sel_hi:[1,0] neg_hi:[0,1]
	v_pk_add_f32 v[50:51], v[50:51], v[58:59] op_sel:[0,1] op_sel_hi:[1,0] neg_lo:[0,1]
	v_pk_add_f32 v[58:59], v[52:53], v[60:61]
	v_pk_add_f32 v[74:75], v[52:53], v[60:61] op_sel:[0,1] op_sel_hi:[1,0] neg_hi:[0,1]
	v_pk_add_f32 v[52:53], v[52:53], v[60:61] op_sel:[0,1] op_sel_hi:[1,0] neg_lo:[0,1]
	v_pk_add_f32 v[60:61], v[54:55], v[62:63]
	v_pk_add_f32 v[78:79], v[54:55], v[62:63] op_sel:[0,1] op_sel_hi:[1,0] neg_hi:[0,1]
	v_pk_add_f32 v[54:55], v[54:55], v[62:63] op_sel:[0,1] op_sel_hi:[1,0] neg_lo:[0,1]
	v_pk_fma_f32 v[22:23], v[22:23], v[30:31], v[38:39] op_sel:[1,1,0] op_sel_hi:[1,0,1] neg_lo:[1,0,0]
	v_pk_mul_f32 v[30:31], v[70:71], s[22:23] op_sel_hi:[1,0]
	v_pk_mul_f32 v[38:39], v[74:75], s[24:25] op_sel_hi:[1,0]
	v_pk_mul_f32 v[62:63], v[78:79], s[20:21] op_sel_hi:[1,0]
	v_pk_mul_f32 v[80:81], v[68:69], s[24:25] op_sel_hi:[1,0]
	v_mul_f32_e32 v72, 0x3f3504f3, v76
	v_pk_mul_f32 v[84:85], v[50:51], s[20:21] op_sel_hi:[1,0]
	s_mov_b32 s48, s37
	s_mov_b32 s49, s22
	v_mul_f32_e32 v86, 0x3f3504f3, v52
	v_pk_mul_f32 v[88:89], v[54:55], s[36:37] op_sel:[1,0]
	v_pk_fma_f32 v[92:93], v[70:71], s[20:21], v[30:31] op_sel:[0,0,1] op_sel_hi:[1,0,0] neg_hi:[0,0,1]
	v_pk_fma_f32 v[70:71], v[74:75], s[24:25], v[38:39] op_sel:[0,0,1] op_sel_hi:[1,0,0] neg_hi:[0,0,1]
	v_pk_fma_f32 v[74:75], v[78:79], s[22:23], v[62:63] op_sel:[0,0,1] op_sel_hi:[1,0,0] neg_hi:[0,0,1]
	v_pk_fma_f32 v[78:79], v[68:69], s[24:25], v[80:81] op_sel:[0,0,1] op_sel_hi:[1,0,0] neg_hi:[0,0,1]
	v_mov_b32_e32 v83, v73
	v_pk_fma_f32 v[72:73], v[76:77], s[24:25], v[72:73] op_sel:[1,0,0] op_sel_hi:[1,1,0] neg_lo:[0,0,1] neg_hi:[0,0,1]
	v_pk_fma_f32 v[76:77], v[50:51], s[22:23], v[84:85] op_sel:[0,0,1] op_sel_hi:[1,0,0] neg_hi:[0,0,1]
	v_pk_add_f32 v[90:91], v[42:43], v[58:59]
	v_pk_add_f32 v[42:43], v[42:43], v[58:59] neg_lo:[0,1] neg_hi:[0,1]
	v_pk_add_f32 v[58:59], v[56:57], v[60:61]
	v_pk_add_f32 v[56:57], v[56:57], v[60:61] neg_lo:[0,1] neg_hi:[0,1]
	v_pk_mul_f32 v[60:61], v[22:23], v[22:23] op_sel:[0,0] op_sel_hi:[0,1]
	v_pk_fma_f32 v[52:53], v[52:53], s[24:25], v[86:87] op_sel:[1,0,0] op_sel_hi:[1,1,0] neg_lo:[0,0,1] neg_hi:[0,0,1]
	v_pk_fma_f32 v[54:55], v[54:55], s[48:49], v[88:89] op_sel_hi:[0,1,1]
	v_pk_add_f32 v[80:81], v[90:91], v[58:59] neg_lo:[0,1] neg_hi:[0,1]
	v_pk_add_f32 v[84:85], v[42:43], v[56:57] op_sel:[0,1] op_sel_hi:[1,0] neg_hi:[0,1]
	v_pk_add_f32 v[42:43], v[42:43], v[56:57] op_sel:[0,1] op_sel_hi:[1,0] neg_lo:[0,1]
	v_pk_add_f32 v[56:57], v[90:91], v[58:59]
	v_pk_fma_f32 v[58:59], v[22:23], v[22:23], v[60:61] op_sel:[1,1,0] op_sel_hi:[1,0,1] neg_lo:[1,0,0]
	v_pk_add_f32 v[30:31], v[64:65], v[82:83]
	v_pk_add_f32 v[38:39], v[64:65], v[82:83] neg_lo:[0,1] neg_hi:[0,1]
	v_pk_add_f32 v[50:51], v[48:49], v[52:53]
	v_pk_add_f32 v[48:49], v[48:49], v[52:53] neg_lo:[0,1] neg_hi:[0,1]
	v_pk_mul_f32 v[60:61], v[58:59], v[58:59] op_sel:[0,0] op_sel_hi:[0,1]
	v_pk_add_f32 v[62:63], v[66:67], v[70:71]
	v_pk_add_f32 v[64:65], v[66:67], v[70:71] neg_lo:[0,1] neg_hi:[0,1]
	v_pk_add_f32 v[66:67], v[92:93], v[74:75]
	v_pk_add_f32 v[68:69], v[92:93], v[74:75] neg_lo:[0,1] neg_hi:[0,1]
	v_pk_add_f32 v[70:71], v[78:79], v[72:73]
	v_pk_add_f32 v[72:73], v[78:79], v[72:73] neg_lo:[0,1] neg_hi:[0,1]
	v_pk_add_f32 v[74:75], v[76:77], v[54:55]
	v_pk_add_f32 v[54:55], v[76:77], v[54:55] neg_lo:[0,1] neg_hi:[0,1]
	v_pk_mul_f32 v[52:53], v[58:59], v[22:23] op_sel:[0,0] op_sel_hi:[0,1]
	v_pk_fma_f32 v[60:61], v[58:59], v[58:59], v[60:61] op_sel:[1,1,0] op_sel_hi:[1,0,1] neg_lo:[1,0,0]
	v_pk_add_f32 v[76:77], v[62:63], v[66:67]
	v_pk_add_f32 v[62:63], v[62:63], v[66:67] neg_lo:[0,1] neg_hi:[0,1]
	v_pk_add_f32 v[66:67], v[64:65], v[68:69] op_sel:[0,1] op_sel_hi:[1,0] neg_hi:[0,1]
	v_pk_add_f32 v[64:65], v[64:65], v[68:69] op_sel:[0,1] op_sel_hi:[1,0] neg_lo:[0,1]
	v_pk_add_f32 v[68:69], v[30:31], v[70:71]
	v_pk_add_f32 v[30:31], v[30:31], v[70:71] neg_lo:[0,1] neg_hi:[0,1]
	v_pk_add_f32 v[70:71], v[38:39], v[72:73] op_sel:[0,1] op_sel_hi:[1,0] neg_hi:[0,1]
	v_pk_add_f32 v[38:39], v[38:39], v[72:73] op_sel:[0,1] op_sel_hi:[1,0] neg_lo:[0,1]
; template <bool INV, int LST, bool HALF = false> __device__ __forceinline__ void fft_pass16(LAS cf* z, const LAS cf* Thi, const LAS cf* Tlo, int tid) {
;     ...
;         const int g = tid + 512 * it; const int j0 = g & (st - 1); const int base = ((g >> LST) << (LST + 4)) + j0; const int phb = PH(base);
;         if (LST == 10 || it == 0) {
;             const int e1 = j0 << (10 - LST);
;             w[1] = cmul(Thi[e1 >> 7], Tlo[e1 & 127]);
;             w[2] = cmul(w[1], w[1]); w[3] = cmul(w[2], w[1]); w[4] = cmul(w[2], w[2]); w[5] = cmul(w[4], w[1]); w[6] = cmul(w[3], w[3]); w[7] = cmul(w[4], w[3]); w[8] = cmul(w[4], w[4]);
; #pragma unroll
;             for (int q = 9; q < 16; ++q) w[q] = cmul(w[8], w[q - 8]);
;         }
;         cf x[16];
;         if (!INV) {
; #pragma unroll
;             for (int m = 0; m < 16; ++m) { if (HALF && m >= 8) x[m] = (cf){0.f, 0.f}; else x[m] = z[pass_pos<LST>(base, phb, m)]; }
;             dft16<false, HALF>(x);
; #pragma unroll
;             for (int q = 0; q < 16; ++q) { cf y = x[4 * (q & 3) + (q >> 2)]; if (q) y = cmul(y, w[q]); z[pass_pos<LST>(base, phb, q)] = y; }
	v_pk_add_f32 v[72:73], v[50:51], v[74:75]
	v_pk_add_f32 v[50:51], v[50:51], v[74:75] neg_lo:[0,1] neg_hi:[0,1]
	v_pk_add_f32 v[74:75], v[48:49], v[54:55] op_sel:[0,1] op_sel_hi:[1,0] neg_hi:[0,1]
	v_pk_add_f32 v[48:49], v[48:49], v[54:55] op_sel:[0,1] op_sel_hi:[1,0] neg_lo:[0,1]
	v_pk_mul_f32 v[54:55], v[60:61], v[22:23] op_sel:[0,0] op_sel_hi:[0,1]
	v_pk_mul_f32 v[86:87], v[60:61], v[60:61] op_sel:[0,0] op_sel_hi:[0,1]
	v_pk_mul_f32 v[88:89], v[76:77], v[22:23] op_sel:[0,0] op_sel_hi:[0,1]
	v_pk_fma_f32 v[52:53], v[58:59], v[22:23], v[52:53] op_sel:[1,1,0] op_sel_hi:[1,0,1] neg_lo:[1,0,0]
	v_pk_mul_f32 v[90:91], v[68:69], v[58:59] op_sel:[0,0] op_sel_hi:[0,1]
	v_pk_mul_f32 v[94:95], v[84:85], v[60:61] op_sel:[0,0] op_sel_hi:[0,1]
	s_nop 0
	v_pk_fma_f32 v[54:55], v[60:61], v[22:23], v[54:55] op_sel:[1,1,0] op_sel_hi:[1,0,1] neg_lo:[1,0,0]
	v_pk_fma_f32 v[86:87], v[60:61], v[60:61], v[86:87] op_sel:[1,1,0] op_sel_hi:[1,0,1] neg_lo:[1,0,0]
	v_pk_fma_f32 v[76:77], v[76:77], v[22:23], v[88:89] op_sel:[1,1,0] op_sel_hi:[1,0,1] neg_lo:[1,0,0]
	v_pk_mul_f32 v[78:79], v[52:53], v[52:53] op_sel:[0,0] op_sel_hi:[0,1]
	v_pk_fma_f32 v[68:69], v[68:69], v[58:59], v[90:91] op_sel:[1,1,0] op_sel_hi:[1,0,1] neg_lo:[1,0,0]
	v_pk_mul_f32 v[82:83], v[60:61], v[52:53] op_sel:[0,0] op_sel_hi:[0,1]
	v_pk_mul_f32 v[92:93], v[72:73], v[52:53] op_sel:[0,0] op_sel_hi:[0,1]
	s_nop 0
	v_pk_mul_f32 v[88:89], v[86:87], v[22:23] op_sel:[0,0] op_sel_hi:[0,1]
	v_pk_fma_f32 v[84:85], v[84:85], v[60:61], v[94:95] op_sel:[1,1,0] op_sel_hi:[1,0,1] neg_lo:[1,0,0]
	v_pk_fma_f32 v[78:79], v[52:53], v[52:53], v[78:79] op_sel:[1,1,0] op_sel_hi:[1,0,1] neg_lo:[1,0,0]
	v_pk_mul_f32 v[96:97], v[86:87], v[54:55] op_sel:[0,0] op_sel_hi:[0,1]
	s_and_b64 vcc, exec, s[46:47]
	v_pk_fma_f32 v[72:73], v[72:73], v[52:53], v[92:93] op_sel:[1,1,0] op_sel_hi:[1,0,1] neg_lo:[1,0,0]
	ds_write2st64_b64 v29, v[56:57], v[76:77] offset1:16
	ds_write2st64_b64 v29, v[68:69], v[72:73] offset0:32 offset1:48
	v_pk_mul_f32 v[56:57], v[66:67], v[54:55] op_sel:[0,0] op_sel_hi:[0,1]
	v_pk_mul_f32 v[68:69], v[70:71], v[78:79] op_sel:[0,0] op_sel_hi:[0,1]
	v_pk_fma_f32 v[22:23], v[86:87], v[22:23], v[88:89] op_sel:[1,1,0] op_sel_hi:[1,0,1] neg_lo:[1,0,0]
	v_pk_fma_f32 v[88:89], v[86:87], v[54:55], v[96:97] op_sel:[1,1,0] op_sel_hi:[1,0,1] neg_lo:[1,0,0]
	s_mov_b64 s[46:47], 0
	v_pk_fma_f32 v[54:55], v[66:67], v[54:55], v[56:57] op_sel:[1,1,0] op_sel_hi:[1,0,1] neg_lo:[1,0,0]
	v_add_u32_e32 v21, 0x10000, v29
	v_add_u32_e32 v37, 0x12000, v29
	v_pk_fma_f32 v[82:83], v[60:61], v[52:53], v[82:83] op_sel:[1,1,0] op_sel_hi:[1,0,1] neg_lo:[1,0,0]
	v_pk_mul_f32 v[90:91], v[86:87], v[58:59] op_sel:[0,0] op_sel_hi:[0,1]
	v_pk_mul_f32 v[92:93], v[86:87], v[52:53] op_sel:[0,0] op_sel_hi:[0,1]
	v_pk_mul_f32 v[76:77], v[80:81], v[86:87] op_sel:[0,0] op_sel_hi:[0,1]
	v_pk_fma_f32 v[56:57], v[70:71], v[78:79], v[68:69] op_sel:[1,1,0] op_sel_hi:[1,0,1] neg_lo:[1,0,0]
	v_add_u32_e32 v41, 0x14000, v29
	v_pk_mul_f32 v[72:73], v[74:75], v[82:83] op_sel:[0,0] op_sel_hi:[0,1]
	v_pk_fma_f32 v[52:53], v[86:87], v[52:53], v[92:93] op_sel:[1,1,0] op_sel_hi:[1,0,1] neg_lo:[1,0,0]
	v_pk_fma_f32 v[68:69], v[80:81], v[86:87], v[76:77] op_sel:[1,1,0] op_sel_hi:[1,0,1] neg_lo:[1,0,0]
	v_add_u32_e32 v102, 0x16000, v29
	v_pk_fma_f32 v[66:67], v[74:75], v[82:83], v[72:73] op_sel:[1,1,0] op_sel_hi:[1,0,1] neg_lo:[1,0,0]
	ds_write2st64_b64 v29, v[84:85], v[54:55] offset0:64 offset1:80
	ds_write2st64_b64 v29, v[56:57], v[66:67] offset0:96 offset1:112
	ds_write_b64 v21, v[68:69]
	v_pk_mul_f32 v[54:55], v[62:63], v[22:23] op_sel:[0,0] op_sel_hi:[0,1]
	v_add_u32_e32 v103, 0x18000, v29
	v_pk_fma_f32 v[22:23], v[62:63], v[22:23], v[54:55] op_sel:[1,1,0] op_sel_hi:[1,0,1] neg_lo:[1,0,0]
	v_add_u32_e32 v104, 0x1a000, v29
	v_add_u32_e32 v105, 0x1c000, v29
	v_add_u32_e32 v106, 0x1e000, v29
	v_pk_mul_f32 v[94:95], v[86:87], v[60:61] op_sel:[0,0] op_sel_hi:[0,1]
	v_pk_mul_f32 v[98:99], v[86:87], v[78:79] op_sel:[0,0] op_sel_hi:[0,1]
	v_pk_mul_f32 v[100:101], v[86:87], v[82:83] op_sel:[0,0] op_sel_hi:[0,1]
	v_pk_fma_f32 v[58:59], v[86:87], v[58:59], v[90:91] op_sel:[1,1,0] op_sel_hi:[1,0,1] neg_lo:[1,0,0]
	v_pk_mul_f32 v[66:67], v[50:51], v[52:53] op_sel:[0,0] op_sel_hi:[0,1]
	v_pk_mul_f32 v[70:71], v[64:65], v[88:89] op_sel:[0,0] op_sel_hi:[0,1]
	s_nop 0
	v_pk_fma_f32 v[60:61], v[86:87], v[60:61], v[94:95] op_sel:[1,1,0] op_sel_hi:[1,0,1] neg_lo:[1,0,0]
	v_pk_fma_f32 v[90:91], v[86:87], v[78:79], v[98:99] op_sel:[1,1,0] op_sel_hi:[1,0,1] neg_lo:[1,0,0]
	v_pk_fma_f32 v[92:93], v[86:87], v[82:83], v[100:101] op_sel:[1,1,0] op_sel_hi:[1,0,1] neg_lo:[1,0,0]
	v_pk_mul_f32 v[56:57], v[30:31], v[58:59] op_sel:[0,0] op_sel_hi:[0,1]
	v_pk_fma_f32 v[50:51], v[50:51], v[52:53], v[66:67] op_sel:[1,1,0] op_sel_hi:[1,0,1] neg_lo:[1,0,0]
	v_pk_fma_f32 v[52:53], v[64:65], v[88:89], v[70:71] op_sel:[1,1,0] op_sel_hi:[1,0,1] neg_lo:[1,0,0]
	s_nop 0
	v_pk_mul_f32 v[68:69], v[42:43], v[60:61] op_sel:[0,0] op_sel_hi:[0,1]
	v_pk_mul_f32 v[72:73], v[38:39], v[90:91] op_sel:[0,0] op_sel_hi:[0,1]
	v_pk_mul_f32 v[74:75], v[48:49], v[92:93] op_sel:[0,0] op_sel_hi:[0,1]
	v_pk_fma_f32 v[30:31], v[30:31], v[58:59], v[56:57] op_sel:[1,1,0] op_sel_hi:[1,0,1] neg_lo:[1,0,0]
	s_nop 0
	v_pk_fma_f32 v[42:43], v[42:43], v[60:61], v[68:69] op_sel:[1,1,0] op_sel_hi:[1,0,1] neg_lo:[1,0,0]
	v_pk_fma_f32 v[38:39], v[38:39], v[90:91], v[72:73] op_sel:[1,1,0] op_sel_hi:[1,0,1] neg_lo:[1,0,0]
	v_pk_fma_f32 v[48:49], v[48:49], v[92:93], v[74:75] op_sel:[1,1,0] op_sel_hi:[1,0,1] neg_lo:[1,0,0]
	ds_write_b64 v37, v[22:23]
	ds_write_b64 v41, v[30:31]
	ds_write_b64 v102, v[50:51]
	ds_write_b64 v103, v[42:43]
	ds_write_b64 v104, v[52:53]
	ds_write_b64 v105, v[38:39]
	ds_write_b64 v106, v[48:49]
	s_cbranch_vccnz .LBB0_1020
	s_mov_b32 s21, 0
	s_mov_b64 s[46:47], -1
	s_waitcnt lgkmcnt(0)
	s_barrier
	s_branch .LBB0_1023
; #define LAS __attribute__((address_space(3)))
; template <bool INV, bool HALFIN = false> __device__ __forceinline__ void dft16(cf (&x)[16]) {
; #pragma unroll
;     for (int m2 = 0; m2 < 4; ++m2) {
;         if (HALFIN) { const cf a0 = x[m2], a1 = x[4 + m2]; x[m2] = a0 + a1; x[8 + m2] = a0 - a1; x[4 + m2] = add_mib(a0, a1); x[12 + m2] = add_pib(a0, a1); }
;         else dft4<INV>(x[m2], x[4 + m2], x[8 + m2], x[12 + m2]);
;     }
;     constexpr float C1 = 0.9238795325112867f, S1 = 0.3826834323650898f, C2 = 0.7071067811865476f;
;     x[4 * 1 + 1] = tw16<INV>(x[5], C1, S1);  x[4 * 1 + 2] = tw16<INV>(x[6], C2, C2);   x[4 * 1 + 3] = tw16<INV>(x[7], S1, C1);
;     x[4 * 2 + 1] = tw16<INV>(x[9], C2, C2);  x[4 * 2 + 2] = tw16<INV>(x[10], 0.f, 1.f); x[4 * 2 + 3] = tw16<INV>(x[11], -C2, C2);
;     x[4 * 3 + 1] = tw16<INV>(x[13], S1, C1); x[4 * 3 + 2] = tw16<INV>(x[14], -C2, C2); x[4 * 3 + 3] = tw16<INV>(x[15], -C1, -S1);
; #pragma unroll
;     for (int q1 = 0; q1 < 4; ++q1) dft4<INV>(x[4 * q1], x[4 * q1 + 1], x[4 * q1 + 2], x[4 * q1 + 3]);
; }
; template <int LST> __device__ __forceinline__ int pass_pos(int base, int phb, int m) {
;     if (LST == 10) return phb + (m << 10);
;     if (LST == 6) return (base ^ (m << 2)) + (m << 6);
;     return PH(base + (m << LST));
; }
; template <bool INV, int LST, bool HALF = false> __device__ __forceinline__ void fft_pass16(LAS cf* z, const LAS cf* Thi, const LAS cf* Tlo, int tid) {
;     constexpr int st = 1 << LST;
;     cf w[16];
; #pragma unroll 1
;     for (int it = 0; it < 2; ++it) {
;         const int g = tid + 512 * it; const int j0 = g & (st - 1); const int base = ((g >> LST) << (LST + 4)) + j0; const int phb = PH(base);
;         if (LST == 10 || it == 0) {
;             const int e1 = j0 << (10 - LST);
;             w[1] = cmul(Thi[e1 >> 7], Tlo[e1 & 127]);
;             w[2] = cmul(w[1], w[1]); w[3] = cmul(w[2], w[1]); w[4] = cmul(w[2], w[2]); w[5] = cmul(w[4], w[1]); w[6] = cmul(w[3], w[3]); w[7] = cmul(w[4], w[3]); w[8] = cmul(w[4], w[4]);
; #pragma unroll
;             for (int q = 9; q < 16; ++q) w[q] = cmul(w[8], w[q - 8]);
;         }
;         cf x[16];
;         if (!INV) {
; #pragma unroll
;             for (int m = 0; m < 16; ++m) { if (HALF && m >= 8) x[m] = (cf){0.f, 0.f}; else x[m] = z[pass_pos<LST>(base, phb, m)]; }
;             dft16<false, HALF>(x);
; #pragma unroll
.LBB0_1022:
	v_add_u32_e32 v21, s21, v169
	v_and_b32_e32 v21, 0x7c00, v21
	v_or_b32_e32 v29, v21, v122
	v_lshl_add_u32 v29, v29, 3, 0
	v_xor_b32_e32 v109, 0x80, v29
	v_xor_b32_e32 v113, 0x100, v29
	v_xor_b32_e32 v110, 0xa0, v29
	v_xor_b32_e32 v114, 0x120, v29
	v_xor_b32_e32 v182, 0x180, v29
	v_xor_b32_e32 v111, 0xc0, v29
	v_xor_b32_e32 v115, 0x140, v29
	v_xor_b32_e32 v183, 0x1a0, v29
	v_xor_b32_e32 v37, 0x20, v29
	v_xor_b32_e32 v41, 0x40, v29
	v_xor_b32_e32 v108, 0x60, v29
	ds_read_b64 v[70:71], v29
	ds_read_b64 v[72:73], v37 offset:512
	ds_read_b64 v[74:75], v41 offset:1024
	ds_read_b64 v[76:77], v108 offset:1536
	v_xor_b32_e32 v112, 0xe0, v29
	ds_read_b64 v[78:79], v109 offset:2048
	ds_read_b64 v[80:81], v110 offset:2560
	ds_read_b64 v[82:83], v111 offset:3072
	ds_read_b64 v[84:85], v112 offset:3584
	v_xor_b32_e32 v125, 0x160, v29
	ds_read_b64 v[86:87], v113 offset:4096
	ds_read_b64 v[88:89], v114 offset:4608
	ds_read_b64 v[90:91], v115 offset:5120
	ds_read_b64 v[92:93], v125 offset:5632
	v_xor_b32_e32 v216, 0x1c0, v29
	v_xor_b32_e32 v21, 0x1e0, v29
	ds_read_b64 v[94:95], v182 offset:6144
	ds_read_b64 v[96:97], v183 offset:6656
	ds_read_b64 v[98:99], v216 offset:7168
	ds_read_b64 v[100:101], v21 offset:7680
	s_waitcnt lgkmcnt(7)
	v_pk_add_f32 v[102:103], v[70:71], v[86:87]
	v_pk_add_f32 v[70:71], v[70:71], v[86:87] neg_lo:[0,1] neg_hi:[0,1]
	s_waitcnt lgkmcnt(3)
	v_pk_add_f32 v[86:87], v[78:79], v[94:95]
	v_pk_add_f32 v[78:79], v[78:79], v[94:95] neg_lo:[0,1] neg_hi:[0,1]
	v_pk_add_f32 v[94:95], v[102:103], v[86:87]
	v_pk_add_f32 v[86:87], v[102:103], v[86:87] neg_lo:[0,1] neg_hi:[0,1]
	v_pk_add_f32 v[102:103], v[70:71], v[78:79] op_sel:[0,1] op_sel_hi:[1,0] neg_hi:[0,1]
	v_pk_add_f32 v[70:71], v[70:71], v[78:79] op_sel:[0,1] op_sel_hi:[1,0] neg_lo:[0,1]
	v_pk_add_f32 v[78:79], v[72:73], v[88:89]
	v_pk_add_f32 v[72:73], v[72:73], v[88:89] neg_lo:[0,1] neg_hi:[0,1]
	s_waitcnt lgkmcnt(2)
	v_pk_add_f32 v[88:89], v[80:81], v[96:97]
	v_pk_add_f32 v[80:81], v[80:81], v[96:97] neg_lo:[0,1] neg_hi:[0,1]
	v_pk_add_f32 v[96:97], v[78:79], v[88:89]
	v_pk_add_f32 v[78:79], v[78:79], v[88:89] neg_lo:[0,1] neg_hi:[0,1]
	v_pk_add_f32 v[88:89], v[72:73], v[80:81] op_sel:[0,1] op_sel_hi:[1,0] neg_hi:[0,1]
	v_pk_add_f32 v[72:73], v[72:73], v[80:81] op_sel:[0,1] op_sel_hi:[1,0] neg_lo:[0,1]
	v_pk_add_f32 v[80:81], v[74:75], v[90:91]
	v_pk_add_f32 v[74:75], v[74:75], v[90:91] neg_lo:[0,1] neg_hi:[0,1]
	s_waitcnt lgkmcnt(1)
	v_pk_add_f32 v[90:91], v[82:83], v[98:99]
	v_pk_add_f32 v[82:83], v[82:83], v[98:99] neg_lo:[0,1] neg_hi:[0,1]
	v_pk_add_f32 v[98:99], v[80:81], v[90:91]
	v_pk_add_f32 v[80:81], v[80:81], v[90:91] neg_lo:[0,1] neg_hi:[0,1]
	v_pk_add_f32 v[90:91], v[74:75], v[82:83] op_sel:[0,1] op_sel_hi:[1,0] neg_hi:[0,1]
	v_pk_add_f32 v[74:75], v[74:75], v[82:83] op_sel:[0,1] op_sel_hi:[1,0] neg_lo:[0,1]
	v_pk_add_f32 v[82:83], v[76:77], v[92:93]
	v_pk_add_f32 v[76:77], v[76:77], v[92:93] neg_lo:[0,1] neg_hi:[0,1]
	s_waitcnt lgkmcnt(0)
	v_pk_add_f32 v[92:93], v[84:85], v[100:101]
	v_pk_add_f32 v[84:85], v[84:85], v[100:101] neg_lo:[0,1] neg_hi:[0,1]
	v_pk_add_f32 v[100:101], v[82:83], v[92:93]
	v_pk_add_f32 v[82:83], v[82:83], v[92:93] neg_lo:[0,1] neg_hi:[0,1]
	v_pk_add_f32 v[92:93], v[76:77], v[84:85] op_sel:[0,1] op_sel_hi:[1,0] neg_hi:[0,1]
	v_pk_add_f32 v[76:77], v[76:77], v[84:85] op_sel:[0,1] op_sel_hi:[1,0] neg_lo:[0,1]
	v_pk_mul_f32 v[84:85], v[88:89], s[22:23] op_sel_hi:[1,0]
	s_mov_b32 s48, s37
	v_pk_fma_f32 v[104:105], v[88:89], s[20:21], v[84:85] op_sel:[0,0,1] op_sel_hi:[1,0,0] neg_hi:[0,0,1]
	s_mov_b32 s49, s22
	v_pk_mul_f32 v[84:85], v[90:91], s[24:25] op_sel_hi:[1,0]
	s_andn2_b64 vcc, exec, s[46:47]
	v_pk_fma_f32 v[88:89], v[90:91], s[24:25], v[84:85] op_sel:[0,0,1] op_sel_hi:[1,0,0] neg_hi:[0,0,1]
	v_pk_mul_f32 v[90:91], v[92:93], s[20:21] op_sel_hi:[1,0]
	s_nop 0
	v_pk_fma_f32 v[106:107], v[92:93], s[22:23], v[90:91] op_sel:[0,0,1] op_sel_hi:[1,0,0] neg_hi:[0,0,1]
	v_pk_add_f32 v[84:85], v[102:103], v[88:89]
	v_pk_mul_f32 v[90:91], v[78:79], s[24:25] op_sel_hi:[1,0]
	v_pk_add_f32 v[88:89], v[102:103], v[88:89] neg_lo:[0,1] neg_hi:[0,1]
	v_pk_fma_f32 v[92:93], v[78:79], s[24:25], v[90:91] op_sel:[0,0,1] op_sel_hi:[1,0,0] neg_hi:[0,0,1]
	v_pk_add_f32 v[102:103], v[104:105], v[106:107] neg_lo:[0,1] neg_hi:[0,1]
	v_pk_fma_f32 v[78:79], v[80:81], 0, v[80:81] op_sel:[0,0,1] op_sel_hi:[1,0,0]
	v_pk_fma_f32 v[80:81], v[80:81], 0, v[80:81] op_sel:[0,0,1] op_sel_hi:[1,0,0] neg_lo:[0,0,1] neg_hi:[0,0,1]
	s_mov_b64 s[46:47], 0
	v_mul_f32_e32 v80, 0x3f3504f3, v82
	v_mov_b32_e32 v79, v81
	v_pk_fma_f32 v[80:81], v[82:83], s[24:25], v[80:81] op_sel:[1,0,0] op_sel_hi:[1,1,0] neg_lo:[0,0,1] neg_hi:[0,0,1]
	v_pk_mul_f32 v[82:83], v[72:73], s[20:21] op_sel_hi:[1,0]
	s_movk_i32 s21, 0x2000
	v_pk_fma_f32 v[90:91], v[72:73], s[22:23], v[82:83] op_sel:[0,0,1] op_sel_hi:[1,0,0]
	v_pk_fma_f32 v[72:73], v[72:73], s[22:23], v[82:83] op_sel:[0,0,1] op_sel_hi:[1,0,0] neg_lo:[0,0,1] neg_hi:[0,0,1]
	v_pk_add_f32 v[82:83], v[94:95], v[98:99] neg_lo:[0,1] neg_hi:[0,1]
	v_mul_f32_e32 v72, 0x3f3504f3, v74
	v_mov_b32_e32 v91, v73
	v_pk_fma_f32 v[72:73], v[74:75], s[24:25], v[72:73] op_sel:[1,0,0] op_sel_hi:[1,1,0] neg_lo:[0,0,1] neg_hi:[0,0,1]
	v_pk_mul_f32 v[74:75], v[76:77], s[36:37] op_sel:[1,0]
	s_nop 0
; #define LAS __attribute__((address_space(3)))
; template <bool INV, bool HALFIN = false> __device__ __forceinline__ void dft16(cf (&x)[16]) {
; #pragma unroll
;     for (int m2 = 0; m2 < 4; ++m2) {
;         if (HALFIN) { const cf a0 = x[m2], a1 = x[4 + m2]; x[m2] = a0 + a1; x[8 + m2] = a0 - a1; x[4 + m2] = add_mib(a0, a1); x[12 + m2] = add_pib(a0, a1); }
;         else dft4<INV>(x[m2], x[4 + m2], x[8 + m2], x[12 + m2]);
;     }
;     constexpr float C1 = 0.9238795325112867f, S1 = 0.3826834323650898f, C2 = 0.7071067811865476f;
;     x[4 * 1 + 1] = tw16<INV>(x[5], C1, S1);  x[4 * 1 + 2] = tw16<INV>(x[6], C2, C2);   x[4 * 1 + 3] = tw16<INV>(x[7], S1, C1);
;     x[4 * 2 + 1] = tw16<INV>(x[9], C2, C2);  x[4 * 2 + 2] = tw16<INV>(x[10], 0.f, 1.f); x[4 * 2 + 3] = tw16<INV>(x[11], -C2, C2);
;     x[4 * 3 + 1] = tw16<INV>(x[13], S1, C1); x[4 * 3 + 2] = tw16<INV>(x[14], -C2, C2); x[4 * 3 + 3] = tw16<INV>(x[15], -C1, -S1);
; #pragma unroll
;     for (int q1 = 0; q1 < 4; ++q1) dft4<INV>(x[4 * q1], x[4 * q1 + 1], x[4 * q1 + 2], x[4 * q1 + 3]);
; }
; template <int LST> __device__ __forceinline__ int pass_pos(int base, int phb, int m) {
;     if (LST == 10) return phb + (m << 10);
;     if (LST == 6) return (base ^ (m << 2)) + (m << 6);
;     return PH(base + (m << LST));
; }
; template <bool INV, int LST, bool HALF = false> __device__ __forceinline__ void fft_pass16(LAS cf* z, const LAS cf* Thi, const LAS cf* Tlo, int tid) {
;     constexpr int st = 1 << LST;
;     cf w[16];
; #pragma unroll 1
;     for (int it = 0; it < 2; ++it) {
;         const int g = tid + 512 * it; const int j0 = g & (st - 1); const int base = ((g >> LST) << (LST + 4)) + j0; const int phb = PH(base);
;         if (LST == 10 || it == 0) {
;             const int e1 = j0 << (10 - LST);
;             w[1] = cmul(Thi[e1 >> 7], Tlo[e1 & 127]);
;             w[2] = cmul(w[1], w[1]); w[3] = cmul(w[2], w[1]); w[4] = cmul(w[2], w[2]); w[5] = cmul(w[4], w[1]); w[6] = cmul(w[3], w[3]); w[7] = cmul(w[4], w[3]); w[8] = cmul(w[4], w[4]);
; #pragma unroll
;             for (int q = 9; q < 16; ++q) w[q] = cmul(w[8], w[q - 8]);
;         }
;         cf x[16];
;         if (!INV) {
; #pragma unroll
;             for (int m = 0; m < 16; ++m) { if (HALF && m >= 8) x[m] = (cf){0.f, 0.f}; else x[m] = z[pass_pos<LST>(base, phb, m)]; }
;             dft16<false, HALF>(x);
; #pragma unroll
	v_pk_fma_f32 v[74:75], v[76:77], s[48:49], v[74:75] op_sel_hi:[0,1,1]
	v_pk_add_f32 v[76:77], v[94:95], v[98:99]
	v_pk_add_f32 v[94:95], v[96:97], v[100:101]
	v_pk_add_f32 v[96:97], v[96:97], v[100:101] neg_lo:[0,1] neg_hi:[0,1]
	v_pk_add_f32 v[98:99], v[76:77], v[94:95] neg_lo:[0,1] neg_hi:[0,1]
	v_pk_add_f32 v[100:101], v[82:83], v[96:97] op_sel:[0,1] op_sel_hi:[1,0] neg_hi:[0,1]
	v_pk_add_f32 v[82:83], v[82:83], v[96:97] op_sel:[0,1] op_sel_hi:[1,0] neg_lo:[0,1]
	v_pk_add_f32 v[96:97], v[104:105], v[106:107]
	s_nop 0
	v_pk_add_f32 v[104:105], v[84:85], v[96:97]
	v_pk_add_f32 v[84:85], v[84:85], v[96:97] neg_lo:[0,1] neg_hi:[0,1]
	v_pk_add_f32 v[96:97], v[88:89], v[102:103] op_sel:[0,1] op_sel_hi:[1,0] neg_hi:[0,1]
	v_pk_add_f32 v[88:89], v[88:89], v[102:103] op_sel:[0,1] op_sel_hi:[1,0] neg_lo:[0,1]
	v_pk_add_f32 v[102:103], v[86:87], v[78:79]
	v_pk_add_f32 v[78:79], v[86:87], v[78:79] neg_lo:[0,1] neg_hi:[0,1]
	v_pk_add_f32 v[86:87], v[92:93], v[80:81]
	v_pk_add_f32 v[80:81], v[92:93], v[80:81] neg_lo:[0,1] neg_hi:[0,1]
	v_pk_add_f32 v[92:93], v[102:103], v[86:87]
	v_pk_add_f32 v[86:87], v[102:103], v[86:87] neg_lo:[0,1] neg_hi:[0,1]
	v_pk_add_f32 v[102:103], v[78:79], v[80:81] op_sel:[0,1] op_sel_hi:[1,0] neg_hi:[0,1]
	v_pk_add_f32 v[78:79], v[78:79], v[80:81] op_sel:[0,1] op_sel_hi:[1,0] neg_lo:[0,1]
	v_pk_add_f32 v[80:81], v[70:71], v[72:73]
	v_pk_add_f32 v[70:71], v[70:71], v[72:73] neg_lo:[0,1] neg_hi:[0,1]
	v_pk_add_f32 v[72:73], v[90:91], v[74:75]
	v_pk_add_f32 v[74:75], v[90:91], v[74:75] neg_lo:[0,1] neg_hi:[0,1]
	v_pk_add_f32 v[90:91], v[80:81], v[72:73]
	v_pk_add_f32 v[72:73], v[80:81], v[72:73] neg_lo:[0,1] neg_hi:[0,1]
	v_pk_add_f32 v[80:81], v[70:71], v[74:75] op_sel:[0,1] op_sel_hi:[1,0] neg_hi:[0,1]
	v_pk_add_f32 v[70:71], v[70:71], v[74:75] op_sel:[0,1] op_sel_hi:[1,0] neg_lo:[0,1]
	v_pk_add_f32 v[74:75], v[76:77], v[94:95]
	ds_write_b64 v29, v[74:75]
	v_pk_mul_f32 v[74:75], v[104:105], v[22:23] op_sel:[0,0] op_sel_hi:[0,1]
	s_nop 0
	v_pk_fma_f32 v[74:75], v[104:105], v[22:23], v[74:75] op_sel:[1,1,0] op_sel_hi:[1,0,1] neg_lo:[1,0,0]
	ds_write_b64 v37, v[74:75] offset:512
	v_pk_mul_f32 v[74:75], v[92:93], v[30:31] op_sel:[0,0] op_sel_hi:[0,1]
	s_nop 0
	v_pk_fma_f32 v[74:75], v[92:93], v[30:31], v[74:75] op_sel:[1,1,0] op_sel_hi:[1,0,1] neg_lo:[1,0,0]
	ds_write_b64 v41, v[74:75] offset:1024
	v_pk_mul_f32 v[74:75], v[90:91], v[38:39] op_sel:[0,0] op_sel_hi:[0,1]
	s_nop 0
	v_pk_fma_f32 v[74:75], v[90:91], v[38:39], v[74:75] op_sel:[1,1,0] op_sel_hi:[1,0,1] neg_lo:[1,0,0]
	ds_write_b64 v108, v[74:75] offset:1536
	v_pk_mul_f32 v[74:75], v[100:101], v[42:43] op_sel:[0,0] op_sel_hi:[0,1]
	s_nop 0
	v_pk_fma_f32 v[74:75], v[100:101], v[42:43], v[74:75] op_sel:[1,1,0] op_sel_hi:[1,0,1] neg_lo:[1,0,0]
	ds_write_b64 v109, v[74:75] offset:2048
	v_pk_mul_f32 v[74:75], v[96:97], v[48:49] op_sel:[0,0] op_sel_hi:[0,1]
	s_nop 0
	v_pk_fma_f32 v[74:75], v[96:97], v[48:49], v[74:75] op_sel:[1,1,0] op_sel_hi:[1,0,1] neg_lo:[1,0,0]
	ds_write_b64 v110, v[74:75] offset:2560
	v_pk_mul_f32 v[74:75], v[102:103], v[50:51] op_sel:[0,0] op_sel_hi:[0,1]
	s_nop 0
	v_pk_fma_f32 v[74:75], v[102:103], v[50:51], v[74:75] op_sel:[1,1,0] op_sel_hi:[1,0,1] neg_lo:[1,0,0]
	ds_write_b64 v111, v[74:75] offset:3072
	v_pk_mul_f32 v[74:75], v[80:81], v[52:53] op_sel:[0,0] op_sel_hi:[0,1]
	s_nop 0
	v_pk_fma_f32 v[74:75], v[80:81], v[52:53], v[74:75] op_sel:[1,1,0] op_sel_hi:[1,0,1] neg_lo:[1,0,0]
	ds_write_b64 v112, v[74:75] offset:3584
	v_pk_mul_f32 v[74:75], v[98:99], v[54:55] op_sel:[0,0] op_sel_hi:[0,1]
	s_nop 0
	v_pk_fma_f32 v[74:75], v[98:99], v[54:55], v[74:75] op_sel:[1,1,0] op_sel_hi:[1,0,1] neg_lo:[1,0,0]
	ds_write_b64 v113, v[74:75] offset:4096
	v_pk_mul_f32 v[74:75], v[84:85], v[56:57] op_sel:[0,0] op_sel_hi:[0,1]
	s_nop 0
	v_pk_fma_f32 v[74:75], v[84:85], v[56:57], v[74:75] op_sel:[1,1,0] op_sel_hi:[1,0,1] neg_lo:[1,0,0]
	ds_write_b64 v114, v[74:75] offset:4608
	v_pk_mul_f32 v[74:75], v[86:87], v[58:59] op_sel:[0,0] op_sel_hi:[0,1]
	s_nop 0
	v_pk_fma_f32 v[74:75], v[86:87], v[58:59], v[74:75] op_sel:[1,1,0] op_sel_hi:[1,0,1] neg_lo:[1,0,0]
	ds_write_b64 v115, v[74:75] offset:5120
	v_pk_mul_f32 v[74:75], v[72:73], v[60:61] op_sel:[0,0] op_sel_hi:[0,1]
	s_nop 0
	v_pk_fma_f32 v[72:73], v[72:73], v[60:61], v[74:75] op_sel:[1,1,0] op_sel_hi:[1,0,1] neg_lo:[1,0,0]
	ds_write_b64 v125, v[72:73] offset:5632
	v_pk_mul_f32 v[72:73], v[82:83], v[62:63] op_sel:[0,0] op_sel_hi:[0,1]
	s_nop 0
	v_pk_fma_f32 v[72:73], v[82:83], v[62:63], v[72:73] op_sel:[1,1,0] op_sel_hi:[1,0,1] neg_lo:[1,0,0]
	ds_write_b64 v182, v[72:73] offset:6144
	v_pk_mul_f32 v[72:73], v[88:89], v[64:65] op_sel:[0,0] op_sel_hi:[0,1]
	s_nop 0
	v_pk_fma_f32 v[72:73], v[88:89], v[64:65], v[72:73] op_sel:[1,1,0] op_sel_hi:[1,0,1] neg_lo:[1,0,0]
	ds_write_b64 v183, v[72:73] offset:6656
	v_pk_mul_f32 v[72:73], v[78:79], v[66:67] op_sel:[0,0] op_sel_hi:[0,1]
	s_nop 0
	v_pk_fma_f32 v[72:73], v[78:79], v[66:67], v[72:73] op_sel:[1,1,0] op_sel_hi:[1,0,1] neg_lo:[1,0,0]
	ds_write_b64 v216, v[72:73] offset:7168
	v_pk_mul_f32 v[72:73], v[70:71], v[68:69] op_sel:[0,0] op_sel_hi:[0,1]
	s_nop 0
	v_pk_fma_f32 v[70:71], v[70:71], v[68:69], v[72:73] op_sel:[1,1,0] op_sel_hi:[1,0,1] neg_lo:[1,0,0]
	ds_write_b64 v21, v[70:71] offset:7680
	s_cbranch_vccz .LBB0_1025

; #define LAS __attribute__((address_space(3)))
; template <bool INV, bool HALFIN = false> __device__ __forceinline__ void dft16(cf (&x)[16]) {
; #pragma unroll
;     for (int m2 = 0; m2 < 4; ++m2) {
;         if (HALFIN) { const cf a0 = x[m2], a1 = x[4 + m2]; x[m2] = a0 + a1; x[8 + m2] = a0 - a1; x[4 + m2] = add_mib(a0, a1); x[12 + m2] = add_pib(a0, a1); }
;         else dft4<INV>(x[m2], x[4 + m2], x[8 + m2], x[12 + m2]);
;     }
;     constexpr float C1 = 0.9238795325112867f, S1 = 0.3826834323650898f, C2 = 0.7071067811865476f;
;     x[4 * 1 + 1] = tw16<INV>(x[5], C1, S1);  x[4 * 1 + 2] = tw16<INV>(x[6], C2, C2);   x[4 * 1 + 3] = tw16<INV>(x[7], S1, C1);
;     x[4 * 2 + 1] = tw16<INV>(x[9], C2, C2);  x[4 * 2 + 2] = tw16<INV>(x[10], 0.f, 1.f); x[4 * 2 + 3] = tw16<INV>(x[11], -C2, C2);
;     x[4 * 3 + 1] = tw16<INV>(x[13], S1, C1); x[4 * 3 + 2] = tw16<INV>(x[14], -C2, C2); x[4 * 3 + 3] = tw16<INV>(x[15], -C1, -S1);
; #pragma unroll
;     for (int q1 = 0; q1 < 4; ++q1) dft4<INV>(x[4 * q1], x[4 * q1 + 1], x[4 * q1 + 2], x[4 * q1 + 3]);
; }
; template <int LST> __device__ __forceinline__ int pass_pos(int base, int phb, int m) {
;     if (LST == 10) return phb + (m << 10);
;     if (LST == 6) return (base ^ (m << 2)) + (m << 6);
;     return PH(base + (m << LST));
; }
; template <bool INV, int LST, bool HALF = false> __device__ __forceinline__ void fft_pass16(LAS cf* z, const LAS cf* Thi, const LAS cf* Tlo, int tid) {
;     constexpr int st = 1 << LST;
;     cf w[16];
; #pragma unroll 1
;     for (int it = 0; it < 2; ++it) {
;         const int g = tid + 512 * it; const int j0 = g & (st - 1); const int base = ((g >> LST) << (LST + 4)) + j0; const int phb = PH(base);
;         if (LST == 10 || it == 0) {
;             const int e1 = j0 << (10 - LST);
;             w[1] = cmul(Thi[e1 >> 7], Tlo[e1 & 127]);
;             w[2] = cmul(w[1], w[1]); w[3] = cmul(w[2], w[1]); w[4] = cmul(w[2], w[2]); w[5] = cmul(w[4], w[1]); w[6] = cmul(w[3], w[3]); w[7] = cmul(w[4], w[3]); w[8] = cmul(w[4], w[4]);
; #pragma unroll
;             for (int q = 9; q < 16; ++q) w[q] = cmul(w[8], w[q - 8]);
;         }
;         cf x[16];
;         if (!INV) {
; #pragma unroll
;             for (int m = 0; m < 16; ++m) { if (HALF && m >= 8) x[m] = (cf){0.f, 0.f}; else x[m] = z[pass_pos<LST>(base, phb, m)]; }
;             dft16<false, HALF>(x);
; #pragma unroll
.LBB0_1026:
	v_add_u32_e32 v29, s21, v169
	v_and_or_b32 v29, v29, s71, v172
	v_lshl_add_u32 v37, v29, 3, v174
	v_xor_b32_e32 v110, 0x80, v37
	v_xor_b32_e32 v114, 0x100, v37
	v_xor_b32_e32 v111, 0xa0, v37
	v_xor_b32_e32 v115, 0x120, v37
	v_xor_b32_e32 v183, 0x180, v37
	v_xor_b32_e32 v108, 0x40, v37
	v_xor_b32_e32 v112, 0xc0, v37
	v_xor_b32_e32 v125, 0x140, v37
	v_xor_b32_e32 v216, 0x1a0, v37
	v_xor_b32_e32 v41, 0x20, v37
	v_xor_b32_e32 v109, 0x60, v37
	ds_read_b64 v[70:71], v37
	ds_read_b64 v[72:73], v41
	ds_read_b64 v[74:75], v108
	ds_read_b64 v[76:77], v109
	v_xor_b32_e32 v113, 0xe0, v37
	ds_read_b64 v[78:79], v110
	ds_read_b64 v[80:81], v111
	ds_read_b64 v[82:83], v112
	ds_read_b64 v[84:85], v113
	v_xor_b32_e32 v182, 0x160, v37
	ds_read_b64 v[86:87], v114
	ds_read_b64 v[88:89], v115
	ds_read_b64 v[90:91], v125
	ds_read_b64 v[92:93], v182
	v_xor_b32_e32 v217, 0x1c0, v37
	v_xor_b32_e32 v29, 0x1e0, v37
	ds_read_b64 v[94:95], v183
	ds_read_b64 v[96:97], v216
	ds_read_b64 v[98:99], v217
	ds_read_b64 v[100:101], v29
	s_waitcnt lgkmcnt(7)
	v_pk_add_f32 v[102:103], v[70:71], v[86:87]
	v_pk_add_f32 v[70:71], v[70:71], v[86:87] neg_lo:[0,1] neg_hi:[0,1]
	s_waitcnt lgkmcnt(3)
	v_pk_add_f32 v[86:87], v[78:79], v[94:95]
	v_pk_add_f32 v[78:79], v[78:79], v[94:95] neg_lo:[0,1] neg_hi:[0,1]
	v_pk_add_f32 v[94:95], v[102:103], v[86:87]
	v_pk_add_f32 v[86:87], v[102:103], v[86:87] neg_lo:[0,1] neg_hi:[0,1]
	v_pk_add_f32 v[102:103], v[70:71], v[78:79] op_sel:[0,1] op_sel_hi:[1,0] neg_hi:[0,1]
	v_pk_add_f32 v[70:71], v[70:71], v[78:79] op_sel:[0,1] op_sel_hi:[1,0] neg_lo:[0,1]
	v_pk_add_f32 v[78:79], v[72:73], v[88:89]
	v_pk_add_f32 v[72:73], v[72:73], v[88:89] neg_lo:[0,1] neg_hi:[0,1]
	s_waitcnt lgkmcnt(2)
	v_pk_add_f32 v[88:89], v[80:81], v[96:97]
	v_pk_add_f32 v[80:81], v[80:81], v[96:97] neg_lo:[0,1] neg_hi:[0,1]
	v_pk_add_f32 v[96:97], v[78:79], v[88:89]
	v_pk_add_f32 v[78:79], v[78:79], v[88:89] neg_lo:[0,1] neg_hi:[0,1]
	v_pk_add_f32 v[88:89], v[72:73], v[80:81] op_sel:[0,1] op_sel_hi:[1,0] neg_hi:[0,1]
	v_pk_add_f32 v[72:73], v[72:73], v[80:81] op_sel:[0,1] op_sel_hi:[1,0] neg_lo:[0,1]
	v_pk_add_f32 v[80:81], v[74:75], v[90:91]
	v_pk_add_f32 v[74:75], v[74:75], v[90:91] neg_lo:[0,1] neg_hi:[0,1]
	s_waitcnt lgkmcnt(1)
	v_pk_add_f32 v[90:91], v[82:83], v[98:99]
	v_pk_add_f32 v[82:83], v[82:83], v[98:99] neg_lo:[0,1] neg_hi:[0,1]
	v_pk_add_f32 v[98:99], v[80:81], v[90:91]
	v_pk_add_f32 v[80:81], v[80:81], v[90:91] neg_lo:[0,1] neg_hi:[0,1]
	v_pk_add_f32 v[90:91], v[74:75], v[82:83] op_sel:[0,1] op_sel_hi:[1,0] neg_hi:[0,1]
	v_pk_add_f32 v[74:75], v[74:75], v[82:83] op_sel:[0,1] op_sel_hi:[1,0] neg_lo:[0,1]
	v_pk_add_f32 v[82:83], v[76:77], v[92:93]
	v_pk_add_f32 v[76:77], v[76:77], v[92:93] neg_lo:[0,1] neg_hi:[0,1]
	s_waitcnt lgkmcnt(0)
	v_pk_add_f32 v[92:93], v[84:85], v[100:101]
	v_pk_add_f32 v[84:85], v[84:85], v[100:101] neg_lo:[0,1] neg_hi:[0,1]
	v_pk_add_f32 v[100:101], v[82:83], v[92:93]
	v_pk_add_f32 v[82:83], v[82:83], v[92:93] neg_lo:[0,1] neg_hi:[0,1]
	v_pk_add_f32 v[92:93], v[76:77], v[84:85] op_sel:[0,1] op_sel_hi:[1,0] neg_hi:[0,1]
	v_pk_add_f32 v[76:77], v[76:77], v[84:85] op_sel:[0,1] op_sel_hi:[1,0] neg_lo:[0,1]
	v_pk_mul_f32 v[84:85], v[88:89], s[22:23] op_sel_hi:[1,0]
	s_mov_b32 s48, s37
	v_pk_fma_f32 v[104:105], v[88:89], s[20:21], v[84:85] op_sel:[0,0,1] op_sel_hi:[1,0,0] neg_hi:[0,0,1]
	s_mov_b32 s49, s22
	v_pk_mul_f32 v[84:85], v[90:91], s[24:25] op_sel_hi:[1,0]
	s_andn2_b64 vcc, exec, s[46:47]
	v_pk_fma_f32 v[88:89], v[90:91], s[24:25], v[84:85] op_sel:[0,0,1] op_sel_hi:[1,0,0] neg_hi:[0,0,1]
	v_pk_mul_f32 v[90:91], v[92:93], s[20:21] op_sel_hi:[1,0]
	s_nop 0
	v_pk_fma_f32 v[106:107], v[92:93], s[22:23], v[90:91] op_sel:[0,0,1] op_sel_hi:[1,0,0] neg_hi:[0,0,1]
	v_pk_add_f32 v[84:85], v[102:103], v[88:89]
	v_pk_mul_f32 v[90:91], v[78:79], s[24:25] op_sel_hi:[1,0]
	v_pk_add_f32 v[88:89], v[102:103], v[88:89] neg_lo:[0,1] neg_hi:[0,1]
	v_pk_fma_f32 v[92:93], v[78:79], s[24:25], v[90:91] op_sel:[0,0,1] op_sel_hi:[1,0,0] neg_hi:[0,0,1]
	v_pk_add_f32 v[102:103], v[104:105], v[106:107] neg_lo:[0,1] neg_hi:[0,1]
	v_pk_fma_f32 v[78:79], v[80:81], 0, v[80:81] op_sel:[0,0,1] op_sel_hi:[1,0,0]
	v_pk_fma_f32 v[80:81], v[80:81], 0, v[80:81] op_sel:[0,0,1] op_sel_hi:[1,0,0] neg_lo:[0,0,1] neg_hi:[0,0,1]
	s_mov_b64 s[46:47], 0
	v_mul_f32_e32 v80, 0x3f3504f3, v82
	v_mov_b32_e32 v79, v81
	v_pk_fma_f32 v[80:81], v[82:83], s[24:25], v[80:81] op_sel:[1,0,0] op_sel_hi:[1,1,0] neg_lo:[0,0,1] neg_hi:[0,0,1]
	v_pk_mul_f32 v[82:83], v[72:73], s[20:21] op_sel_hi:[1,0]
	s_movk_i32 s21, 0x2000
	v_pk_fma_f32 v[90:91], v[72:73], s[22:23], v[82:83] op_sel:[0,0,1] op_sel_hi:[1,0,0]
	v_pk_fma_f32 v[72:73], v[72:73], s[22:23], v[82:83] op_sel:[0,0,1] op_sel_hi:[1,0,0] neg_lo:[0,0,1] neg_hi:[0,0,1]
	v_pk_add_f32 v[82:83], v[94:95], v[98:99] neg_lo:[0,1] neg_hi:[0,1]
	v_mul_f32_e32 v72, 0x3f3504f3, v74
	v_mov_b32_e32 v91, v73
	v_pk_fma_f32 v[72:73], v[74:75], s[24:25], v[72:73] op_sel:[1,0,0] op_sel_hi:[1,1,0] neg_lo:[0,0,1] neg_hi:[0,0,1]
	v_pk_mul_f32 v[74:75], v[76:77], s[36:37] op_sel:[1,0]
	s_nop 0
; #define LAS __attribute__((address_space(3)))
; template <bool INV, bool HALFIN = false> __device__ __forceinline__ void dft16(cf (&x)[16]) {
; #pragma unroll
;     for (int m2 = 0; m2 < 4; ++m2) {
;         if (HALFIN) { const cf a0 = x[m2], a1 = x[4 + m2]; x[m2] = a0 + a1; x[8 + m2] = a0 - a1; x[4 + m2] = add_mib(a0, a1); x[12 + m2] = add_pib(a0, a1); }
;         else dft4<INV>(x[m2], x[4 + m2], x[8 + m2], x[12 + m2]);
;     }
;     constexpr float C1 = 0.9238795325112867f, S1 = 0.3826834323650898f, C2 = 0.7071067811865476f;
;     x[4 * 1 + 1] = tw16<INV>(x[5], C1, S1);  x[4 * 1 + 2] = tw16<INV>(x[6], C2, C2);   x[4 * 1 + 3] = tw16<INV>(x[7], S1, C1);
;     x[4 * 2 + 1] = tw16<INV>(x[9], C2, C2);  x[4 * 2 + 2] = tw16<INV>(x[10], 0.f, 1.f); x[4 * 2 + 3] = tw16<INV>(x[11], -C2, C2);
;     x[4 * 3 + 1] = tw16<INV>(x[13], S1, C1); x[4 * 3 + 2] = tw16<INV>(x[14], -C2, C2); x[4 * 3 + 3] = tw16<INV>(x[15], -C1, -S1);
; #pragma unroll
;     for (int q1 = 0; q1 < 4; ++q1) dft4<INV>(x[4 * q1], x[4 * q1 + 1], x[4 * q1 + 2], x[4 * q1 + 3]);
; }
; template <int LST> __device__ __forceinline__ int pass_pos(int base, int phb, int m) {
;     if (LST == 10) return phb + (m << 10);
;     if (LST == 6) return (base ^ (m << 2)) + (m << 6);
;     return PH(base + (m << LST));
; }
; template <bool INV, int LST, bool HALF = false> __device__ __forceinline__ void fft_pass16(LAS cf* z, const LAS cf* Thi, const LAS cf* Tlo, int tid) {
;     constexpr int st = 1 << LST;
;     cf w[16];
; #pragma unroll 1
;     for (int it = 0; it < 2; ++it) {
;         const int g = tid + 512 * it; const int j0 = g & (st - 1); const int base = ((g >> LST) << (LST + 4)) + j0; const int phb = PH(base);
;         if (LST == 10 || it == 0) {
;             const int e1 = j0 << (10 - LST);
;             w[1] = cmul(Thi[e1 >> 7], Tlo[e1 & 127]);
;             w[2] = cmul(w[1], w[1]); w[3] = cmul(w[2], w[1]); w[4] = cmul(w[2], w[2]); w[5] = cmul(w[4], w[1]); w[6] = cmul(w[3], w[3]); w[7] = cmul(w[4], w[3]); w[8] = cmul(w[4], w[4]);
; #pragma unroll
;             for (int q = 9; q < 16; ++q) w[q] = cmul(w[8], w[q - 8]);
;         }
;         cf x[16];
;         if (!INV) {
; #pragma unroll
;             for (int m = 0; m < 16; ++m) { if (HALF && m >= 8) x[m] = (cf){0.f, 0.f}; else x[m] = z[pass_pos<LST>(base, phb, m)]; }
;             dft16<false, HALF>(x);
; #pragma unroll
	v_pk_fma_f32 v[74:75], v[76:77], s[48:49], v[74:75] op_sel_hi:[0,1,1]
	v_pk_add_f32 v[76:77], v[94:95], v[98:99]
	v_pk_add_f32 v[94:95], v[96:97], v[100:101]
	v_pk_add_f32 v[96:97], v[96:97], v[100:101] neg_lo:[0,1] neg_hi:[0,1]
	v_pk_add_f32 v[98:99], v[76:77], v[94:95] neg_lo:[0,1] neg_hi:[0,1]
	v_pk_add_f32 v[100:101], v[82:83], v[96:97] op_sel:[0,1] op_sel_hi:[1,0] neg_hi:[0,1]
	v_pk_add_f32 v[82:83], v[82:83], v[96:97] op_sel:[0,1] op_sel_hi:[1,0] neg_lo:[0,1]
	v_pk_add_f32 v[96:97], v[104:105], v[106:107]
	s_nop 0
	v_pk_add_f32 v[104:105], v[84:85], v[96:97]
	v_pk_add_f32 v[84:85], v[84:85], v[96:97] neg_lo:[0,1] neg_hi:[0,1]
	v_pk_add_f32 v[96:97], v[88:89], v[102:103] op_sel:[0,1] op_sel_hi:[1,0] neg_hi:[0,1]
	v_pk_add_f32 v[88:89], v[88:89], v[102:103] op_sel:[0,1] op_sel_hi:[1,0] neg_lo:[0,1]
	v_pk_add_f32 v[102:103], v[86:87], v[78:79]
	v_pk_add_f32 v[78:79], v[86:87], v[78:79] neg_lo:[0,1] neg_hi:[0,1]
	v_pk_add_f32 v[86:87], v[92:93], v[80:81]
	v_pk_add_f32 v[80:81], v[92:93], v[80:81] neg_lo:[0,1] neg_hi:[0,1]
	v_pk_add_f32 v[92:93], v[102:103], v[86:87]
	v_pk_add_f32 v[86:87], v[102:103], v[86:87] neg_lo:[0,1] neg_hi:[0,1]
	v_pk_add_f32 v[102:103], v[78:79], v[80:81] op_sel:[0,1] op_sel_hi:[1,0] neg_hi:[0,1]
	v_pk_add_f32 v[78:79], v[78:79], v[80:81] op_sel:[0,1] op_sel_hi:[1,0] neg_lo:[0,1]
	v_pk_add_f32 v[80:81], v[70:71], v[72:73]
	v_pk_add_f32 v[70:71], v[70:71], v[72:73] neg_lo:[0,1] neg_hi:[0,1]
	v_pk_add_f32 v[72:73], v[90:91], v[74:75]
	v_pk_add_f32 v[74:75], v[90:91], v[74:75] neg_lo:[0,1] neg_hi:[0,1]
	v_pk_add_f32 v[90:91], v[80:81], v[72:73]
	v_pk_add_f32 v[72:73], v[80:81], v[72:73] neg_lo:[0,1] neg_hi:[0,1]
	v_pk_add_f32 v[80:81], v[70:71], v[74:75] op_sel:[0,1] op_sel_hi:[1,0] neg_hi:[0,1]
	v_pk_add_f32 v[70:71], v[70:71], v[74:75] op_sel:[0,1] op_sel_hi:[1,0] neg_lo:[0,1]
	v_pk_add_f32 v[74:75], v[76:77], v[94:95]
	ds_write_b64 v37, v[74:75]
	v_pk_mul_f32 v[74:75], v[104:105], v[22:23] op_sel:[0,0] op_sel_hi:[0,1]
	s_nop 0
	v_pk_fma_f32 v[74:75], v[104:105], v[22:23], v[74:75] op_sel:[1,1,0] op_sel_hi:[1,0,1] neg_lo:[1,0,0]
	ds_write_b64 v41, v[74:75]
	v_pk_mul_f32 v[74:75], v[92:93], v[30:31] op_sel:[0,0] op_sel_hi:[0,1]
	s_nop 0
	v_pk_fma_f32 v[74:75], v[92:93], v[30:31], v[74:75] op_sel:[1,1,0] op_sel_hi:[1,0,1] neg_lo:[1,0,0]
	ds_write_b64 v108, v[74:75]
	v_pk_mul_f32 v[74:75], v[90:91], v[38:39] op_sel:[0,0] op_sel_hi:[0,1]
	s_nop 0
	v_pk_fma_f32 v[74:75], v[90:91], v[38:39], v[74:75] op_sel:[1,1,0] op_sel_hi:[1,0,1] neg_lo:[1,0,0]
	ds_write_b64 v109, v[74:75]
	v_pk_mul_f32 v[74:75], v[100:101], v[42:43] op_sel:[0,0] op_sel_hi:[0,1]
	s_nop 0
	v_pk_fma_f32 v[74:75], v[100:101], v[42:43], v[74:75] op_sel:[1,1,0] op_sel_hi:[1,0,1] neg_lo:[1,0,0]
	ds_write_b64 v110, v[74:75]
	v_pk_mul_f32 v[74:75], v[96:97], v[48:49] op_sel:[0,0] op_sel_hi:[0,1]
	s_nop 0
	v_pk_fma_f32 v[74:75], v[96:97], v[48:49], v[74:75] op_sel:[1,1,0] op_sel_hi:[1,0,1] neg_lo:[1,0,0]
	ds_write_b64 v111, v[74:75]
	v_pk_mul_f32 v[74:75], v[102:103], v[50:51] op_sel:[0,0] op_sel_hi:[0,1]
	s_nop 0
	v_pk_fma_f32 v[74:75], v[102:103], v[50:51], v[74:75] op_sel:[1,1,0] op_sel_hi:[1,0,1] neg_lo:[1,0,0]
	ds_write_b64 v112, v[74:75]
	v_pk_mul_f32 v[74:75], v[80:81], v[52:53] op_sel:[0,0] op_sel_hi:[0,1]
	s_nop 0
	v_pk_fma_f32 v[74:75], v[80:81], v[52:53], v[74:75] op_sel:[1,1,0] op_sel_hi:[1,0,1] neg_lo:[1,0,0]
	ds_write_b64 v113, v[74:75]
	v_pk_mul_f32 v[74:75], v[98:99], v[54:55] op_sel:[0,0] op_sel_hi:[0,1]
	s_nop 0
	v_pk_fma_f32 v[74:75], v[98:99], v[54:55], v[74:75] op_sel:[1,1,0] op_sel_hi:[1,0,1] neg_lo:[1,0,0]
	ds_write_b64 v114, v[74:75]
	v_pk_mul_f32 v[74:75], v[84:85], v[56:57] op_sel:[0,0] op_sel_hi:[0,1]
	s_nop 0
	v_pk_fma_f32 v[74:75], v[84:85], v[56:57], v[74:75] op_sel:[1,1,0] op_sel_hi:[1,0,1] neg_lo:[1,0,0]
	ds_write_b64 v115, v[74:75]
	v_pk_mul_f32 v[74:75], v[86:87], v[58:59] op_sel:[0,0] op_sel_hi:[0,1]
	s_nop 0
	v_pk_fma_f32 v[74:75], v[86:87], v[58:59], v[74:75] op_sel:[1,1,0] op_sel_hi:[1,0,1] neg_lo:[1,0,0]
	ds_write_b64 v125, v[74:75]
	v_pk_mul_f32 v[74:75], v[72:73], v[60:61] op_sel:[0,0] op_sel_hi:[0,1]
	s_nop 0
	v_pk_fma_f32 v[72:73], v[72:73], v[60:61], v[74:75] op_sel:[1,1,0] op_sel_hi:[1,0,1] neg_lo:[1,0,0]
	ds_write_b64 v182, v[72:73]
	v_pk_mul_f32 v[72:73], v[82:83], v[62:63] op_sel:[0,0] op_sel_hi:[0,1]
	s_nop 0
	v_pk_fma_f32 v[72:73], v[82:83], v[62:63], v[72:73] op_sel:[1,1,0] op_sel_hi:[1,0,1] neg_lo:[1,0,0]
	ds_write_b64 v183, v[72:73]
	v_pk_mul_f32 v[72:73], v[88:89], v[64:65] op_sel:[0,0] op_sel_hi:[0,1]
	s_nop 0
	v_pk_fma_f32 v[72:73], v[88:89], v[64:65], v[72:73] op_sel:[1,1,0] op_sel_hi:[1,0,1] neg_lo:[1,0,0]
	ds_write_b64 v216, v[72:73]
	v_pk_mul_f32 v[72:73], v[78:79], v[66:67] op_sel:[0,0] op_sel_hi:[0,1]
	s_nop 0
	v_pk_fma_f32 v[72:73], v[78:79], v[66:67], v[72:73] op_sel:[1,1,0] op_sel_hi:[1,0,1] neg_lo:[1,0,0]
	ds_write_b64 v217, v[72:73]
	v_pk_mul_f32 v[72:73], v[70:71], v[68:69] op_sel:[0,0] op_sel_hi:[0,1]
	s_nop 0
	v_pk_fma_f32 v[70:71], v[70:71], v[68:69], v[72:73] op_sel:[1,1,0] op_sel_hi:[1,0,1] neg_lo:[1,0,0]
	ds_write_b64 v29, v[70:71]
	s_cbranch_vccz .LBB0_1029

; __device__ __forceinline__ cf cconj(cf a) { return (cf){a.x, -a.y}; }
; __device__ __forceinline__ void hyena_phase(LAS unsigned char* L, const Args& a, int vcu, int G) {
;     ...
;         f32x4 sd[16];
;         {
;             const f32x4* sdp = SD + (size_t)pair * 8192;
; #pragma unroll
;             for (int i = 0; i < 16; ++i) sd[i] = sdp[2 * (tid + 512 * (i >> 1)) + (i & 1)];
;         }
;     ...
;             if (tid == 0) { const f32x4 s8 = SD8[pair]; const cf S = {s8[0], s8[1]}, Dd = {s8[2], s8[3]}; const cf zk = z[PH(2)]; z[PH(2)] = cmul(zk, S) + cmul(cconj(zk), Dd); }
.LBB0_1029:
	s_ashr_i32 s45, s44, 31
	s_lshl_b64 s[46:47], s[44:45], 17
	s_add_u32 s46, s62, s46
	s_addc_u32 s47, s63, s47
	s_waitcnt lgkmcnt(0)
	s_barrier
	s_lshl_b64 s[74:75], s[44:45], 4
	s_add_u32 s74, s64, s74
	s_addc_u32 s75, s65, s75
	global_load_dwordx4 v[236:239], v117, s[74:75]
	global_load_dwordx4 v[104:107], v218, s[46:47] offset:16
	global_load_dwordx4 v[108:111], v218, s[46:47]
	global_load_dwordx4 v[96:99], v219, s[46:47] offset:16
	global_load_dwordx4 v[100:103], v219, s[46:47]
	global_load_dwordx4 v[88:91], v220, s[46:47] offset:16
	global_load_dwordx4 v[92:95], v220, s[46:47]
	global_load_dwordx4 v[80:83], v221, s[46:47] offset:16
	global_load_dwordx4 v[84:87], v221, s[46:47]
	global_load_dwordx4 v[72:75], v222, s[46:47] offset:16
	global_load_dwordx4 v[76:79], v222, s[46:47]
	global_load_dwordx4 v[64:67], v223, s[46:47] offset:16
	global_load_dwordx4 v[68:71], v223, s[46:47]
	global_load_dwordx4 v[56:59], v224, s[46:47] offset:16
	global_load_dwordx4 v[60:63], v224, s[46:47]
	global_load_dwordx4 v[48:51], v225, s[46:47] offset:16
	global_load_dwordx4 v[52:55], v225, s[46:47]
	s_mov_b32 s21, 0

; #define LAS __attribute__((address_space(3)))
; __device__ __forceinline__ cf cconj(cf a) { return (cf){a.x, -a.y}; }
; __device__ __forceinline__ int p_of_k(int k) { return ((k & 15) << 10) | (((k >> 4) & 15) << 6) | (((k >> 8) & 15) << 2) | (k >> 12); }
; __device__ __forceinline__ void hyena_phase(LAS unsigned char* L, const Args& a, int vcu, int G) {
;     ...
; #pragma unroll
;             for (int i = 0; i < 8; ++i) {
;                 const int g = tid + 512 * i;
;                 const int kg = (g >> 8) | (((g >> 4) & 15) << 4) | ((g & 15) << 8);
;                 const int pp0 = p_of_k((NFFT - kg) & (NFFT - 1)), pp1 = p_of_k(12288 - kg);
;                 const int p0 = PH(4 * g);
;                 const f32x4 zz = *(LAS f32x4*)(z + p0);
;                 const cf zk0 = {zz[0], zz[1]}, zk1 = {zz[2], zz[3]};
;                 const cf zn0 = z[PH(pp0)], zn1 = z[PH(pp1)];
;                 const f32x4 s0 = sd[2 * i], s1 = sd[2 * i + 1];
;                 const cf S0 = {s0[0], s0[1]}, D0 = {s0[2], s0[3]}, S1 = {s1[0], s1[1]}, D1 = {s1[2], s1[3]};
;                 const cf w0 = cmul(zk0, S0) + cmul(cconj(zn0), D0), w1 = cmul(zk1, S1) + cmul(cconj(zn1), D1);
;                 *(LAS f32x4*)(z + p0) = (f32x4){w0.x, w0.y, w1.x, w1.y};
;                 if (kg != 0) z[PH(pp0)] = cmulc(zn0, S0) + cconj(cmul(zk0, D0));
;                 z[PH(pp1)] = cmulc(zn1, S1) + cconj(cmul(zk1, D1));
;             }
.LBB0_1033:
	s_or_b64 exec, exec, s[46:47]
	v_pk_mul_f32 v[30:31], v[22:23], v[104:105] op_sel:[0,0] op_sel_hi:[0,1] neg_hi:[0,1]
	s_nop 0
	v_pk_fma_f32 v[22:23], v[22:23], v[104:105], v[30:31] op_sel:[1,1,0] op_sel_hi:[1,0,1]
	v_pk_mul_f32 v[30:31], v[114:115], v[106:107] op_sel:[0,0] op_sel_hi:[0,1]
	s_nop 0
	v_pk_fma_f32 v[30:31], v[114:115], v[106:107], v[30:31] op_sel:[1,1,0] op_sel_hi:[1,0,1] neg_lo:[1,0,0]
	s_nop 0
	v_pk_add_f32 v[38:39], v[30:31], 0 neg_lo:[1,1] neg_hi:[1,1]
	s_nop 0
	v_mov_b32_e32 v31, v39
	v_pk_add_f32 v[22:23], v[22:23], v[30:31]
	ds_write_b64 v188, v[22:23]
	ds_read_b128 v[104:107], v189
	ds_read_b64 v[22:23], v190
	ds_read_b64 v[30:31], v191
	s_waitcnt vmcnt(12) lgkmcnt(2)
	v_pk_mul_f32 v[38:39], v[104:105], v[100:101] op_sel:[0,0] op_sel_hi:[0,1]
	s_waitcnt lgkmcnt(1)
	v_pk_add_f32 v[42:43], v[22:23], 0 neg_lo:[1,1] neg_hi:[1,1]
	v_pk_fma_f32 v[38:39], v[104:105], v[100:101], v[38:39] op_sel:[1,1,0] op_sel_hi:[1,0,1] neg_lo:[1,0,0]
	s_nop 0
	v_mov_b32_e32 v42, v22
	v_pk_mul_f32 v[108:109], v[42:43], v[102:103] op_sel:[0,0] op_sel_hi:[0,1]
	s_nop 0
	v_pk_fma_f32 v[42:43], v[42:43], v[102:103], v[108:109] op_sel:[1,1,0] op_sel_hi:[1,0,1] neg_lo:[1,0,0]
	v_pk_mul_f32 v[108:109], v[106:107], v[96:97] op_sel:[0,0] op_sel_hi:[0,1]
	s_nop 0
	v_pk_fma_f32 v[110:111], v[106:107], v[96:97], v[108:109] op_sel:[1,1,0] op_sel_hi:[1,0,1] neg_lo:[1,0,0]
	s_waitcnt lgkmcnt(0)
	v_pk_add_f32 v[108:109], v[30:31], 0 neg_lo:[1,1] neg_hi:[1,1]
	s_nop 0
	v_mov_b32_e32 v108, v30
	v_pk_mul_f32 v[112:113], v[108:109], v[98:99] op_sel:[0,0] op_sel_hi:[0,1]
	s_nop 0
	v_pk_fma_f32 v[112:113], v[108:109], v[98:99], v[112:113] op_sel:[1,1,0] op_sel_hi:[1,0,1] neg_lo:[1,0,0]
	v_pk_add_f32 v[108:109], v[38:39], v[42:43]
	v_pk_mul_f32 v[38:39], v[22:23], v[100:101] op_sel:[0,0] op_sel_hi:[0,1] neg_hi:[0,1]
	v_pk_add_f32 v[110:111], v[110:111], v[112:113]
	v_pk_fma_f32 v[22:23], v[22:23], v[100:101], v[38:39] op_sel:[1,1,0] op_sel_hi:[1,0,1]
	v_pk_mul_f32 v[38:39], v[104:105], v[102:103] op_sel:[0,0] op_sel_hi:[0,1]
	ds_write_b128 v189, v[108:111]
	v_pk_fma_f32 v[38:39], v[104:105], v[102:103], v[38:39] op_sel:[1,1,0] op_sel_hi:[1,0,1] neg_lo:[1,0,0]
	s_nop 0
	v_pk_add_f32 v[42:43], v[38:39], 0 neg_lo:[1,1] neg_hi:[1,1]
	s_nop 0
	v_mov_b32_e32 v39, v43
	v_pk_add_f32 v[22:23], v[22:23], v[38:39]
	ds_write_b64 v190, v[22:23]
	v_pk_mul_f32 v[22:23], v[30:31], v[96:97] op_sel:[0,0] op_sel_hi:[0,1] neg_hi:[0,1]
	s_nop 0
	v_pk_fma_f32 v[22:23], v[30:31], v[96:97], v[22:23] op_sel:[1,1,0] op_sel_hi:[1,0,1]
	v_pk_mul_f32 v[30:31], v[106:107], v[98:99] op_sel:[0,0] op_sel_hi:[0,1]
	s_nop 0
	v_pk_fma_f32 v[30:31], v[106:107], v[98:99], v[30:31] op_sel:[1,1,0] op_sel_hi:[1,0,1] neg_lo:[1,0,0]
	s_nop 0
	v_pk_add_f32 v[38:39], v[30:31], 0 neg_lo:[1,1] neg_hi:[1,1]
	s_nop 0
	v_mov_b32_e32 v31, v39
	v_pk_add_f32 v[22:23], v[22:23], v[30:31]
	ds_write_b64 v191, v[22:23]
	ds_read_b128 v[96:99], v192
	ds_read_b64 v[22:23], v193
	ds_read_b64 v[30:31], v194
	s_waitcnt vmcnt(10) lgkmcnt(2)
	v_pk_mul_f32 v[38:39], v[96:97], v[92:93] op_sel:[0,0] op_sel_hi:[0,1]
	s_waitcnt lgkmcnt(1)
	v_pk_add_f32 v[42:43], v[22:23], 0 neg_lo:[1,1] neg_hi:[1,1]
	v_pk_fma_f32 v[38:39], v[96:97], v[92:93], v[38:39] op_sel:[1,1,0] op_sel_hi:[1,0,1] neg_lo:[1,0,0]
	s_nop 0
	v_mov_b32_e32 v42, v22
	v_pk_mul_f32 v[100:101], v[42:43], v[94:95] op_sel:[0,0] op_sel_hi:[0,1]
	s_nop 0
	v_pk_fma_f32 v[42:43], v[42:43], v[94:95], v[100:101] op_sel:[1,1,0] op_sel_hi:[1,0,1] neg_lo:[1,0,0]
	v_pk_mul_f32 v[100:101], v[98:99], v[88:89] op_sel:[0,0] op_sel_hi:[0,1]
	s_nop 0
	v_pk_fma_f32 v[102:103], v[98:99], v[88:89], v[100:101] op_sel:[1,1,0] op_sel_hi:[1,0,1] neg_lo:[1,0,0]
	s_waitcnt lgkmcnt(0)
	v_pk_add_f32 v[100:101], v[30:31], 0 neg_lo:[1,1] neg_hi:[1,1]
	s_nop 0
	v_mov_b32_e32 v100, v30
	v_pk_mul_f32 v[104:105], v[100:101], v[90:91] op_sel:[0,0] op_sel_hi:[0,1]
	s_nop 0
	v_pk_fma_f32 v[104:105], v[100:101], v[90:91], v[104:105] op_sel:[1,1,0] op_sel_hi:[1,0,1] neg_lo:[1,0,0]
	v_pk_add_f32 v[100:101], v[38:39], v[42:43]
	v_pk_mul_f32 v[38:39], v[22:23], v[92:93] op_sel:[0,0] op_sel_hi:[0,1] neg_hi:[0,1]
	v_pk_add_f32 v[102:103], v[102:103], v[104:105]
	v_pk_fma_f32 v[22:23], v[22:23], v[92:93], v[38:39] op_sel:[1,1,0] op_sel_hi:[1,0,1]
	v_pk_mul_f32 v[38:39], v[96:97], v[94:95] op_sel:[0,0] op_sel_hi:[0,1]
	ds_write_b128 v192, v[100:103]
	v_pk_fma_f32 v[38:39], v[96:97], v[94:95], v[38:39] op_sel:[1,1,0] op_sel_hi:[1,0,1] neg_lo:[1,0,0]
	s_nop 0
	v_pk_add_f32 v[42:43], v[38:39], 0 neg_lo:[1,1] neg_hi:[1,1]
	s_nop 0
	v_mov_b32_e32 v39, v43
	v_pk_add_f32 v[22:23], v[22:23], v[38:39]
	ds_write_b64 v193, v[22:23]
	v_pk_mul_f32 v[22:23], v[30:31], v[88:89] op_sel:[0,0] op_sel_hi:[0,1] neg_hi:[0,1]
	s_nop 0
	v_pk_fma_f32 v[22:23], v[30:31], v[88:89], v[22:23] op_sel:[1,1,0] op_sel_hi:[1,0,1]
	v_pk_mul_f32 v[30:31], v[98:99], v[90:91] op_sel:[0,0] op_sel_hi:[0,1]
	s_nop 0
	v_pk_fma_f32 v[30:31], v[98:99], v[90:91], v[30:31] op_sel:[1,1,0] op_sel_hi:[1,0,1] neg_lo:[1,0,0]
	s_nop 0
	v_pk_add_f32 v[38:39], v[30:31], 0 neg_lo:[1,1] neg_hi:[1,1]
	s_nop 0
	v_mov_b32_e32 v31, v39
	v_pk_add_f32 v[22:23], v[22:23], v[30:31]
	ds_write_b64 v194, v[22:23]
	ds_read_b128 v[88:91], v195
	ds_read_b64 v[22:23], v196
	ds_read_b64 v[30:31], v197
	s_waitcnt vmcnt(8) lgkmcnt(2)
	v_pk_mul_f32 v[38:39], v[88:89], v[84:85] op_sel:[0,0] op_sel_hi:[0,1]
	s_waitcnt lgkmcnt(1)
; #define LAS __attribute__((address_space(3)))
; __device__ __forceinline__ cf cconj(cf a) { return (cf){a.x, -a.y}; }
; __device__ __forceinline__ int p_of_k(int k) { return ((k & 15) << 10) | (((k >> 4) & 15) << 6) | (((k >> 8) & 15) << 2) | (k >> 12); }
; __device__ __forceinline__ void hyena_phase(LAS unsigned char* L, const Args& a, int vcu, int G) {
;     ...
; #pragma unroll
;             for (int i = 0; i < 8; ++i) {
;                 const int g = tid + 512 * i;
;                 const int kg = (g >> 8) | (((g >> 4) & 15) << 4) | ((g & 15) << 8);
;                 const int pp0 = p_of_k((NFFT - kg) & (NFFT - 1)), pp1 = p_of_k(12288 - kg);
;                 const int p0 = PH(4 * g);
;                 const f32x4 zz = *(LAS f32x4*)(z + p0);
;                 const cf zk0 = {zz[0], zz[1]}, zk1 = {zz[2], zz[3]};
;                 const cf zn0 = z[PH(pp0)], zn1 = z[PH(pp1)];
;                 const f32x4 s0 = sd[2 * i], s1 = sd[2 * i + 1];
;                 const cf S0 = {s0[0], s0[1]}, D0 = {s0[2], s0[3]}, S1 = {s1[0], s1[1]}, D1 = {s1[2], s1[3]};
;                 const cf w0 = cmul(zk0, S0) + cmul(cconj(zn0), D0), w1 = cmul(zk1, S1) + cmul(cconj(zn1), D1);
;                 *(LAS f32x4*)(z + p0) = (f32x4){w0.x, w0.y, w1.x, w1.y};
;                 if (kg != 0) z[PH(pp0)] = cmulc(zn0, S0) + cconj(cmul(zk0, D0));
;                 z[PH(pp1)] = cmulc(zn1, S1) + cconj(cmul(zk1, D1));
;             }
	v_pk_add_f32 v[42:43], v[22:23], 0 neg_lo:[1,1] neg_hi:[1,1]
	v_pk_fma_f32 v[38:39], v[88:89], v[84:85], v[38:39] op_sel:[1,1,0] op_sel_hi:[1,0,1] neg_lo:[1,0,0]
	s_nop 0
	v_mov_b32_e32 v42, v22
	v_pk_mul_f32 v[92:93], v[42:43], v[86:87] op_sel:[0,0] op_sel_hi:[0,1]
	s_nop 0
	v_pk_fma_f32 v[42:43], v[42:43], v[86:87], v[92:93] op_sel:[1,1,0] op_sel_hi:[1,0,1] neg_lo:[1,0,0]
	v_pk_mul_f32 v[92:93], v[90:91], v[80:81] op_sel:[0,0] op_sel_hi:[0,1]
	s_nop 0
	v_pk_fma_f32 v[94:95], v[90:91], v[80:81], v[92:93] op_sel:[1,1,0] op_sel_hi:[1,0,1] neg_lo:[1,0,0]
	s_waitcnt lgkmcnt(0)
	v_pk_add_f32 v[92:93], v[30:31], 0 neg_lo:[1,1] neg_hi:[1,1]
	s_nop 0
	v_mov_b32_e32 v92, v30
	v_pk_mul_f32 v[96:97], v[92:93], v[82:83] op_sel:[0,0] op_sel_hi:[0,1]
	s_nop 0
	v_pk_fma_f32 v[96:97], v[92:93], v[82:83], v[96:97] op_sel:[1,1,0] op_sel_hi:[1,0,1] neg_lo:[1,0,0]
	v_pk_add_f32 v[92:93], v[38:39], v[42:43]
	v_pk_mul_f32 v[38:39], v[22:23], v[84:85] op_sel:[0,0] op_sel_hi:[0,1] neg_hi:[0,1]
	v_pk_add_f32 v[94:95], v[94:95], v[96:97]
	v_pk_fma_f32 v[22:23], v[22:23], v[84:85], v[38:39] op_sel:[1,1,0] op_sel_hi:[1,0,1]
	v_pk_mul_f32 v[38:39], v[88:89], v[86:87] op_sel:[0,0] op_sel_hi:[0,1]
	ds_write_b128 v195, v[92:95]
	v_pk_fma_f32 v[38:39], v[88:89], v[86:87], v[38:39] op_sel:[1,1,0] op_sel_hi:[1,0,1] neg_lo:[1,0,0]
	s_nop 0
	v_pk_add_f32 v[42:43], v[38:39], 0 neg_lo:[1,1] neg_hi:[1,1]
	s_nop 0
	v_mov_b32_e32 v39, v43
	v_pk_add_f32 v[22:23], v[22:23], v[38:39]
	ds_write_b64 v196, v[22:23]
	v_pk_mul_f32 v[22:23], v[30:31], v[80:81] op_sel:[0,0] op_sel_hi:[0,1] neg_hi:[0,1]
	s_nop 0
	v_pk_fma_f32 v[22:23], v[30:31], v[80:81], v[22:23] op_sel:[1,1,0] op_sel_hi:[1,0,1]
	v_pk_mul_f32 v[30:31], v[90:91], v[82:83] op_sel:[0,0] op_sel_hi:[0,1]
	s_nop 0
	v_pk_fma_f32 v[30:31], v[90:91], v[82:83], v[30:31] op_sel:[1,1,0] op_sel_hi:[1,0,1] neg_lo:[1,0,0]
	s_nop 0
	v_pk_add_f32 v[38:39], v[30:31], 0 neg_lo:[1,1] neg_hi:[1,1]
	s_nop 0
	v_mov_b32_e32 v31, v39
	v_pk_add_f32 v[22:23], v[22:23], v[30:31]
	ds_write_b64 v197, v[22:23]
	ds_read_b128 v[80:83], v198
	ds_read_b64 v[22:23], v199
	ds_read_b64 v[30:31], v200
	s_waitcnt vmcnt(6) lgkmcnt(2)
	v_pk_mul_f32 v[38:39], v[80:81], v[76:77] op_sel:[0,0] op_sel_hi:[0,1]
	s_waitcnt lgkmcnt(1)
	v_pk_add_f32 v[42:43], v[22:23], 0 neg_lo:[1,1] neg_hi:[1,1]
	v_pk_fma_f32 v[38:39], v[80:81], v[76:77], v[38:39] op_sel:[1,1,0] op_sel_hi:[1,0,1] neg_lo:[1,0,0]
	s_nop 0
	v_mov_b32_e32 v42, v22
	v_pk_mul_f32 v[84:85], v[42:43], v[78:79] op_sel:[0,0] op_sel_hi:[0,1]
	s_nop 0
	v_pk_fma_f32 v[42:43], v[42:43], v[78:79], v[84:85] op_sel:[1,1,0] op_sel_hi:[1,0,1] neg_lo:[1,0,0]
	v_pk_mul_f32 v[84:85], v[82:83], v[72:73] op_sel:[0,0] op_sel_hi:[0,1]
	s_nop 0
	v_pk_fma_f32 v[86:87], v[82:83], v[72:73], v[84:85] op_sel:[1,1,0] op_sel_hi:[1,0,1] neg_lo:[1,0,0]
	s_waitcnt lgkmcnt(0)
	v_pk_add_f32 v[84:85], v[30:31], 0 neg_lo:[1,1] neg_hi:[1,1]
	s_nop 0
	v_mov_b32_e32 v84, v30
	v_pk_mul_f32 v[88:89], v[84:85], v[74:75] op_sel:[0,0] op_sel_hi:[0,1]
	s_nop 0
	v_pk_fma_f32 v[88:89], v[84:85], v[74:75], v[88:89] op_sel:[1,1,0] op_sel_hi:[1,0,1] neg_lo:[1,0,0]
	v_pk_add_f32 v[84:85], v[38:39], v[42:43]
	v_pk_mul_f32 v[38:39], v[22:23], v[76:77] op_sel:[0,0] op_sel_hi:[0,1] neg_hi:[0,1]
	v_pk_add_f32 v[86:87], v[86:87], v[88:89]
	v_pk_fma_f32 v[22:23], v[22:23], v[76:77], v[38:39] op_sel:[1,1,0] op_sel_hi:[1,0,1]
	v_pk_mul_f32 v[38:39], v[80:81], v[78:79] op_sel:[0,0] op_sel_hi:[0,1]
	ds_write_b128 v198, v[84:87]
	v_pk_fma_f32 v[38:39], v[80:81], v[78:79], v[38:39] op_sel:[1,1,0] op_sel_hi:[1,0,1] neg_lo:[1,0,0]
	s_nop 0
	v_pk_add_f32 v[42:43], v[38:39], 0 neg_lo:[1,1] neg_hi:[1,1]
	s_nop 0
	v_mov_b32_e32 v39, v43
	v_pk_add_f32 v[22:23], v[22:23], v[38:39]
	ds_write_b64 v199, v[22:23]
	v_pk_mul_f32 v[22:23], v[30:31], v[72:73] op_sel:[0,0] op_sel_hi:[0,1] neg_hi:[0,1]
	s_nop 0
	v_pk_fma_f32 v[22:23], v[30:31], v[72:73], v[22:23] op_sel:[1,1,0] op_sel_hi:[1,0,1]
	v_pk_mul_f32 v[30:31], v[82:83], v[74:75] op_sel:[0,0] op_sel_hi:[0,1]
	s_nop 0
	v_pk_fma_f32 v[30:31], v[82:83], v[74:75], v[30:31] op_sel:[1,1,0] op_sel_hi:[1,0,1] neg_lo:[1,0,0]
	s_nop 0
	v_pk_add_f32 v[38:39], v[30:31], 0 neg_lo:[1,1] neg_hi:[1,1]
	s_nop 0
	v_mov_b32_e32 v31, v39
	v_pk_add_f32 v[22:23], v[22:23], v[30:31]
	ds_write_b64 v200, v[22:23]
	ds_read_b128 v[72:75], v201
	ds_read_b64 v[22:23], v202
	ds_read_b64 v[30:31], v203
	s_waitcnt vmcnt(4) lgkmcnt(2)
	v_pk_mul_f32 v[38:39], v[72:73], v[68:69] op_sel:[0,0] op_sel_hi:[0,1]
	s_waitcnt lgkmcnt(1)
	v_pk_add_f32 v[42:43], v[22:23], 0 neg_lo:[1,1] neg_hi:[1,1]
	v_pk_fma_f32 v[38:39], v[72:73], v[68:69], v[38:39] op_sel:[1,1,0] op_sel_hi:[1,0,1] neg_lo:[1,0,0]
	s_nop 0
	v_mov_b32_e32 v42, v22
	v_pk_mul_f32 v[76:77], v[42:43], v[70:71] op_sel:[0,0] op_sel_hi:[0,1]
	s_nop 0
	v_pk_fma_f32 v[42:43], v[42:43], v[70:71], v[76:77] op_sel:[1,1,0] op_sel_hi:[1,0,1] neg_lo:[1,0,0]
	v_pk_mul_f32 v[76:77], v[74:75], v[64:65] op_sel:[0,0] op_sel_hi:[0,1]
	s_nop 0
	v_pk_fma_f32 v[78:79], v[74:75], v[64:65], v[76:77] op_sel:[1,1,0] op_sel_hi:[1,0,1] neg_lo:[1,0,0]
	s_waitcnt lgkmcnt(0)
; #define LAS __attribute__((address_space(3)))
; __device__ __forceinline__ cf cconj(cf a) { return (cf){a.x, -a.y}; }
; __device__ __forceinline__ int p_of_k(int k) { return ((k & 15) << 10) | (((k >> 4) & 15) << 6) | (((k >> 8) & 15) << 2) | (k >> 12); }
; __device__ __forceinline__ void hyena_phase(LAS unsigned char* L, const Args& a, int vcu, int G) {
;     ...
; #pragma unroll
;             for (int i = 0; i < 8; ++i) {
;                 const int g = tid + 512 * i;
;                 const int kg = (g >> 8) | (((g >> 4) & 15) << 4) | ((g & 15) << 8);
;                 const int pp0 = p_of_k((NFFT - kg) & (NFFT - 1)), pp1 = p_of_k(12288 - kg);
;                 const int p0 = PH(4 * g);
;                 const f32x4 zz = *(LAS f32x4*)(z + p0);
;                 const cf zk0 = {zz[0], zz[1]}, zk1 = {zz[2], zz[3]};
;                 const cf zn0 = z[PH(pp0)], zn1 = z[PH(pp1)];
;                 const f32x4 s0 = sd[2 * i], s1 = sd[2 * i + 1];
;                 const cf S0 = {s0[0], s0[1]}, D0 = {s0[2], s0[3]}, S1 = {s1[0], s1[1]}, D1 = {s1[2], s1[3]};
;                 const cf w0 = cmul(zk0, S0) + cmul(cconj(zn0), D0), w1 = cmul(zk1, S1) + cmul(cconj(zn1), D1);
;                 *(LAS f32x4*)(z + p0) = (f32x4){w0.x, w0.y, w1.x, w1.y};
;                 if (kg != 0) z[PH(pp0)] = cmulc(zn0, S0) + cconj(cmul(zk0, D0));
;                 z[PH(pp1)] = cmulc(zn1, S1) + cconj(cmul(zk1, D1));
;             }
;             if (tid == 0) { const f32x4 s8 = SD8[pair]; const cf S = {s8[0], s8[1]}, Dd = {s8[2], s8[3]}; const cf zk = z[PH(2)]; z[PH(2)] = cmul(zk, S) + cmul(cconj(zk), Dd); }
	v_pk_add_f32 v[76:77], v[30:31], 0 neg_lo:[1,1] neg_hi:[1,1]
	s_nop 0
	v_mov_b32_e32 v76, v30
	v_pk_mul_f32 v[80:81], v[76:77], v[66:67] op_sel:[0,0] op_sel_hi:[0,1]
	s_nop 0
	v_pk_fma_f32 v[80:81], v[76:77], v[66:67], v[80:81] op_sel:[1,1,0] op_sel_hi:[1,0,1] neg_lo:[1,0,0]
	v_pk_add_f32 v[76:77], v[38:39], v[42:43]
	v_pk_mul_f32 v[38:39], v[22:23], v[68:69] op_sel:[0,0] op_sel_hi:[0,1] neg_hi:[0,1]
	v_pk_add_f32 v[78:79], v[78:79], v[80:81]
	v_pk_fma_f32 v[22:23], v[22:23], v[68:69], v[38:39] op_sel:[1,1,0] op_sel_hi:[1,0,1]
	v_pk_mul_f32 v[38:39], v[72:73], v[70:71] op_sel:[0,0] op_sel_hi:[0,1]
	ds_write_b128 v201, v[76:79]
	v_pk_fma_f32 v[38:39], v[72:73], v[70:71], v[38:39] op_sel:[1,1,0] op_sel_hi:[1,0,1] neg_lo:[1,0,0]
	s_nop 0
	v_pk_add_f32 v[42:43], v[38:39], 0 neg_lo:[1,1] neg_hi:[1,1]
	s_nop 0
	v_mov_b32_e32 v39, v43
	v_pk_add_f32 v[22:23], v[22:23], v[38:39]
	ds_write_b64 v202, v[22:23]
	v_pk_mul_f32 v[22:23], v[30:31], v[64:65] op_sel:[0,0] op_sel_hi:[0,1] neg_hi:[0,1]
	s_nop 0
	v_pk_fma_f32 v[22:23], v[30:31], v[64:65], v[22:23] op_sel:[1,1,0] op_sel_hi:[1,0,1]
	v_pk_mul_f32 v[30:31], v[74:75], v[66:67] op_sel:[0,0] op_sel_hi:[0,1]
	s_nop 0
	v_pk_fma_f32 v[30:31], v[74:75], v[66:67], v[30:31] op_sel:[1,1,0] op_sel_hi:[1,0,1] neg_lo:[1,0,0]
	s_nop 0
	v_pk_add_f32 v[38:39], v[30:31], 0 neg_lo:[1,1] neg_hi:[1,1]
	s_nop 0
	v_mov_b32_e32 v31, v39
	v_pk_add_f32 v[22:23], v[22:23], v[30:31]
	ds_write_b64 v203, v[22:23]
	ds_read_b128 v[64:67], v204
	ds_read_b64 v[22:23], v205
	ds_read_b64 v[30:31], v206
	s_waitcnt vmcnt(2) lgkmcnt(2)
	v_pk_mul_f32 v[38:39], v[64:65], v[60:61] op_sel:[0,0] op_sel_hi:[0,1]
	s_waitcnt lgkmcnt(1)
	v_pk_add_f32 v[42:43], v[22:23], 0 neg_lo:[1,1] neg_hi:[1,1]
	v_pk_fma_f32 v[38:39], v[64:65], v[60:61], v[38:39] op_sel:[1,1,0] op_sel_hi:[1,0,1] neg_lo:[1,0,0]
	s_nop 0
	v_mov_b32_e32 v42, v22
	v_pk_mul_f32 v[68:69], v[42:43], v[62:63] op_sel:[0,0] op_sel_hi:[0,1]
	s_nop 0
	v_pk_fma_f32 v[42:43], v[42:43], v[62:63], v[68:69] op_sel:[1,1,0] op_sel_hi:[1,0,1] neg_lo:[1,0,0]
	v_pk_mul_f32 v[68:69], v[66:67], v[56:57] op_sel:[0,0] op_sel_hi:[0,1]
	s_nop 0
	v_pk_fma_f32 v[70:71], v[66:67], v[56:57], v[68:69] op_sel:[1,1,0] op_sel_hi:[1,0,1] neg_lo:[1,0,0]
	s_waitcnt lgkmcnt(0)
	v_pk_add_f32 v[68:69], v[30:31], 0 neg_lo:[1,1] neg_hi:[1,1]
	s_nop 0
	v_mov_b32_e32 v68, v30
	v_pk_mul_f32 v[72:73], v[68:69], v[58:59] op_sel:[0,0] op_sel_hi:[0,1]
	s_nop 0
	v_pk_fma_f32 v[72:73], v[68:69], v[58:59], v[72:73] op_sel:[1,1,0] op_sel_hi:[1,0,1] neg_lo:[1,0,0]
	v_pk_add_f32 v[68:69], v[38:39], v[42:43]
	v_pk_mul_f32 v[38:39], v[22:23], v[60:61] op_sel:[0,0] op_sel_hi:[0,1] neg_hi:[0,1]
	v_pk_add_f32 v[70:71], v[70:71], v[72:73]
	v_pk_fma_f32 v[22:23], v[22:23], v[60:61], v[38:39] op_sel:[1,1,0] op_sel_hi:[1,0,1]
	v_pk_mul_f32 v[38:39], v[64:65], v[62:63] op_sel:[0,0] op_sel_hi:[0,1]
	ds_write_b128 v204, v[68:71]
	v_pk_fma_f32 v[38:39], v[64:65], v[62:63], v[38:39] op_sel:[1,1,0] op_sel_hi:[1,0,1] neg_lo:[1,0,0]
	s_nop 0
	v_pk_add_f32 v[42:43], v[38:39], 0 neg_lo:[1,1] neg_hi:[1,1]
	s_nop 0
	v_mov_b32_e32 v39, v43
	v_pk_add_f32 v[22:23], v[22:23], v[38:39]
	ds_write_b64 v205, v[22:23]
	v_pk_mul_f32 v[22:23], v[30:31], v[56:57] op_sel:[0,0] op_sel_hi:[0,1] neg_hi:[0,1]
	s_nop 0
	v_pk_fma_f32 v[22:23], v[30:31], v[56:57], v[22:23] op_sel:[1,1,0] op_sel_hi:[1,0,1]
	v_pk_mul_f32 v[30:31], v[66:67], v[58:59] op_sel:[0,0] op_sel_hi:[0,1]
	s_nop 0
	v_pk_fma_f32 v[30:31], v[66:67], v[58:59], v[30:31] op_sel:[1,1,0] op_sel_hi:[1,0,1] neg_lo:[1,0,0]
	s_nop 0
	v_pk_add_f32 v[38:39], v[30:31], 0 neg_lo:[1,1] neg_hi:[1,1]
	s_nop 0
	v_mov_b32_e32 v31, v39
	v_pk_add_f32 v[22:23], v[22:23], v[30:31]
	ds_write_b64 v206, v[22:23]
	ds_read_b128 v[56:59], v207
	ds_read_b64 v[22:23], v208
	ds_read_b64 v[30:31], v209
	s_waitcnt vmcnt(0) lgkmcnt(2)
	v_pk_mul_f32 v[38:39], v[56:57], v[52:53] op_sel:[0,0] op_sel_hi:[0,1]
	s_waitcnt lgkmcnt(1)
	v_pk_add_f32 v[42:43], v[22:23], 0 neg_lo:[1,1] neg_hi:[1,1]
	v_pk_fma_f32 v[38:39], v[56:57], v[52:53], v[38:39] op_sel:[1,1,0] op_sel_hi:[1,0,1] neg_lo:[1,0,0]
	s_nop 0
	v_mov_b32_e32 v42, v22
	v_pk_mul_f32 v[60:61], v[42:43], v[54:55] op_sel:[0,0] op_sel_hi:[0,1]
	s_nop 0
	v_pk_fma_f32 v[42:43], v[42:43], v[54:55], v[60:61] op_sel:[1,1,0] op_sel_hi:[1,0,1] neg_lo:[1,0,0]
	v_pk_mul_f32 v[60:61], v[58:59], v[48:49] op_sel:[0,0] op_sel_hi:[0,1]
	s_nop 0
	v_pk_fma_f32 v[62:63], v[58:59], v[48:49], v[60:61] op_sel:[1,1,0] op_sel_hi:[1,0,1] neg_lo:[1,0,0]
	s_waitcnt lgkmcnt(0)
	v_pk_add_f32 v[60:61], v[30:31], 0 neg_lo:[1,1] neg_hi:[1,1]
	s_nop 0
	v_mov_b32_e32 v60, v30
	v_pk_mul_f32 v[64:65], v[60:61], v[50:51] op_sel:[0,0] op_sel_hi:[0,1]
	s_nop 0
	v_pk_fma_f32 v[64:65], v[60:61], v[50:51], v[64:65] op_sel:[1,1,0] op_sel_hi:[1,0,1] neg_lo:[1,0,0]
	v_pk_add_f32 v[60:61], v[38:39], v[42:43]
	v_pk_mul_f32 v[38:39], v[22:23], v[52:53] op_sel:[0,0] op_sel_hi:[0,1] neg_hi:[0,1]
	v_pk_add_f32 v[62:63], v[62:63], v[64:65]
	v_pk_fma_f32 v[22:23], v[22:23], v[52:53], v[38:39] op_sel:[1,1,0] op_sel_hi:[1,0,1]
	v_pk_mul_f32 v[38:39], v[56:57], v[54:55] op_sel:[0,0] op_sel_hi:[0,1]
	ds_write_b128 v207, v[60:63]
	v_pk_fma_f32 v[38:39], v[56:57], v[54:55], v[38:39] op_sel:[1,1,0] op_sel_hi:[1,0,1] neg_lo:[1,0,0]
	s_nop 0
	v_pk_add_f32 v[42:43], v[38:39], 0 neg_lo:[1,1] neg_hi:[1,1]
	s_nop 0
	v_mov_b32_e32 v39, v43
	v_pk_add_f32 v[22:23], v[22:23], v[38:39]
	ds_write_b64 v208, v[22:23]
	v_pk_mul_f32 v[22:23], v[30:31], v[48:49] op_sel:[0,0] op_sel_hi:[0,1] neg_hi:[0,1]
	s_nop 0
	v_pk_fma_f32 v[22:23], v[30:31], v[48:49], v[22:23] op_sel:[1,1,0] op_sel_hi:[1,0,1]
	v_pk_mul_f32 v[30:31], v[58:59], v[50:51] op_sel:[0,0] op_sel_hi:[0,1]
	s_nop 0
	v_pk_fma_f32 v[30:31], v[58:59], v[50:51], v[30:31] op_sel:[1,1,0] op_sel_hi:[1,0,1] neg_lo:[1,0,0]
	s_nop 0
	v_pk_add_f32 v[38:39], v[30:31], 0 neg_lo:[1,1] neg_hi:[1,1]
	s_nop 0
	v_mov_b32_e32 v31, v39
	v_pk_add_f32 v[22:23], v[22:23], v[30:31]
	ds_write_b64 v209, v[22:23]
	s_and_saveexec_b64 s[46:47], s[0:1]
	s_cbranch_execz .LBB0_1035
	ds_read_b64 v[22:23], v117 offset:16
	s_waitcnt vmcnt(0) lgkmcnt(0)
	v_pk_mul_f32 v[30:31], v[22:23], v[236:237] op_sel:[0,0] op_sel_hi:[0,1]
	s_nop 0
	v_pk_fma_f32 v[30:31], v[22:23], v[236:237], v[30:31] op_sel:[1,1,0] op_sel_hi:[1,0,1] neg_lo:[1,0,0]
	v_xor_b32_e32 v23, 0x80000000, v23
	v_pk_mul_f32 v[38:39], v[22:23], v[238:239] op_sel:[0,0] op_sel_hi:[0,1]
	s_nop 0
	v_pk_fma_f32 v[22:23], v[22:23], v[238:239], v[38:39] op_sel:[1,1,0] op_sel_hi:[1,0,1] neg_lo:[1,0,0]
	s_nop 0
	v_pk_add_f32 v[22:23], v[30:31], v[22:23]
	ds_write_b64 v117, v[22:23] offset:16

; #define LAS __attribute__((address_space(3)))
; template <bool INV, int LST, bool HALF = false> __device__ __forceinline__ void fft_pass16(LAS cf* z, const LAS cf* Thi, const LAS cf* Tlo, int tid) {
;     constexpr int st = 1 << LST;
;     cf w[16];
; #pragma unroll 1
;     for (int it = 0; it < 2; ++it) {
;         const int g = tid + 512 * it; const int j0 = g & (st - 1); const int base = ((g >> LST) << (LST + 4)) + j0; const int phb = PH(base);
;         if (LST == 10 || it == 0) {
;             const int e1 = j0 << (10 - LST);
;             w[1] = cmul(Thi[e1 >> 7], Tlo[e1 & 127]);
;             w[2] = cmul(w[1], w[1]); w[3] = cmul(w[2], w[1]); w[4] = cmul(w[2], w[2]); w[5] = cmul(w[4], w[1]); w[6] = cmul(w[3], w[3]); w[7] = cmul(w[4], w[3]); w[8] = cmul(w[4], w[4]);
; #pragma unroll
;             for (int q = 9; q < 16; ++q) w[q] = cmul(w[8], w[q - 8]);
;         }
;         cf x[16];
;         if (!INV) {
; #pragma unroll
;             for (int m = 0; m < 16; ++m) { if (HALF && m >= 8) x[m] = (cf){0.f, 0.f}; else x[m] = z[pass_pos<LST>(base, phb, m)]; }
;             dft16<false, HALF>(x);
; #pragma unroll
;             for (int q = 0; q < 16; ++q) { cf y = x[4 * (q & 3) + (q >> 2)]; if (q) y = cmul(y, w[q]); z[pass_pos<LST>(base, phb, q)] = y; }
;         } else {
; #pragma unroll
;             for (int q = 0; q < 16; ++q) { cf y = z[pass_pos<LST>(base, phb, q)]; if (q) y = cmulc(y, w[q]); x[q] = y; }
;             dft16<true>(x);
.LBB0_1038:
	v_add_u32_e32 v29, s21, v169
	v_and_or_b32 v29, v29, s71, v172
	v_lshl_add_u32 v37, v29, 3, v174
	v_xor_b32_e32 v41, 0x20, v37
	v_xor_b32_e32 v108, 0x40, v37
	ds_read_b64 v[70:71], v41
	v_xor_b32_e32 v109, 0x60, v37
	ds_read_b64 v[72:73], v108
	ds_read_b64 v[74:75], v37
	ds_read_b64 v[76:77], v109
	s_waitcnt lgkmcnt(3)
	v_pk_mul_f32 v[78:79], v[70:71], v[22:23] op_sel:[0,0] op_sel_hi:[0,1] neg_hi:[0,1]
	s_nop 0
	v_pk_fma_f32 v[70:71], v[70:71], v[22:23], v[78:79] op_sel:[1,1,0] op_sel_hi:[1,0,1]
	s_waitcnt lgkmcnt(2)
	v_pk_mul_f32 v[78:79], v[72:73], v[30:31] op_sel:[0,0] op_sel_hi:[0,1] neg_hi:[0,1]
	v_xor_b32_e32 v111, 0xa0, v37
	v_pk_fma_f32 v[72:73], v[72:73], v[30:31], v[78:79] op_sel:[1,1,0] op_sel_hi:[1,0,1]
	s_waitcnt lgkmcnt(0)
	v_pk_mul_f32 v[78:79], v[76:77], v[38:39] op_sel:[0,0] op_sel_hi:[0,1] neg_hi:[0,1]
	s_nop 0
	v_pk_fma_f32 v[76:77], v[76:77], v[38:39], v[78:79] op_sel:[1,1,0] op_sel_hi:[1,0,1]
	v_xor_b32_e32 v110, 0x80, v37
	v_xor_b32_e32 v112, 0xc0, v37
	ds_read_b64 v[78:79], v110
	v_xor_b32_e32 v113, 0xe0, v37
	ds_read_b64 v[80:81], v111
	ds_read_b64 v[82:83], v112
	ds_read_b64 v[84:85], v113
	s_waitcnt lgkmcnt(3)
	v_pk_mul_f32 v[86:87], v[78:79], v[42:43] op_sel:[0,0] op_sel_hi:[0,1] neg_hi:[0,1]
	s_nop 0
	v_pk_fma_f32 v[78:79], v[78:79], v[42:43], v[86:87] op_sel:[1,1,0] op_sel_hi:[1,0,1]
	s_waitcnt lgkmcnt(2)
	v_pk_mul_f32 v[86:87], v[80:81], v[48:49] op_sel:[0,0] op_sel_hi:[0,1] neg_hi:[0,1]
	v_xor_b32_e32 v115, 0x120, v37
	v_pk_fma_f32 v[80:81], v[80:81], v[48:49], v[86:87] op_sel:[1,1,0] op_sel_hi:[1,0,1]
	s_waitcnt lgkmcnt(1)
	v_pk_mul_f32 v[86:87], v[82:83], v[50:51] op_sel:[0,0] op_sel_hi:[0,1] neg_hi:[0,1]
	s_nop 0
	v_pk_fma_f32 v[82:83], v[82:83], v[50:51], v[86:87] op_sel:[1,1,0] op_sel_hi:[1,0,1]
	s_waitcnt lgkmcnt(0)
	v_pk_mul_f32 v[86:87], v[84:85], v[52:53] op_sel:[0,0] op_sel_hi:[0,1] neg_hi:[0,1]
	v_xor_b32_e32 v125, 0x140, v37
	v_pk_fma_f32 v[84:85], v[84:85], v[52:53], v[86:87] op_sel:[1,1,0] op_sel_hi:[1,0,1]
	v_xor_b32_e32 v114, 0x100, v37
	ds_read_b64 v[86:87], v114
	v_xor_b32_e32 v182, 0x160, v37
	ds_read_b64 v[88:89], v115
	ds_read_b64 v[90:91], v125
	ds_read_b64 v[92:93], v182
	s_waitcnt lgkmcnt(3)
	v_pk_mul_f32 v[94:95], v[86:87], v[54:55] op_sel:[0,0] op_sel_hi:[0,1] neg_hi:[0,1]
	s_nop 0
	v_pk_fma_f32 v[86:87], v[86:87], v[54:55], v[94:95] op_sel:[1,1,0] op_sel_hi:[1,0,1]
	s_waitcnt lgkmcnt(2)
	v_pk_mul_f32 v[94:95], v[88:89], v[56:57] op_sel:[0,0] op_sel_hi:[0,1] neg_hi:[0,1]
	v_xor_b32_e32 v216, 0x1a0, v37
	v_pk_fma_f32 v[88:89], v[88:89], v[56:57], v[94:95] op_sel:[1,1,0] op_sel_hi:[1,0,1]
	s_waitcnt lgkmcnt(1)
	v_pk_mul_f32 v[94:95], v[90:91], v[58:59] op_sel:[0,0] op_sel_hi:[0,1] neg_hi:[0,1]
	s_nop 0
	v_pk_fma_f32 v[90:91], v[90:91], v[58:59], v[94:95] op_sel:[1,1,0] op_sel_hi:[1,0,1]
	s_waitcnt lgkmcnt(0)
	v_pk_mul_f32 v[94:95], v[92:93], v[60:61] op_sel:[0,0] op_sel_hi:[0,1] neg_hi:[0,1]
	v_xor_b32_e32 v217, 0x1c0, v37
	v_pk_fma_f32 v[92:93], v[92:93], v[60:61], v[94:95] op_sel:[1,1,0] op_sel_hi:[1,0,1]
	v_xor_b32_e32 v183, 0x180, v37
	ds_read_b64 v[94:95], v183
	v_xor_b32_e32 v29, 0x1e0, v37
	ds_read_b64 v[96:97], v216
	ds_read_b64 v[98:99], v217
	ds_read_b64 v[100:101], v29
	s_waitcnt lgkmcnt(3)
	v_pk_mul_f32 v[102:103], v[94:95], v[62:63] op_sel:[0,0] op_sel_hi:[0,1] neg_hi:[0,1]
	s_mov_b32 s46, s25
	v_pk_fma_f32 v[94:95], v[94:95], v[62:63], v[102:103] op_sel:[1,1,0] op_sel_hi:[1,0,1]
	s_waitcnt lgkmcnt(2)
	v_pk_mul_f32 v[102:103], v[96:97], v[64:65] op_sel:[0,0] op_sel_hi:[0,1] neg_hi:[0,1]
	s_mov_b32 s47, s24
	v_pk_fma_f32 v[96:97], v[96:97], v[64:65], v[102:103] op_sel:[1,1,0] op_sel_hi:[1,0,1]
	s_waitcnt lgkmcnt(1)
	v_pk_mul_f32 v[102:103], v[98:99], v[66:67] op_sel:[0,0] op_sel_hi:[0,1] neg_hi:[0,1]
	s_andn2_b64 vcc, exec, s[44:45]
	v_pk_fma_f32 v[98:99], v[98:99], v[66:67], v[102:103] op_sel:[1,1,0] op_sel_hi:[1,0,1]
	s_waitcnt lgkmcnt(0)
; __device__ __forceinline__ cf add_mib(cf a, cf b) { cf r; asm("v_pk_add_f32 %0, %1, %2 op_sel:[0,1] op_sel_hi:[1,0] neg_hi:[0,1]" : "=v"(r) : "v"(a), "v"(b)); return r; }
; __device__ __forceinline__ cf add_pib(cf a, cf b) { cf r; asm("v_pk_add_f32 %0, %1, %2 op_sel:[0,1] op_sel_hi:[1,0] neg_lo:[0,1]" : "=v"(r) : "v"(a), "v"(b)); return r; }
; template <bool INV, bool HALFIN = false> __device__ __forceinline__ void dft16(cf (&x)[16]) {
; #pragma unroll
;     for (int m2 = 0; m2 < 4; ++m2) {
;         if (HALFIN) { const cf a0 = x[m2], a1 = x[4 + m2]; x[m2] = a0 + a1; x[8 + m2] = a0 - a1; x[4 + m2] = add_mib(a0, a1); x[12 + m2] = add_pib(a0, a1); }
;         else dft4<INV>(x[m2], x[4 + m2], x[8 + m2], x[12 + m2]);
;     }
;     constexpr float C1 = 0.9238795325112867f, S1 = 0.3826834323650898f, C2 = 0.7071067811865476f;
;     x[4 * 1 + 1] = tw16<INV>(x[5], C1, S1);  x[4 * 1 + 2] = tw16<INV>(x[6], C2, C2);   x[4 * 1 + 3] = tw16<INV>(x[7], S1, C1);
;     x[4 * 2 + 1] = tw16<INV>(x[9], C2, C2);  x[4 * 2 + 2] = tw16<INV>(x[10], 0.f, 1.f); x[4 * 2 + 3] = tw16<INV>(x[11], -C2, C2);
;     x[4 * 3 + 1] = tw16<INV>(x[13], S1, C1); x[4 * 3 + 2] = tw16<INV>(x[14], -C2, C2); x[4 * 3 + 3] = tw16<INV>(x[15], -C1, -S1);
; #pragma unroll
;     for (int q1 = 0; q1 < 4; ++q1) dft4<INV>(x[4 * q1], x[4 * q1 + 1], x[4 * q1 + 2], x[4 * q1 + 3]);
; }
; template <bool INV, int LST, bool HALF = false> __device__ __forceinline__ void fft_pass16(LAS cf* z, const LAS cf* Thi, const LAS cf* Tlo, int tid) {
;     ...
;             dft16<true>(x);
; #pragma unroll
;             for (int m = 0; m < (HALF ? 8 : 16); ++m) z[pass_pos<LST>(base, phb, m)] = x[4 * (m & 3) + (m >> 2)];
	v_pk_mul_f32 v[102:103], v[100:101], v[68:69] op_sel:[0,0] op_sel_hi:[0,1] neg_hi:[0,1]
	s_mov_b64 s[44:45], 0
	v_pk_fma_f32 v[100:101], v[100:101], v[68:69], v[102:103] op_sel:[1,1,0] op_sel_hi:[1,0,1]
	v_pk_add_f32 v[102:103], v[74:75], v[86:87]
	v_pk_add_f32 v[74:75], v[74:75], v[86:87] neg_lo:[0,1] neg_hi:[0,1]
	v_pk_add_f32 v[86:87], v[78:79], v[94:95]
	v_pk_add_f32 v[78:79], v[78:79], v[94:95] neg_lo:[0,1] neg_hi:[0,1]
	v_pk_add_f32 v[94:95], v[102:103], v[86:87]
	v_pk_add_f32 v[86:87], v[102:103], v[86:87] neg_lo:[0,1] neg_hi:[0,1]
	v_pk_add_f32 v[102:103], v[74:75], v[78:79] op_sel:[0,1] op_sel_hi:[1,0] neg_lo:[0,1]
	v_pk_add_f32 v[74:75], v[74:75], v[78:79] op_sel:[0,1] op_sel_hi:[1,0] neg_hi:[0,1]
	v_pk_add_f32 v[78:79], v[70:71], v[88:89]
	v_pk_add_f32 v[70:71], v[70:71], v[88:89] neg_lo:[0,1] neg_hi:[0,1]
	v_pk_add_f32 v[88:89], v[80:81], v[96:97]
	v_pk_add_f32 v[80:81], v[80:81], v[96:97] neg_lo:[0,1] neg_hi:[0,1]
	v_pk_add_f32 v[96:97], v[78:79], v[88:89]
	v_pk_add_f32 v[78:79], v[78:79], v[88:89] neg_lo:[0,1] neg_hi:[0,1]
	v_pk_add_f32 v[88:89], v[70:71], v[80:81] op_sel:[0,1] op_sel_hi:[1,0] neg_lo:[0,1]
	v_pk_add_f32 v[70:71], v[70:71], v[80:81] op_sel:[0,1] op_sel_hi:[1,0] neg_hi:[0,1]
	v_pk_add_f32 v[80:81], v[72:73], v[90:91]
	v_pk_add_f32 v[72:73], v[72:73], v[90:91] neg_lo:[0,1] neg_hi:[0,1]
	v_pk_add_f32 v[90:91], v[82:83], v[98:99]
	v_pk_add_f32 v[82:83], v[82:83], v[98:99] neg_lo:[0,1] neg_hi:[0,1]
	v_pk_add_f32 v[98:99], v[80:81], v[90:91]
	v_pk_add_f32 v[80:81], v[80:81], v[90:91] neg_lo:[0,1] neg_hi:[0,1]
	v_pk_add_f32 v[90:91], v[72:73], v[82:83] op_sel:[0,1] op_sel_hi:[1,0] neg_lo:[0,1]
	v_pk_add_f32 v[72:73], v[72:73], v[82:83] op_sel:[0,1] op_sel_hi:[1,0] neg_hi:[0,1]
	v_pk_add_f32 v[82:83], v[76:77], v[92:93]
	v_pk_add_f32 v[76:77], v[76:77], v[92:93] neg_lo:[0,1] neg_hi:[0,1]
	v_pk_add_f32 v[92:93], v[84:85], v[100:101]
	v_pk_add_f32 v[84:85], v[84:85], v[100:101] neg_lo:[0,1] neg_hi:[0,1]
	v_pk_add_f32 v[100:101], v[82:83], v[92:93]
	v_pk_add_f32 v[82:83], v[82:83], v[92:93] neg_lo:[0,1] neg_hi:[0,1]
	v_pk_add_f32 v[92:93], v[76:77], v[84:85] op_sel:[0,1] op_sel_hi:[1,0] neg_lo:[0,1]
	v_pk_add_f32 v[76:77], v[76:77], v[84:85] op_sel:[0,1] op_sel_hi:[1,0] neg_hi:[0,1]
	v_pk_mul_f32 v[84:85], v[88:89], s[22:23] op_sel_hi:[1,0]
	s_nop 0
	v_pk_fma_f32 v[104:105], v[88:89], s[20:21], v[84:85] op_sel:[0,0,1] op_sel_hi:[1,0,0] neg_lo:[0,0,1]
	s_nop 0
	v_pk_mul_f32 v[84:85], v[90:91], s[24:25] op_sel_hi:[1,0]
	s_nop 0
	v_pk_fma_f32 v[88:89], v[90:91], s[24:25], v[84:85] op_sel:[0,0,1] op_sel_hi:[1,0,0] neg_lo:[0,0,1]
	v_pk_mul_f32 v[90:91], v[92:93], s[20:21] op_sel_hi:[1,0]
	s_nop 0
	v_pk_fma_f32 v[106:107], v[92:93], s[22:23], v[90:91] op_sel:[0,0,1] op_sel_hi:[1,0,0] neg_lo:[0,0,1]
	v_pk_add_f32 v[84:85], v[102:103], v[88:89]
	v_pk_mul_f32 v[90:91], v[78:79], s[24:25] op_sel_hi:[1,0]
	v_pk_add_f32 v[88:89], v[102:103], v[88:89] neg_lo:[0,1] neg_hi:[0,1]
	v_pk_fma_f32 v[92:93], v[78:79], s[24:25], v[90:91] op_sel:[0,0,1] op_sel_hi:[1,0,0] neg_lo:[0,0,1]
	s_nop 0
	v_pk_fma_f32 v[78:79], v[80:81], 0, v[80:81] op_sel:[0,0,1] op_sel_hi:[1,0,0] neg_lo:[0,0,1] neg_hi:[0,0,1]
	v_pk_fma_f32 v[80:81], v[80:81], 0, v[80:81] op_sel:[0,0,1] op_sel_hi:[1,0,0]
	s_nop 0
	v_mul_f32_e32 v80, 0x3f3504f3, v83
	v_mov_b32_e32 v79, v81
	v_pk_fma_f32 v[80:81], v[82:83], s[46:47], v[80:81] op_sel_hi:[0,1,0] neg_lo:[0,0,1] neg_hi:[0,0,1]
	v_pk_mul_f32 v[82:83], v[70:71], s[20:21] op_sel_hi:[1,0]
	s_movk_i32 s21, 0x2000
	v_pk_fma_f32 v[90:91], v[70:71], s[22:23], v[82:83] op_sel:[0,0,1] op_sel_hi:[1,0,0] neg_lo:[0,0,1] neg_hi:[0,0,1]
	v_pk_fma_f32 v[70:71], v[70:71], s[22:23], v[82:83] op_sel:[0,0,1] op_sel_hi:[1,0,0]
	s_mov_b32 s23, s37
	v_mul_f32_e32 v70, 0x3f3504f3, v73
	v_mov_b32_e32 v91, v71
	v_pk_fma_f32 v[70:71], v[72:73], s[46:47], v[70:71] op_sel_hi:[0,1,0] neg_lo:[0,0,1] neg_hi:[0,0,1]
	s_mov_b32 s46, s37
	s_mov_b32 s47, s36
	v_pk_mul_f32 v[72:73], v[76:77], s[46:47] op_sel_hi:[0,1]
	v_pk_fma_f32 v[72:73], v[76:77], s[22:23], v[72:73] op_sel:[1,0,0]
	v_pk_add_f32 v[76:77], v[94:95], v[98:99]
	v_pk_add_f32 v[82:83], v[94:95], v[98:99] neg_lo:[0,1] neg_hi:[0,1]
	v_pk_add_f32 v[94:95], v[96:97], v[100:101]
	v_pk_add_f32 v[96:97], v[96:97], v[100:101] neg_lo:[0,1] neg_hi:[0,1]
	v_pk_add_f32 v[98:99], v[76:77], v[94:95]
	v_pk_add_f32 v[76:77], v[76:77], v[94:95] neg_lo:[0,1] neg_hi:[0,1]
	v_pk_add_f32 v[94:95], v[82:83], v[96:97] op_sel:[0,1] op_sel_hi:[1,0] neg_lo:[0,1]
	v_pk_add_f32 v[82:83], v[82:83], v[96:97] op_sel:[0,1] op_sel_hi:[1,0] neg_hi:[0,1]
	v_pk_add_f32 v[96:97], v[104:105], v[106:107]
	v_pk_add_f32 v[100:101], v[104:105], v[106:107] neg_lo:[0,1] neg_hi:[0,1]
	v_pk_add_f32 v[102:103], v[84:85], v[96:97]
	v_pk_add_f32 v[84:85], v[84:85], v[96:97] neg_lo:[0,1] neg_hi:[0,1]
	v_pk_add_f32 v[96:97], v[88:89], v[100:101] op_sel:[0,1] op_sel_hi:[1,0] neg_lo:[0,1]
	v_pk_add_f32 v[88:89], v[88:89], v[100:101] op_sel:[0,1] op_sel_hi:[1,0] neg_hi:[0,1]
	v_pk_add_f32 v[100:101], v[86:87], v[78:79]
	v_pk_add_f32 v[78:79], v[86:87], v[78:79] neg_lo:[0,1] neg_hi:[0,1]
	v_pk_add_f32 v[86:87], v[92:93], v[80:81]
	v_pk_add_f32 v[80:81], v[92:93], v[80:81] neg_lo:[0,1] neg_hi:[0,1]
	v_pk_add_f32 v[92:93], v[100:101], v[86:87]
	v_pk_add_f32 v[86:87], v[100:101], v[86:87] neg_lo:[0,1] neg_hi:[0,1]
	v_pk_add_f32 v[100:101], v[78:79], v[80:81] op_sel:[0,1] op_sel_hi:[1,0] neg_lo:[0,1]
	v_pk_add_f32 v[78:79], v[78:79], v[80:81] op_sel:[0,1] op_sel_hi:[1,0] neg_hi:[0,1]
	v_pk_add_f32 v[80:81], v[74:75], v[70:71]
	v_pk_add_f32 v[70:71], v[74:75], v[70:71] neg_lo:[0,1] neg_hi:[0,1]
	v_pk_add_f32 v[74:75], v[90:91], v[72:73]
	v_pk_add_f32 v[72:73], v[90:91], v[72:73] neg_lo:[0,1] neg_hi:[0,1]
	v_pk_add_f32 v[90:91], v[80:81], v[74:75]
	v_pk_add_f32 v[74:75], v[80:81], v[74:75] neg_lo:[0,1] neg_hi:[0,1]
	v_pk_add_f32 v[80:81], v[70:71], v[72:73] op_sel:[0,1] op_sel_hi:[1,0] neg_lo:[0,1]
	v_pk_add_f32 v[70:71], v[70:71], v[72:73] op_sel:[0,1] op_sel_hi:[1,0] neg_hi:[0,1]
	ds_write_b64 v37, v[98:99]
	ds_write_b64 v41, v[102:103]
	ds_write_b64 v108, v[92:93]
	ds_write_b64 v109, v[90:91]
	ds_write_b64 v110, v[94:95]
	ds_write_b64 v111, v[96:97]
	ds_write_b64 v112, v[100:101]
	ds_write_b64 v113, v[80:81]
	ds_write_b64 v114, v[76:77]
	ds_write_b64 v115, v[84:85]
	ds_write_b64 v125, v[86:87]
	ds_write_b64 v182, v[74:75]
	ds_write_b64 v183, v[82:83]
	ds_write_b64 v216, v[88:89]
	ds_write_b64 v217, v[78:79]
	ds_write_b64 v29, v[70:71]
	s_cbranch_vccz .LBB0_1041

; #define LAS __attribute__((address_space(3)))
; template <int LST> __device__ __forceinline__ int pass_pos(int base, int phb, int m) {
;     ...
;     if (LST == 6) return (base ^ (m << 2)) + (m << 6);
;     return PH(base + (m << LST));
; }
; template <bool INV, int LST, bool HALF = false> __device__ __forceinline__ void fft_pass16(LAS cf* z, const LAS cf* Thi, const LAS cf* Tlo, int tid) {
;     constexpr int st = 1 << LST;
;     cf w[16];
; #pragma unroll 1
;     for (int it = 0; it < 2; ++it) {
;         const int g = tid + 512 * it; const int j0 = g & (st - 1); const int base = ((g >> LST) << (LST + 4)) + j0; const int phb = PH(base);
;         if (LST == 10 || it == 0) {
;             const int e1 = j0 << (10 - LST);
;             w[1] = cmul(Thi[e1 >> 7], Tlo[e1 & 127]);
;             w[2] = cmul(w[1], w[1]); w[3] = cmul(w[2], w[1]); w[4] = cmul(w[2], w[2]); w[5] = cmul(w[4], w[1]); w[6] = cmul(w[3], w[3]); w[7] = cmul(w[4], w[3]); w[8] = cmul(w[4], w[4]);
; #pragma unroll
;             for (int q = 9; q < 16; ++q) w[q] = cmul(w[8], w[q - 8]);
;         }
;         cf x[16];
;         if (!INV) {
; #pragma unroll
;             for (int m = 0; m < 16; ++m) { if (HALF && m >= 8) x[m] = (cf){0.f, 0.f}; else x[m] = z[pass_pos<LST>(base, phb, m)]; }
;             dft16<false, HALF>(x);
; #pragma unroll
;             for (int q = 0; q < 16; ++q) { cf y = x[4 * (q & 3) + (q >> 2)]; if (q) y = cmul(y, w[q]); z[pass_pos<LST>(base, phb, q)] = y; }
;         } else {
; #pragma unroll
;             for (int q = 0; q < 16; ++q) { cf y = z[pass_pos<LST>(base, phb, q)]; if (q) y = cmulc(y, w[q]); x[q] = y; }
.LBB0_1042:
	v_add_u32_e32 v21, s21, v169
	v_and_b32_e32 v21, 0x7c00, v21
	v_or_b32_e32 v29, v21, v122
	v_lshl_add_u32 v29, v29, 3, 0
	v_xor_b32_e32 v37, 0x20, v29
	v_xor_b32_e32 v41, 0x40, v29
	ds_read_b64 v[70:71], v37 offset:512
	v_xor_b32_e32 v108, 0x60, v29
	ds_read_b64 v[72:73], v41 offset:1024
	ds_read_b64 v[74:75], v29
	ds_read_b64 v[76:77], v108 offset:1536
	s_waitcnt lgkmcnt(3)
	v_pk_mul_f32 v[78:79], v[70:71], v[22:23] op_sel:[0,0] op_sel_hi:[0,1] neg_hi:[0,1]
	s_nop 0
	v_pk_fma_f32 v[70:71], v[70:71], v[22:23], v[78:79] op_sel:[1,1,0] op_sel_hi:[1,0,1]
	s_waitcnt lgkmcnt(2)
	v_pk_mul_f32 v[78:79], v[72:73], v[30:31] op_sel:[0,0] op_sel_hi:[0,1] neg_hi:[0,1]
	v_xor_b32_e32 v110, 0xa0, v29
	v_pk_fma_f32 v[72:73], v[72:73], v[30:31], v[78:79] op_sel:[1,1,0] op_sel_hi:[1,0,1]
	s_waitcnt lgkmcnt(0)
	v_pk_mul_f32 v[78:79], v[76:77], v[38:39] op_sel:[0,0] op_sel_hi:[0,1] neg_hi:[0,1]
	s_nop 0
	v_pk_fma_f32 v[76:77], v[76:77], v[38:39], v[78:79] op_sel:[1,1,0] op_sel_hi:[1,0,1]
	v_xor_b32_e32 v109, 0x80, v29
	v_xor_b32_e32 v111, 0xc0, v29
	ds_read_b64 v[78:79], v109 offset:2048
	v_xor_b32_e32 v112, 0xe0, v29
	ds_read_b64 v[80:81], v110 offset:2560
	ds_read_b64 v[82:83], v111 offset:3072
	ds_read_b64 v[84:85], v112 offset:3584
	s_waitcnt lgkmcnt(3)
	v_pk_mul_f32 v[86:87], v[78:79], v[42:43] op_sel:[0,0] op_sel_hi:[0,1] neg_hi:[0,1]
	s_nop 0
	v_pk_fma_f32 v[78:79], v[78:79], v[42:43], v[86:87] op_sel:[1,1,0] op_sel_hi:[1,0,1]
	s_waitcnt lgkmcnt(2)
	v_pk_mul_f32 v[86:87], v[80:81], v[48:49] op_sel:[0,0] op_sel_hi:[0,1] neg_hi:[0,1]
	v_xor_b32_e32 v114, 0x120, v29
	v_pk_fma_f32 v[80:81], v[80:81], v[48:49], v[86:87] op_sel:[1,1,0] op_sel_hi:[1,0,1]
	s_waitcnt lgkmcnt(1)
	v_pk_mul_f32 v[86:87], v[82:83], v[50:51] op_sel:[0,0] op_sel_hi:[0,1] neg_hi:[0,1]
	s_nop 0
	v_pk_fma_f32 v[82:83], v[82:83], v[50:51], v[86:87] op_sel:[1,1,0] op_sel_hi:[1,0,1]
	s_waitcnt lgkmcnt(0)
	v_pk_mul_f32 v[86:87], v[84:85], v[52:53] op_sel:[0,0] op_sel_hi:[0,1] neg_hi:[0,1]
	v_xor_b32_e32 v115, 0x140, v29
	v_pk_fma_f32 v[84:85], v[84:85], v[52:53], v[86:87] op_sel:[1,1,0] op_sel_hi:[1,0,1]
	v_xor_b32_e32 v113, 0x100, v29
	ds_read_b64 v[86:87], v113 offset:4096
	v_xor_b32_e32 v125, 0x160, v29
	ds_read_b64 v[88:89], v114 offset:4608
	ds_read_b64 v[90:91], v115 offset:5120
	ds_read_b64 v[92:93], v125 offset:5632
	s_waitcnt lgkmcnt(3)
	v_pk_mul_f32 v[94:95], v[86:87], v[54:55] op_sel:[0,0] op_sel_hi:[0,1] neg_hi:[0,1]
	s_nop 0
	v_pk_fma_f32 v[86:87], v[86:87], v[54:55], v[94:95] op_sel:[1,1,0] op_sel_hi:[1,0,1]
	s_waitcnt lgkmcnt(2)
	v_pk_mul_f32 v[94:95], v[88:89], v[56:57] op_sel:[0,0] op_sel_hi:[0,1] neg_hi:[0,1]
	v_xor_b32_e32 v183, 0x1a0, v29
	v_pk_fma_f32 v[88:89], v[88:89], v[56:57], v[94:95] op_sel:[1,1,0] op_sel_hi:[1,0,1]
	s_waitcnt lgkmcnt(1)
	v_pk_mul_f32 v[94:95], v[90:91], v[58:59] op_sel:[0,0] op_sel_hi:[0,1] neg_hi:[0,1]
	s_nop 0
	v_pk_fma_f32 v[90:91], v[90:91], v[58:59], v[94:95] op_sel:[1,1,0] op_sel_hi:[1,0,1]
	s_waitcnt lgkmcnt(0)
	v_pk_mul_f32 v[94:95], v[92:93], v[60:61] op_sel:[0,0] op_sel_hi:[0,1] neg_hi:[0,1]
	v_xor_b32_e32 v216, 0x1c0, v29
	v_pk_fma_f32 v[92:93], v[92:93], v[60:61], v[94:95] op_sel:[1,1,0] op_sel_hi:[1,0,1]
	v_xor_b32_e32 v182, 0x180, v29
	ds_read_b64 v[94:95], v182 offset:6144
	v_xor_b32_e32 v21, 0x1e0, v29
	ds_read_b64 v[96:97], v183 offset:6656
	ds_read_b64 v[98:99], v216 offset:7168
	ds_read_b64 v[100:101], v21 offset:7680
	s_waitcnt lgkmcnt(3)
	v_pk_mul_f32 v[102:103], v[94:95], v[62:63] op_sel:[0,0] op_sel_hi:[0,1] neg_hi:[0,1]
	s_mov_b32 s46, s25
	v_pk_fma_f32 v[94:95], v[94:95], v[62:63], v[102:103] op_sel:[1,1,0] op_sel_hi:[1,0,1]
	s_waitcnt lgkmcnt(2)
	v_pk_mul_f32 v[102:103], v[96:97], v[64:65] op_sel:[0,0] op_sel_hi:[0,1] neg_hi:[0,1]
	s_mov_b32 s47, s24
	v_pk_fma_f32 v[96:97], v[96:97], v[64:65], v[102:103] op_sel:[1,1,0] op_sel_hi:[1,0,1]
	s_waitcnt lgkmcnt(1)
	v_pk_mul_f32 v[102:103], v[98:99], v[66:67] op_sel:[0,0] op_sel_hi:[0,1] neg_hi:[0,1]
	s_andn2_b64 vcc, exec, s[44:45]
	v_pk_fma_f32 v[98:99], v[98:99], v[66:67], v[102:103] op_sel:[1,1,0] op_sel_hi:[1,0,1]
	s_waitcnt lgkmcnt(0)
; __device__ __forceinline__ cf add_mib(cf a, cf b) { cf r; asm("v_pk_add_f32 %0, %1, %2 op_sel:[0,1] op_sel_hi:[1,0] neg_hi:[0,1]" : "=v"(r) : "v"(a), "v"(b)); return r; }
; __device__ __forceinline__ cf add_pib(cf a, cf b) { cf r; asm("v_pk_add_f32 %0, %1, %2 op_sel:[0,1] op_sel_hi:[1,0] neg_lo:[0,1]" : "=v"(r) : "v"(a), "v"(b)); return r; }
; template <bool INV, bool HALFIN = false> __device__ __forceinline__ void dft16(cf (&x)[16]) {
; #pragma unroll
;     for (int m2 = 0; m2 < 4; ++m2) {
;         if (HALFIN) { const cf a0 = x[m2], a1 = x[4 + m2]; x[m2] = a0 + a1; x[8 + m2] = a0 - a1; x[4 + m2] = add_mib(a0, a1); x[12 + m2] = add_pib(a0, a1); }
;         else dft4<INV>(x[m2], x[4 + m2], x[8 + m2], x[12 + m2]);
;     }
;     constexpr float C1 = 0.9238795325112867f, S1 = 0.3826834323650898f, C2 = 0.7071067811865476f;
;     x[4 * 1 + 1] = tw16<INV>(x[5], C1, S1);  x[4 * 1 + 2] = tw16<INV>(x[6], C2, C2);   x[4 * 1 + 3] = tw16<INV>(x[7], S1, C1);
;     x[4 * 2 + 1] = tw16<INV>(x[9], C2, C2);  x[4 * 2 + 2] = tw16<INV>(x[10], 0.f, 1.f); x[4 * 2 + 3] = tw16<INV>(x[11], -C2, C2);
;     x[4 * 3 + 1] = tw16<INV>(x[13], S1, C1); x[4 * 3 + 2] = tw16<INV>(x[14], -C2, C2); x[4 * 3 + 3] = tw16<INV>(x[15], -C1, -S1);
; #pragma unroll
;     for (int q1 = 0; q1 < 4; ++q1) dft4<INV>(x[4 * q1], x[4 * q1 + 1], x[4 * q1 + 2], x[4 * q1 + 3]);
; }
; template <bool INV, int LST, bool HALF = false> __device__ __forceinline__ void fft_pass16(LAS cf* z, const LAS cf* Thi, const LAS cf* Tlo, int tid) {
;     ...
;             dft16<true>(x);
; #pragma unroll
;             for (int m = 0; m < (HALF ? 8 : 16); ++m) z[pass_pos<LST>(base, phb, m)] = x[4 * (m & 3) + (m >> 2)];
	v_pk_mul_f32 v[102:103], v[100:101], v[68:69] op_sel:[0,0] op_sel_hi:[0,1] neg_hi:[0,1]
	s_mov_b64 s[44:45], 0
	v_pk_fma_f32 v[100:101], v[100:101], v[68:69], v[102:103] op_sel:[1,1,0] op_sel_hi:[1,0,1]
	v_pk_add_f32 v[102:103], v[74:75], v[86:87]
	v_pk_add_f32 v[74:75], v[74:75], v[86:87] neg_lo:[0,1] neg_hi:[0,1]
	v_pk_add_f32 v[86:87], v[78:79], v[94:95]
	v_pk_add_f32 v[78:79], v[78:79], v[94:95] neg_lo:[0,1] neg_hi:[0,1]
	v_pk_add_f32 v[94:95], v[102:103], v[86:87]
	v_pk_add_f32 v[86:87], v[102:103], v[86:87] neg_lo:[0,1] neg_hi:[0,1]
	v_pk_add_f32 v[102:103], v[74:75], v[78:79] op_sel:[0,1] op_sel_hi:[1,0] neg_lo:[0,1]
	v_pk_add_f32 v[74:75], v[74:75], v[78:79] op_sel:[0,1] op_sel_hi:[1,0] neg_hi:[0,1]
	v_pk_add_f32 v[78:79], v[70:71], v[88:89]
	v_pk_add_f32 v[70:71], v[70:71], v[88:89] neg_lo:[0,1] neg_hi:[0,1]
	v_pk_add_f32 v[88:89], v[80:81], v[96:97]
	v_pk_add_f32 v[80:81], v[80:81], v[96:97] neg_lo:[0,1] neg_hi:[0,1]
	v_pk_add_f32 v[96:97], v[78:79], v[88:89]
	v_pk_add_f32 v[78:79], v[78:79], v[88:89] neg_lo:[0,1] neg_hi:[0,1]
	v_pk_add_f32 v[88:89], v[70:71], v[80:81] op_sel:[0,1] op_sel_hi:[1,0] neg_lo:[0,1]
	v_pk_add_f32 v[70:71], v[70:71], v[80:81] op_sel:[0,1] op_sel_hi:[1,0] neg_hi:[0,1]
	v_pk_add_f32 v[80:81], v[72:73], v[90:91]
	v_pk_add_f32 v[72:73], v[72:73], v[90:91] neg_lo:[0,1] neg_hi:[0,1]
	v_pk_add_f32 v[90:91], v[82:83], v[98:99]
	v_pk_add_f32 v[82:83], v[82:83], v[98:99] neg_lo:[0,1] neg_hi:[0,1]
	v_pk_add_f32 v[98:99], v[80:81], v[90:91]
	v_pk_add_f32 v[80:81], v[80:81], v[90:91] neg_lo:[0,1] neg_hi:[0,1]
	v_pk_add_f32 v[90:91], v[72:73], v[82:83] op_sel:[0,1] op_sel_hi:[1,0] neg_lo:[0,1]
	v_pk_add_f32 v[72:73], v[72:73], v[82:83] op_sel:[0,1] op_sel_hi:[1,0] neg_hi:[0,1]
	v_pk_add_f32 v[82:83], v[76:77], v[92:93]
	v_pk_add_f32 v[76:77], v[76:77], v[92:93] neg_lo:[0,1] neg_hi:[0,1]
	v_pk_add_f32 v[92:93], v[84:85], v[100:101]
	v_pk_add_f32 v[84:85], v[84:85], v[100:101] neg_lo:[0,1] neg_hi:[0,1]
	v_pk_add_f32 v[100:101], v[82:83], v[92:93]
	v_pk_add_f32 v[82:83], v[82:83], v[92:93] neg_lo:[0,1] neg_hi:[0,1]
	v_pk_add_f32 v[92:93], v[76:77], v[84:85] op_sel:[0,1] op_sel_hi:[1,0] neg_lo:[0,1]
	v_pk_add_f32 v[76:77], v[76:77], v[84:85] op_sel:[0,1] op_sel_hi:[1,0] neg_hi:[0,1]
	v_pk_mul_f32 v[84:85], v[88:89], s[22:23] op_sel_hi:[1,0]
	s_nop 0
	v_pk_fma_f32 v[104:105], v[88:89], s[20:21], v[84:85] op_sel:[0,0,1] op_sel_hi:[1,0,0] neg_lo:[0,0,1]
	s_nop 0
	v_pk_mul_f32 v[84:85], v[90:91], s[24:25] op_sel_hi:[1,0]
	s_nop 0
	v_pk_fma_f32 v[88:89], v[90:91], s[24:25], v[84:85] op_sel:[0,0,1] op_sel_hi:[1,0,0] neg_lo:[0,0,1]
	v_pk_mul_f32 v[90:91], v[92:93], s[20:21] op_sel_hi:[1,0]
	s_nop 0
	v_pk_fma_f32 v[106:107], v[92:93], s[22:23], v[90:91] op_sel:[0,0,1] op_sel_hi:[1,0,0] neg_lo:[0,0,1]
	v_pk_add_f32 v[84:85], v[102:103], v[88:89]
	v_pk_mul_f32 v[90:91], v[78:79], s[24:25] op_sel_hi:[1,0]
	v_pk_add_f32 v[88:89], v[102:103], v[88:89] neg_lo:[0,1] neg_hi:[0,1]
	v_pk_fma_f32 v[92:93], v[78:79], s[24:25], v[90:91] op_sel:[0,0,1] op_sel_hi:[1,0,0] neg_lo:[0,0,1]
	s_nop 0
	v_pk_fma_f32 v[78:79], v[80:81], 0, v[80:81] op_sel:[0,0,1] op_sel_hi:[1,0,0] neg_lo:[0,0,1] neg_hi:[0,0,1]
	v_pk_fma_f32 v[80:81], v[80:81], 0, v[80:81] op_sel:[0,0,1] op_sel_hi:[1,0,0]
	s_nop 0
	v_mul_f32_e32 v80, 0x3f3504f3, v83
	v_mov_b32_e32 v79, v81
	v_pk_fma_f32 v[80:81], v[82:83], s[46:47], v[80:81] op_sel_hi:[0,1,0] neg_lo:[0,0,1] neg_hi:[0,0,1]
	v_pk_mul_f32 v[82:83], v[70:71], s[20:21] op_sel_hi:[1,0]
	s_movk_i32 s21, 0x2000
	v_pk_fma_f32 v[90:91], v[70:71], s[22:23], v[82:83] op_sel:[0,0,1] op_sel_hi:[1,0,0] neg_lo:[0,0,1] neg_hi:[0,0,1]
	v_pk_fma_f32 v[70:71], v[70:71], s[22:23], v[82:83] op_sel:[0,0,1] op_sel_hi:[1,0,0]
	s_mov_b32 s23, s37
	v_mul_f32_e32 v70, 0x3f3504f3, v73
	v_mov_b32_e32 v91, v71
	v_pk_fma_f32 v[70:71], v[72:73], s[46:47], v[70:71] op_sel_hi:[0,1,0] neg_lo:[0,0,1] neg_hi:[0,0,1]
	s_mov_b32 s46, s37
	s_mov_b32 s47, s36
	v_pk_mul_f32 v[72:73], v[76:77], s[46:47] op_sel_hi:[0,1]
	v_pk_fma_f32 v[72:73], v[76:77], s[22:23], v[72:73] op_sel:[1,0,0]
	v_pk_add_f32 v[76:77], v[94:95], v[98:99]
	v_pk_add_f32 v[82:83], v[94:95], v[98:99] neg_lo:[0,1] neg_hi:[0,1]
	v_pk_add_f32 v[94:95], v[96:97], v[100:101]
	v_pk_add_f32 v[96:97], v[96:97], v[100:101] neg_lo:[0,1] neg_hi:[0,1]
	v_pk_add_f32 v[98:99], v[76:77], v[94:95]
	v_pk_add_f32 v[76:77], v[76:77], v[94:95] neg_lo:[0,1] neg_hi:[0,1]
	v_pk_add_f32 v[94:95], v[82:83], v[96:97] op_sel:[0,1] op_sel_hi:[1,0] neg_lo:[0,1]
	v_pk_add_f32 v[82:83], v[82:83], v[96:97] op_sel:[0,1] op_sel_hi:[1,0] neg_hi:[0,1]
	v_pk_add_f32 v[96:97], v[104:105], v[106:107]
	v_pk_add_f32 v[100:101], v[104:105], v[106:107] neg_lo:[0,1] neg_hi:[0,1]
	v_pk_add_f32 v[102:103], v[84:85], v[96:97]
	v_pk_add_f32 v[84:85], v[84:85], v[96:97] neg_lo:[0,1] neg_hi:[0,1]
	v_pk_add_f32 v[96:97], v[88:89], v[100:101] op_sel:[0,1] op_sel_hi:[1,0] neg_lo:[0,1]
	v_pk_add_f32 v[88:89], v[88:89], v[100:101] op_sel:[0,1] op_sel_hi:[1,0] neg_hi:[0,1]
	v_pk_add_f32 v[100:101], v[86:87], v[78:79]
	v_pk_add_f32 v[78:79], v[86:87], v[78:79] neg_lo:[0,1] neg_hi:[0,1]
	v_pk_add_f32 v[86:87], v[92:93], v[80:81]
	v_pk_add_f32 v[80:81], v[92:93], v[80:81] neg_lo:[0,1] neg_hi:[0,1]
	v_pk_add_f32 v[92:93], v[100:101], v[86:87]
	v_pk_add_f32 v[86:87], v[100:101], v[86:87] neg_lo:[0,1] neg_hi:[0,1]
	v_pk_add_f32 v[100:101], v[78:79], v[80:81] op_sel:[0,1] op_sel_hi:[1,0] neg_lo:[0,1]
	v_pk_add_f32 v[78:79], v[78:79], v[80:81] op_sel:[0,1] op_sel_hi:[1,0] neg_hi:[0,1]
	v_pk_add_f32 v[80:81], v[74:75], v[70:71]
	v_pk_add_f32 v[70:71], v[74:75], v[70:71] neg_lo:[0,1] neg_hi:[0,1]
	v_pk_add_f32 v[74:75], v[90:91], v[72:73]
	v_pk_add_f32 v[72:73], v[90:91], v[72:73] neg_lo:[0,1] neg_hi:[0,1]
	v_pk_add_f32 v[90:91], v[80:81], v[74:75]
	v_pk_add_f32 v[74:75], v[80:81], v[74:75] neg_lo:[0,1] neg_hi:[0,1]
	v_pk_add_f32 v[80:81], v[70:71], v[72:73] op_sel:[0,1] op_sel_hi:[1,0] neg_lo:[0,1]
	v_pk_add_f32 v[70:71], v[70:71], v[72:73] op_sel:[0,1] op_sel_hi:[1,0] neg_hi:[0,1]
	ds_write_b64 v29, v[98:99]
	ds_write_b64 v37, v[102:103] offset:512
	ds_write_b64 v41, v[92:93] offset:1024
	ds_write_b64 v108, v[90:91] offset:1536
	ds_write_b64 v109, v[94:95] offset:2048
	ds_write_b64 v110, v[96:97] offset:2560
	ds_write_b64 v111, v[100:101] offset:3072
	ds_write_b64 v112, v[80:81] offset:3584
	ds_write_b64 v113, v[76:77] offset:4096
	ds_write_b64 v114, v[84:85] offset:4608
	ds_write_b64 v115, v[86:87] offset:5120
	ds_write_b64 v125, v[74:75] offset:5632
	ds_write_b64 v182, v[82:83] offset:6144
	ds_write_b64 v183, v[88:89] offset:6656
	ds_write_b64 v216, v[78:79] offset:7168
	ds_write_b64 v21, v[70:71] offset:7680
	s_cbranch_vccz .LBB0_1045

; template <bool INV, int LST, bool HALF = false> __device__ __forceinline__ void fft_pass16(LAS cf* z, const LAS cf* Thi, const LAS cf* Tlo, int tid) {
;     ...
;         const int g = tid + 512 * it; const int j0 = g & (st - 1); const int base = ((g >> LST) << (LST + 4)) + j0; const int phb = PH(base);
;         if (LST == 10 || it == 0) {
;             const int e1 = j0 << (10 - LST);
;             w[1] = cmul(Thi[e1 >> 7], Tlo[e1 & 127]);
;             w[2] = cmul(w[1], w[1]); w[3] = cmul(w[2], w[1]); w[4] = cmul(w[2], w[2]); w[5] = cmul(w[4], w[1]); w[6] = cmul(w[3], w[3]); w[7] = cmul(w[4], w[3]); w[8] = cmul(w[4], w[4]);
; #pragma unroll
;             for (int q = 9; q < 16; ++q) w[q] = cmul(w[8], w[q - 8]);
;         }
;         cf x[16];
;         if (!INV) {
; #pragma unroll
;             for (int m = 0; m < 16; ++m) { if (HALF && m >= 8) x[m] = (cf){0.f, 0.f}; else x[m] = z[pass_pos<LST>(base, phb, m)]; }
;             dft16<false, HALF>(x);
; #pragma unroll
;             for (int q = 0; q < 16; ++q) { cf y = x[4 * (q & 3) + (q >> 2)]; if (q) y = cmul(y, w[q]); z[pass_pos<LST>(base, phb, q)] = y; }
;         } else {
; #pragma unroll
;             for (int q = 0; q < 16; ++q) { cf y = z[pass_pos<LST>(base, phb, q)]; if (q) y = cmulc(y, w[q]); x[q] = y; }
.LBB0_1084:
	v_add_u32_e32 v21, s52, v152
	v_and_b32_e32 v22, 0x3ff, v21
	v_lshlrev_b32_e32 v23, 4, v21
	v_lshrrev_b32_e32 v21, 4, v21
	v_and_b32_e32 v23, 0x4000, v23
	v_and_b32_e32 v29, 60, v21
	v_and_b32_e32 v21, 56, v21
	v_bitop3_b32 v22, v23, v29, v22 bitop3:0x36
	v_add_u32_e32 v21, 0, v21
	v_lshl_add_u32 v29, v22, 3, 0
	v_add_u32_e32 v21, 0x20000, v21
	ds_read2st64_b64 v[84:87], v29 offset1:16
	ds_read2st64_b64 v[88:91], v29 offset0:32 offset1:48
	ds_read2st64_b64 v[92:95], v29 offset0:64 offset1:80
	ds_read2st64_b64 v[96:99], v29 offset0:96 offset1:112
	v_add_u32_e32 v30, 0x10000, v29
	v_add_u32_e32 v110, 0x1e000, v29
	v_add_u32_e32 v37, 0x12000, v29
	v_add_u32_e32 v41, 0x14000, v29
	v_add_u32_e32 v76, 0x16000, v29
	v_add_u32_e32 v78, 0x18000, v29
	v_add_u32_e32 v80, 0x1a000, v29
	v_add_u32_e32 v82, 0x1c000, v29
	ds_read_b64 v[22:23], v21
	ds_read_b64 v[30:31], v30
	ds_read_b64 v[38:39], v37
	ds_read_b64 v[42:43], v120
	ds_read_b64 v[100:101], v41
	ds_read_b64 v[102:103], v76
	ds_read_b64 v[104:105], v78
	ds_read_b64 v[106:107], v80
	ds_read_b64 v[108:109], v82
	ds_read_b64 v[110:111], v110
	s_waitcnt lgkmcnt(6)
	v_pk_mul_f32 v[112:113], v[22:23], v[42:43] op_sel:[0,0] op_sel_hi:[0,1]
	s_mov_b32 s21, s22
	v_pk_fma_f32 v[22:23], v[22:23], v[42:43], v[112:113] op_sel:[1,1,0] op_sel_hi:[1,0,1] neg_lo:[1,0,0]
	s_mov_b32 s23, s20
	v_pk_mul_f32 v[42:43], v[22:23], v[22:23] op_sel:[0,0] op_sel_hi:[0,1]
	v_pk_mul_f32 v[112:113], v[86:87], v[22:23] op_sel:[0,0] op_sel_hi:[0,1] neg_hi:[0,1]
	s_mov_b32 s48, s25
	v_pk_fma_f32 v[42:43], v[22:23], v[22:23], v[42:43] op_sel:[1,1,0] op_sel_hi:[1,0,1] neg_lo:[1,0,0]
	v_pk_fma_f32 v[86:87], v[86:87], v[22:23], v[112:113] op_sel:[1,1,0] op_sel_hi:[1,0,1]
	s_mov_b32 s49, s24
	v_pk_mul_f32 v[112:113], v[42:43], v[22:23] op_sel:[0,0] op_sel_hi:[0,1]
	v_pk_mul_f32 v[114:115], v[42:43], v[42:43] op_sel:[0,0] op_sel_hi:[0,1]
	v_pk_mul_f32 v[230:231], v[88:89], v[42:43] op_sel:[0,0] op_sel_hi:[0,1] neg_hi:[0,1]
	s_movk_i32 s52, 0x200
	v_pk_fma_f32 v[112:113], v[42:43], v[22:23], v[112:113] op_sel:[1,1,0] op_sel_hi:[1,0,1] neg_lo:[1,0,0]
	v_pk_fma_f32 v[114:115], v[42:43], v[42:43], v[114:115] op_sel:[1,1,0] op_sel_hi:[1,0,1] neg_lo:[1,0,0]
	v_pk_fma_f32 v[88:89], v[88:89], v[42:43], v[230:231] op_sel:[1,1,0] op_sel_hi:[1,0,1]
	s_and_b64 vcc, exec, s[46:47]
	v_pk_mul_f32 v[230:231], v[114:115], v[22:23] op_sel:[0,0] op_sel_hi:[0,1]
	v_pk_mul_f32 v[232:233], v[112:113], v[112:113] op_sel:[0,0] op_sel_hi:[0,1]
	v_pk_mul_f32 v[234:235], v[114:115], v[112:113] op_sel:[0,0] op_sel_hi:[0,1]
	v_pk_mul_f32 v[236:237], v[114:115], v[114:115] op_sel:[0,0] op_sel_hi:[0,1]
	v_pk_mul_f32 v[238:239], v[90:91], v[112:113] op_sel:[0,0] op_sel_hi:[0,1] neg_hi:[0,1]
	v_pk_mul_f32 v[240:241], v[92:93], v[114:115] op_sel:[0,0] op_sel_hi:[0,1] neg_hi:[0,1]
	s_nop 0
	v_pk_fma_f32 v[230:231], v[114:115], v[22:23], v[230:231] op_sel:[1,1,0] op_sel_hi:[1,0,1] neg_lo:[1,0,0]
	v_pk_fma_f32 v[232:233], v[112:113], v[112:113], v[232:233] op_sel:[1,1,0] op_sel_hi:[1,0,1] neg_lo:[1,0,0]
	v_pk_fma_f32 v[234:235], v[114:115], v[112:113], v[234:235] op_sel:[1,1,0] op_sel_hi:[1,0,1] neg_lo:[1,0,0]
	v_pk_fma_f32 v[236:237], v[114:115], v[114:115], v[236:237] op_sel:[1,1,0] op_sel_hi:[1,0,1] neg_lo:[1,0,0]
	v_pk_fma_f32 v[90:91], v[90:91], v[112:113], v[238:239] op_sel:[1,1,0] op_sel_hi:[1,0,1]
	v_pk_fma_f32 v[92:93], v[92:93], v[114:115], v[240:241] op_sel:[1,1,0] op_sel_hi:[1,0,1]
	s_nop 0
	v_pk_mul_f32 v[252:253], v[94:95], v[230:231] op_sel:[0,0] op_sel_hi:[0,1] neg_hi:[0,1]
	v_pk_mul_f32 v[216:217], v[96:97], v[232:233] op_sel:[0,0] op_sel_hi:[0,1] neg_hi:[0,1]
	v_pk_mul_f32 v[226:227], v[98:99], v[234:235] op_sel:[0,0] op_sel_hi:[0,1] neg_hi:[0,1]
	v_pk_mul_f32 v[238:239], v[236:237], v[22:23] op_sel:[0,0] op_sel_hi:[0,1]
	v_pk_mul_f32 v[240:241], v[236:237], v[42:43] op_sel:[0,0] op_sel_hi:[0,1]
	v_pk_mul_f32 v[242:243], v[236:237], v[112:113] op_sel:[0,0] op_sel_hi:[0,1]
	v_pk_mul_f32 v[244:245], v[236:237], v[114:115] op_sel:[0,0] op_sel_hi:[0,1]
	v_pk_mul_f32 v[182:183], v[30:31], v[236:237] op_sel:[0,0] op_sel_hi:[0,1] neg_hi:[0,1]
	v_pk_mul_f32 v[246:247], v[236:237], v[230:231] op_sel:[0,0] op_sel_hi:[0,1]
	s_nop 0
	v_pk_fma_f32 v[22:23], v[236:237], v[22:23], v[238:239] op_sel:[1,1,0] op_sel_hi:[1,0,1] neg_lo:[1,0,0]
	v_pk_fma_f32 v[42:43], v[236:237], v[42:43], v[240:241] op_sel:[1,1,0] op_sel_hi:[1,0,1] neg_lo:[1,0,0]
	v_pk_mul_f32 v[248:249], v[236:237], v[232:233] op_sel:[0,0] op_sel_hi:[0,1]
	v_pk_mul_f32 v[250:251], v[236:237], v[234:235] op_sel:[0,0] op_sel_hi:[0,1]
	v_pk_fma_f32 v[30:31], v[30:31], v[236:237], v[182:183] op_sel:[1,1,0] op_sel_hi:[1,0,1]
	v_pk_fma_f32 v[112:113], v[236:237], v[112:113], v[242:243] op_sel:[1,1,0] op_sel_hi:[1,0,1] neg_lo:[1,0,0]
	v_pk_fma_f32 v[114:115], v[236:237], v[114:115], v[244:245] op_sel:[1,1,0] op_sel_hi:[1,0,1] neg_lo:[1,0,0]
	v_pk_fma_f32 v[238:239], v[236:237], v[230:231], v[246:247] op_sel:[1,1,0] op_sel_hi:[1,0,1] neg_lo:[1,0,0]
	s_nop 0
	v_pk_fma_f32 v[240:241], v[236:237], v[232:233], v[248:249] op_sel:[1,1,0] op_sel_hi:[1,0,1] neg_lo:[1,0,0]
	v_pk_fma_f32 v[242:243], v[236:237], v[234:235], v[250:251] op_sel:[1,1,0] op_sel_hi:[1,0,1] neg_lo:[1,0,0]
	v_pk_fma_f32 v[94:95], v[94:95], v[230:231], v[252:253] op_sel:[1,1,0] op_sel_hi:[1,0,1]
	v_pk_fma_f32 v[96:97], v[96:97], v[232:233], v[216:217] op_sel:[1,1,0] op_sel_hi:[1,0,1]
	v_pk_fma_f32 v[98:99], v[98:99], v[234:235], v[226:227] op_sel:[1,1,0] op_sel_hi:[1,0,1]
	v_pk_mul_f32 v[182:183], v[38:39], v[22:23] op_sel:[0,0] op_sel_hi:[0,1] neg_hi:[0,1]
	s_waitcnt lgkmcnt(5)
; __device__ __forceinline__ cf add_mib(cf a, cf b) { cf r; asm("v_pk_add_f32 %0, %1, %2 op_sel:[0,1] op_sel_hi:[1,0] neg_hi:[0,1]" : "=v"(r) : "v"(a), "v"(b)); return r; }
; __device__ __forceinline__ cf add_pib(cf a, cf b) { cf r; asm("v_pk_add_f32 %0, %1, %2 op_sel:[0,1] op_sel_hi:[1,0] neg_lo:[0,1]" : "=v"(r) : "v"(a), "v"(b)); return r; }
; template <bool INV, bool HALFIN = false> __device__ __forceinline__ void dft16(cf (&x)[16]) {
; #pragma unroll
;     for (int m2 = 0; m2 < 4; ++m2) {
;         if (HALFIN) { const cf a0 = x[m2], a1 = x[4 + m2]; x[m2] = a0 + a1; x[8 + m2] = a0 - a1; x[4 + m2] = add_mib(a0, a1); x[12 + m2] = add_pib(a0, a1); }
;         else dft4<INV>(x[m2], x[4 + m2], x[8 + m2], x[12 + m2]);
;     }
;     constexpr float C1 = 0.9238795325112867f, S1 = 0.3826834323650898f, C2 = 0.7071067811865476f;
;     x[4 * 1 + 1] = tw16<INV>(x[5], C1, S1);  x[4 * 1 + 2] = tw16<INV>(x[6], C2, C2);   x[4 * 1 + 3] = tw16<INV>(x[7], S1, C1);
;     x[4 * 2 + 1] = tw16<INV>(x[9], C2, C2);  x[4 * 2 + 2] = tw16<INV>(x[10], 0.f, 1.f); x[4 * 2 + 3] = tw16<INV>(x[11], -C2, C2);
;     x[4 * 3 + 1] = tw16<INV>(x[13], S1, C1); x[4 * 3 + 2] = tw16<INV>(x[14], -C2, C2); x[4 * 3 + 3] = tw16<INV>(x[15], -C1, -S1);
; #pragma unroll
;     for (int q1 = 0; q1 < 4; ++q1) dft4<INV>(x[4 * q1], x[4 * q1 + 1], x[4 * q1 + 2], x[4 * q1 + 3]);
; }
; template <bool INV, int LST, bool HALF = false> __device__ __forceinline__ void fft_pass16(LAS cf* z, const LAS cf* Thi, const LAS cf* Tlo, int tid) {
;     ...
;             dft16<true>(x);
; #pragma unroll
;             for (int m = 0; m < (HALF ? 8 : 16); ++m) z[pass_pos<LST>(base, phb, m)] = x[4 * (m & 3) + (m >> 2)];
	v_pk_mul_f32 v[216:217], v[100:101], v[42:43] op_sel:[0,0] op_sel_hi:[0,1] neg_hi:[0,1]
	s_waitcnt lgkmcnt(4)
	v_pk_mul_f32 v[226:227], v[102:103], v[112:113] op_sel:[0,0] op_sel_hi:[0,1] neg_hi:[0,1]
	s_waitcnt lgkmcnt(3)
	v_pk_mul_f32 v[230:231], v[104:105], v[114:115] op_sel:[0,0] op_sel_hi:[0,1] neg_hi:[0,1]
	s_waitcnt lgkmcnt(2)
	v_pk_mul_f32 v[232:233], v[106:107], v[238:239] op_sel:[0,0] op_sel_hi:[0,1] neg_hi:[0,1]
	s_waitcnt lgkmcnt(1)
	v_pk_mul_f32 v[234:235], v[108:109], v[240:241] op_sel:[0,0] op_sel_hi:[0,1] neg_hi:[0,1]
	v_pk_add_f32 v[244:245], v[84:85], v[30:31]
	v_pk_add_f32 v[30:31], v[84:85], v[30:31] neg_lo:[0,1] neg_hi:[0,1]
	v_pk_fma_f32 v[22:23], v[38:39], v[22:23], v[182:183] op_sel:[1,1,0] op_sel_hi:[1,0,1]
	v_pk_fma_f32 v[38:39], v[100:101], v[42:43], v[216:217] op_sel:[1,1,0] op_sel_hi:[1,0,1]
	v_pk_fma_f32 v[42:43], v[102:103], v[112:113], v[226:227] op_sel:[1,1,0] op_sel_hi:[1,0,1]
	v_pk_fma_f32 v[84:85], v[104:105], v[114:115], v[230:231] op_sel:[1,1,0] op_sel_hi:[1,0,1]
	v_pk_fma_f32 v[100:101], v[106:107], v[238:239], v[232:233] op_sel:[1,1,0] op_sel_hi:[1,0,1]
	v_pk_fma_f32 v[102:103], v[108:109], v[240:241], v[234:235] op_sel:[1,1,0] op_sel_hi:[1,0,1]
	s_waitcnt lgkmcnt(0)
	v_pk_mul_f32 v[236:237], v[110:111], v[242:243] op_sel:[0,0] op_sel_hi:[0,1] neg_hi:[0,1]
	s_mov_b64 s[46:47], 0
	v_pk_fma_f32 v[104:105], v[110:111], v[242:243], v[236:237] op_sel:[1,1,0] op_sel_hi:[1,0,1]
	v_pk_add_f32 v[106:107], v[92:93], v[84:85]
	v_pk_add_f32 v[84:85], v[92:93], v[84:85] neg_lo:[0,1] neg_hi:[0,1]
	v_pk_add_f32 v[92:93], v[86:87], v[22:23]
	v_pk_add_f32 v[22:23], v[86:87], v[22:23] neg_lo:[0,1] neg_hi:[0,1]
	v_pk_add_f32 v[86:87], v[94:95], v[100:101]
	v_pk_add_f32 v[94:95], v[94:95], v[100:101] neg_lo:[0,1] neg_hi:[0,1]
	v_pk_add_f32 v[100:101], v[88:89], v[38:39]
	v_pk_add_f32 v[38:39], v[88:89], v[38:39] neg_lo:[0,1] neg_hi:[0,1]
	v_pk_add_f32 v[88:89], v[96:97], v[102:103]
	v_pk_add_f32 v[96:97], v[96:97], v[102:103] neg_lo:[0,1] neg_hi:[0,1]
	v_pk_add_f32 v[102:103], v[90:91], v[42:43]
	v_pk_add_f32 v[42:43], v[90:91], v[42:43] neg_lo:[0,1] neg_hi:[0,1]
	v_pk_add_f32 v[90:91], v[98:99], v[104:105]
	v_pk_add_f32 v[98:99], v[98:99], v[104:105] neg_lo:[0,1] neg_hi:[0,1]
	v_pk_add_f32 v[104:105], v[244:245], v[106:107]
	v_pk_add_f32 v[108:109], v[30:31], v[84:85] op_sel:[0,1] op_sel_hi:[1,0] neg_lo:[0,1]
	v_pk_add_f32 v[30:31], v[30:31], v[84:85] op_sel:[0,1] op_sel_hi:[1,0] neg_hi:[0,1]
	v_pk_add_f32 v[84:85], v[92:93], v[86:87]
	v_pk_add_f32 v[86:87], v[92:93], v[86:87] neg_lo:[0,1] neg_hi:[0,1]
	v_pk_add_f32 v[92:93], v[22:23], v[94:95] op_sel:[0,1] op_sel_hi:[1,0] neg_lo:[0,1]
	v_pk_add_f32 v[22:23], v[22:23], v[94:95] op_sel:[0,1] op_sel_hi:[1,0] neg_hi:[0,1]
	v_pk_add_f32 v[94:95], v[100:101], v[88:89]
	v_pk_add_f32 v[88:89], v[100:101], v[88:89] neg_lo:[0,1] neg_hi:[0,1]
	v_pk_add_f32 v[100:101], v[38:39], v[96:97] op_sel:[0,1] op_sel_hi:[1,0] neg_lo:[0,1]
	v_pk_add_f32 v[38:39], v[38:39], v[96:97] op_sel:[0,1] op_sel_hi:[1,0] neg_hi:[0,1]
	v_pk_add_f32 v[96:97], v[102:103], v[90:91]
	v_pk_add_f32 v[90:91], v[102:103], v[90:91] neg_lo:[0,1] neg_hi:[0,1]
	v_pk_add_f32 v[102:103], v[42:43], v[98:99] op_sel:[0,1] op_sel_hi:[1,0] neg_lo:[0,1]
	v_pk_add_f32 v[42:43], v[42:43], v[98:99] op_sel:[0,1] op_sel_hi:[1,0] neg_hi:[0,1]
	v_mul_f32_e32 v76, 0x3ec3ef15, v93
	v_mul_f32_e32 v78, 0x3ec3ef15, v92
	v_pk_mul_f32 v[98:99], v[100:101], s[24:25] op_sel_hi:[1,0]
	v_pk_mul_f32 v[110:111], v[102:103], s[20:21] op_sel_hi:[1,0]
	v_pk_mul_f32 v[112:113], v[86:87], s[24:25] op_sel_hi:[1,0]
	v_pk_fma_f32 v[114:115], v[88:89], 0, v[88:89] op_sel:[0,0,1] op_sel_hi:[1,0,0] neg_lo:[0,0,1]
	v_mul_f32_e32 v80, 0x3f3504f3, v91
	v_pk_mul_f32 v[182:183], v[22:23], s[20:21] op_sel_hi:[1,0]
	v_mul_f32_e32 v82, 0x3f3504f3, v39
	v_pk_add_f32 v[226:227], v[104:105], v[94:95]
	v_pk_add_f32 v[94:95], v[104:105], v[94:95] neg_lo:[0,1] neg_hi:[0,1]
	v_pk_add_f32 v[104:105], v[84:85], v[96:97]
	v_pk_add_f32 v[84:85], v[84:85], v[96:97] neg_lo:[0,1] neg_hi:[0,1]
	v_pk_fma_f32 v[96:97], v[92:93], s[20:21], v[76:77] op_sel_hi:[1,1,0] neg_lo:[0,0,1] neg_hi:[0,0,1]
	v_pk_fma_f32 v[92:93], v[92:93], s[22:23], v[78:79] op_sel_hi:[1,1,0]
	v_pk_fma_f32 v[230:231], v[100:101], s[24:25], v[98:99] op_sel:[0,0,1] op_sel_hi:[1,0,0] neg_lo:[0,0,1]
	v_pk_fma_f32 v[100:101], v[102:103], s[22:23], v[110:111] op_sel:[0,0,1] op_sel_hi:[1,0,0] neg_lo:[0,0,1]
	v_pk_mul_f32 v[216:217], v[42:43], s[20:21] op_sel_hi:[0,1]
	v_pk_fma_f32 v[110:111], v[86:87], s[24:25], v[112:113] op_sel:[0,0,1] op_sel_hi:[1,0,0] neg_lo:[0,0,1]
	v_pk_fma_f32 v[88:89], v[90:91], s[48:49], v[80:81] op_sel_hi:[0,1,0] neg_lo:[0,0,1] neg_hi:[0,0,1]
	v_pk_fma_f32 v[90:91], v[22:23], s[22:23], v[182:183] op_sel:[0,0,1] op_sel_hi:[1,0,0] neg_lo:[0,0,1]
	v_pk_fma_f32 v[38:39], v[38:39], s[48:49], v[82:83] op_sel_hi:[0,1,0] neg_lo:[0,0,1] neg_hi:[0,0,1]
	s_mov_b32 s23, s37
	v_mov_b32_e32 v97, v93
	v_pk_add_f32 v[106:107], v[244:245], v[106:107] neg_lo:[0,1] neg_hi:[0,1]
	v_pk_fma_f32 v[22:23], v[42:43], s[22:23], v[216:217] op_sel:[1,0,0] neg_lo:[0,0,1] neg_hi:[0,0,1]
	v_pk_add_f32 v[92:93], v[30:31], v[38:39]
	v_pk_add_f32 v[30:31], v[30:31], v[38:39] neg_lo:[0,1] neg_hi:[0,1]
	v_pk_add_f32 v[38:39], v[108:109], v[230:231]
	v_pk_add_f32 v[98:99], v[96:97], v[100:101]
	v_pk_add_f32 v[104:105], v[226:227], v[104:105]
	v_pk_add_f32 v[42:43], v[106:107], v[114:115]
	v_pk_add_f32 v[86:87], v[106:107], v[114:115] neg_lo:[0,1] neg_hi:[0,1]
	v_pk_add_f32 v[96:97], v[96:97], v[100:101] neg_lo:[0,1] neg_hi:[0,1]
	v_pk_add_f32 v[100:101], v[110:111], v[88:89]
	v_pk_add_f32 v[88:89], v[110:111], v[88:89] neg_lo:[0,1] neg_hi:[0,1]
	v_pk_add_f32 v[102:103], v[90:91], v[22:23]
	v_pk_add_f32 v[22:23], v[90:91], v[22:23] neg_lo:[0,1] neg_hi:[0,1]
	v_pk_add_f32 v[38:39], v[38:39], v[98:99]
	v_pk_add_f32 v[84:85], v[94:95], v[84:85] op_sel:[0,1] op_sel_hi:[1,0] neg_lo:[0,1]
	v_pk_add_f32 v[94:95], v[108:109], v[230:231] neg_lo:[0,1] neg_hi:[0,1]
	v_pk_add_f32 v[42:43], v[42:43], v[100:101]
	v_pk_add_f32 v[90:91], v[94:95], v[96:97] op_sel:[0,1] op_sel_hi:[1,0] neg_lo:[0,1]
	v_pk_add_f32 v[86:87], v[86:87], v[88:89] op_sel:[0,1] op_sel_hi:[1,0] neg_lo:[0,1]
	v_pk_add_f32 v[88:89], v[92:93], v[102:103]
	v_pk_add_f32 v[22:23], v[30:31], v[22:23] op_sel:[0,1] op_sel_hi:[1,0] neg_lo:[0,1]
	ds_write2st64_b64 v29, v[104:105], v[38:39] offset1:16
	ds_write2st64_b64 v29, v[42:43], v[88:89] offset0:32 offset1:48
	ds_write2st64_b64 v29, v[84:85], v[90:91] offset0:64 offset1:80
	ds_write2st64_b64 v29, v[86:87], v[22:23] offset0:96 offset1:112
	s_cbranch_vccnz .LBB0_1084
; #define LAS __attribute__((address_space(3)))
; __device__ __forceinline__ float bf_lo(unsigned w) { return __uint_as_float(w << 16); }
; __device__ __forceinline__ float bf_hi(unsigned w) { return __uint_as_float(w & 0xffff0000u); }
; __device__ __forceinline__ void conv8(const unsigned* zp, int cidx, float w0, float w1, float w2, float cb, float (&o)[8]) {
;     const u32x4 cur = *(const u32x4*)(zp + 4 * cidx); const unsigned prev = cidx > 0 ? zp[4 * cidx - 1] : 0u; const unsigned next = cidx < SEQ / 8 - 1 ? zp[4 * cidx + 4] : 0u;
;     const float zz[10] = {bf_hi(prev), bf_lo(cur.x), bf_hi(cur.x), bf_lo(cur.y), bf_hi(cur.y), bf_lo(cur.z), bf_hi(cur.z), bf_lo(cur.w), bf_hi(cur.w), bf_lo(next)};
; #pragma unroll
;     for (int e = 0; e < 8; ++e) o[e] = w0 * zz[e] + w1 * zz[e + 1] + w2 * zz[e + 2] + cb;
; }
; __device__ __forceinline__ void hyena_phase(LAS unsigned char* L, const Args& a, int vcu, int G) {
;     ...
;         float xa[2][8], xb[2][8];
;         {
;             const int r0a = ca, r0b = ca + 1;
;             const float wa0 = cw[r0a], wa1 = cw[3072 + r0a], wa2 = cw[6144 + r0a], c0a = cb[r0a];
;             const float wb0 = cw[r0b], wb1 = cw[3072 + r0b], wb2 = cw[6144 + r0b], c0b = cb[r0b];
;             const unsigned* p0a = (const unsigned*)(ZT + (size_t)r0a * ZLD + (size_t)b * SEQ); const unsigned* p0b = (const unsigned*)(ZT + (size_t)r0b * ZLD + (size_t)b * SEQ);
; #pragma unroll
;             for (int i = 0; i < 2; ++i) { const int cidx = tid + 512 * i; conv8(p0a, cidx, wa0, wa1, wa2, c0a, xa[i]); conv8(p0b, cidx, wb0, wb1, wb2, c0b, xb[i]); }
;         }
;         if (unit + G < 4096) HY_PREFETCH(unit + G);
;         fft_pass16<true, 10, true>(z, Thi, Tlo, tid);
;         {
;             const float ska = skip[ca], skb = skip[ca + 1];
;             u32x4* ga = (u32x4*)(Gc + (size_t)ca * GLD + (size_t)b * SEQ); u32x4* gb = (u32x4*)(Gc + (size_t)(ca + 1) * GLD + (size_t)b * SEQ);
; #pragma unroll
;             for (int i = 0; i < 2; ++i) { const int cidx = tid + 512 * i;
;                 float ya[8], yb[8];
; #pragma unroll
;                 for (int e = 0; e < 8; e += 2) { const f32x4 y = *(LAS f32x4*)(z + PH(8 * cidx + e)); ya[e] = y[0]; yb[e] = y[1]; ya[e + 1] = y[2]; yb[e + 1] = y[3]; }
	s_waitcnt vmcnt(0)
	v_and_b32_e32 v23, 0xffff0000, v60
	v_and_b32_e32 v60, 0xffff0000, v61
	v_mov_b32_e32 v84, v69
	v_mov_b32_e32 v85, v65
	v_mov_b32_e32 v22, v60
	v_lshlrev_b32_e32 v30, 16, v61
	v_pk_mul_f32 v[22:23], v[84:85], v[22:23]
	v_lshlrev_b32_e32 v61, 16, v62
	v_pk_fma_f32 v[22:23], v[84:85], v[30:31], v[22:23] op_sel:[0,0,1] op_sel_hi:[1,0,0]
	v_and_b32_e32 v39, 16, v63
	v_and_b32_e32 v38, 0xffff0000, v62
	v_pk_fma_f32 v[22:23], v[66:67], v[60:61], v[22:23] op_sel:[1,0,0]
	v_lshlrev_b32_e32 v91, 16, v74
	v_pk_add_f32 v[42:43], v[70:71], v[22:23] op_sel:[1,0]
	v_pk_mov_b32 v[22:23], v[60:61], v[38:39] op_sel:[1,0]
	v_and_b32_e32 v87, 0xffff0000, v74
	v_pk_mul_f32 v[22:23], v[68:69], v[22:23] op_sel:[1,0]
	v_and_b32_e32 v88, 0xffff0000, v63
	v_mov_b32_e32 v86, v91
	v_lshlrev_b32_e32 v93, 16, v63
	v_mov_b32_e32 v92, v38
	v_pk_fma_f32 v[22:23], v[64:65], v[60:61], v[22:23] op_sel:[1,0,0]
	v_and_b32_e32 v89, 16, v74
	v_mov_b32_e32 v90, v88
	v_pk_fma_f32 v[22:23], v[66:67], v[92:93], v[22:23] op_sel:[1,0,0]
	v_pk_mul_f32 v[30:31], v[68:69], v[86:87] op_sel:[1,0]
	v_pk_add_f32 v[38:39], v[70:71], v[22:23] op_sel:[1,0]
	v_pk_mov_b32 v[22:23], v[92:93], v[88:89] op_sel:[1,0]
	v_pk_fma_f32 v[30:31], v[64:65], v[90:91], v[30:31] op_sel:[1,0,0]
	v_mov_b32_e32 v82, v87
	v_and_b32_e32 v96, 0xffff0000, v57
	v_pk_mul_f32 v[22:23], v[68:69], v[22:23] op_sel:[1,0]
	v_pk_fma_f32 v[30:31], v[66:67], v[82:83], v[30:31] op_sel:[1,0,0]
	v_and_b32_e32 v61, 0xffff0000, v56
	v_mov_b32_e32 v82, v68
	v_mov_b32_e32 v83, v64
	v_mov_b32_e32 v60, v96
	v_pk_fma_f32 v[22:23], v[64:65], v[92:93], v[22:23] op_sel:[1,0,0]
	v_lshlrev_b32_e32 v56, 16, v57
	v_and_b32_e32 v88, 0xffff0000, v59
	v_and_b32_e32 v93, 16, v59
	v_and_b32_e32 v92, 0xffff0000, v58
	v_lshlrev_b32_e32 v95, 16, v59
	v_lshlrev_b32_e32 v97, 16, v58
	v_pk_mul_f32 v[58:59], v[82:83], v[60:61]
	v_mov_b32_e32 v94, v92
	v_pk_fma_f32 v[56:57], v[82:83], v[56:57], v[58:59] op_sel:[0,0,1] op_sel_hi:[1,0,0]
	s_add_u32 s38, s14, s38
	v_pk_fma_f32 v[56:57], v[66:67], v[96:97], v[56:57] op_sel_hi:[0,1,1]
	v_pk_add_f32 v[62:63], v[70:71], v[56:57] op_sel_hi:[0,1]
	v_pk_mov_b32 v[56:57], v[96:97], v[92:93] op_sel:[1,0]
	v_and_b32_e32 v89, 16, v72
	v_pk_mul_f32 v[56:57], v[68:69], v[56:57] op_sel_hi:[0,1]
	v_pk_fma_f32 v[56:57], v[64:65], v[96:97], v[56:57] op_sel_hi:[0,1,1]
	v_pk_fma_f32 v[56:57], v[66:67], v[94:95], v[56:57] op_sel_hi:[0,1,1]
	s_addc_u32 s39, s15, s39
	v_pk_fma_f32 v[22:23], v[66:67], v[90:91], v[22:23] op_sel:[1,0,0]
	v_mov_b32_e32 v90, v88
	v_pk_add_f32 v[60:61], v[70:71], v[56:57] op_sel_hi:[0,1]
	v_pk_mov_b32 v[56:57], v[94:95], v[88:89] op_sel:[1,0]
	s_waitcnt lgkmcnt(0)
	s_barrier
	global_load_dwordx2 v[88:89], v117, s[38:39]
	v_and_b32_e32 v87, 0xffff0000, v72
	v_lshlrev_b32_e32 v91, 16, v72
	v_lshlrev_b32_e32 v72, 16, v52
	v_and_b32_e32 v52, 0xffff0000, v52
	v_mov_b32_e32 v78, v52
	v_pk_mul_f32 v[78:79], v[84:85], v[78:79]
	v_and_b32_e32 v92, 0xffff0000, v53
	v_lshlrev_b32_e32 v53, 16, v53
	v_pk_fma_f32 v[78:79], v[84:85], v[72:73], v[78:79] op_sel:[0,0,1] op_sel_hi:[1,0,0]
	v_mov_b32_e32 v86, v91
	v_and_b32_e32 v93, 16, v54
	v_pk_fma_f32 v[78:79], v[66:67], v[52:53], v[78:79] op_sel:[1,0,0]
	v_pk_mul_f32 v[56:57], v[68:69], v[56:57] op_sel_hi:[0,1]
	v_pk_mul_f32 v[58:59], v[68:69], v[86:87] op_sel_hi:[0,1]
	v_pk_add_f32 v[84:85], v[70:71], v[78:79] op_sel:[1,0]
	v_pk_mov_b32 v[78:79], v[52:53], v[92:93] op_sel:[1,0]
	v_pk_fma_f32 v[56:57], v[64:65], v[94:95], v[56:57] op_sel_hi:[0,1,1]
	v_pk_fma_f32 v[58:59], v[64:65], v[90:91], v[58:59] op_sel_hi:[0,1,1]
	v_mov_b32_e32 v80, v87
	v_pk_mul_f32 v[78:79], v[68:69], v[78:79] op_sel:[1,0]
	v_pk_fma_f32 v[56:57], v[66:67], v[90:91], v[56:57] op_sel_hi:[0,1,1]
	v_pk_fma_f32 v[58:59], v[66:67], v[80:81], v[58:59] op_sel_hi:[0,1,1]
	v_and_b32_e32 v81, 0xffff0000, v55
	v_and_b32_e32 v87, 16, v55
	v_and_b32_e32 v86, 0xffff0000, v54
	v_lshlrev_b32_e32 v91, 16, v55
	v_lshlrev_b32_e32 v55, 16, v54
	v_mov_b32_e32 v54, v92
	v_pk_fma_f32 v[52:53], v[64:65], v[52:53], v[78:79] op_sel:[1,0,0]
	v_mov_b32_e32 v90, v86
	v_pk_fma_f32 v[52:53], v[66:67], v[54:55], v[52:53] op_sel:[1,0,0]
	v_mov_b32_e32 v80, v91
	v_pk_add_f32 v[92:93], v[70:71], v[52:53] op_sel:[1,0]
	v_pk_mov_b32 v[52:53], v[54:55], v[86:87] op_sel:[1,0]
	v_mov_b32_e32 v76, v81
	v_pk_mul_f32 v[52:53], v[68:69], v[52:53] op_sel:[1,0]
	v_lshlrev_b32_e32 v79, 16, v51
	v_pk_fma_f32 v[52:53], v[64:65], v[54:55], v[52:53] op_sel:[1,0,0]
	v_and_b32_e32 v55, 0xffff0000, v51
	v_pk_fma_f32 v[52:53], v[66:67], v[90:91], v[52:53] op_sel:[1,0,0]
	v_mov_b32_e32 v54, v79
	v_pk_add_f32 v[86:87], v[70:71], v[52:53] op_sel:[1,0]
	v_pk_mul_f32 v[52:53], v[68:69], v[80:81] op_sel:[1,0]
	v_and_b32_e32 v80, 0xffff0000, v49
	v_pk_fma_f32 v[52:53], v[64:65], v[90:91], v[52:53] op_sel:[1,0,0]
	v_lshlrev_b32_e32 v49, 16, v49
	v_pk_fma_f32 v[52:53], v[66:67], v[76:77], v[52:53] op_sel:[1,0,0]
	v_and_b32_e32 v81, 16, v50
	v_pk_add_f32 v[90:91], v[70:71], v[52:53] op_sel:[1,0]
	v_lshlrev_b32_e32 v52, 16, v48
	v_and_b32_e32 v48, 0xffff0000, v48
	v_mov_b32_e32 v74, v48
	v_pk_mul_f32 v[74:75], v[82:83], v[74:75]
	v_and_b32_e32 v77, 16, v51
	v_pk_fma_f32 v[52:53], v[82:83], v[52:53], v[74:75] op_sel:[0,0,1] op_sel_hi:[1,0,0]
	v_and_b32_e32 v76, 0xffff0000, v50
	v_pk_fma_f32 v[52:53], v[66:67], v[48:49], v[52:53] op_sel_hi:[0,1,1]
	v_pk_add_f32 v[82:83], v[70:71], v[52:53] op_sel_hi:[0,1]
	v_pk_mov_b32 v[52:53], v[48:49], v[80:81] op_sel:[1,0]
	v_lshlrev_b32_e32 v51, 16, v50
	v_pk_mul_f32 v[52:53], v[68:69], v[52:53] op_sel_hi:[0,1]
	v_mov_b32_e32 v50, v80
	v_pk_fma_f32 v[48:49], v[64:65], v[48:49], v[52:53] op_sel_hi:[0,1,1]
	v_pk_fma_f32 v[48:49], v[66:67], v[50:51], v[48:49] op_sel_hi:[0,1,1]
	v_pk_add_f32 v[80:81], v[70:71], v[48:49] op_sel_hi:[0,1]
	v_pk_mov_b32 v[48:49], v[50:51], v[76:77] op_sel:[1,0]
	v_mov_b32_e32 v78, v76
	v_pk_mul_f32 v[48:49], v[68:69], v[48:49] op_sel_hi:[0,1]
	v_pk_fma_f32 v[48:49], v[64:65], v[50:51], v[48:49] op_sel_hi:[0,1,1]
	v_pk_fma_f32 v[48:49], v[66:67], v[78:79], v[48:49] op_sel_hi:[0,1,1]
	v_pk_add_f32 v[94:95], v[70:71], v[48:49] op_sel_hi:[0,1]
	v_pk_mul_f32 v[48:49], v[68:69], v[54:55] op_sel_hi:[0,1]
	v_pk_fma_f32 v[48:49], v[64:65], v[78:79], v[48:49] op_sel_hi:[0,1,1]
	v_mov_b32_e32 v72, v55
	v_pk_fma_f32 v[48:49], v[66:67], v[72:73], v[48:49] op_sel_hi:[0,1,1]
	v_pk_add_f32 v[22:23], v[70:71], v[22:23] op_sel:[1,0]
	v_pk_add_f32 v[30:31], v[70:71], v[30:31] op_sel:[1,0]
	v_pk_add_f32 v[56:57], v[70:71], v[56:57] op_sel_hi:[0,1]
	v_pk_add_f32 v[58:59], v[70:71], v[58:59] op_sel_hi:[0,1]
	v_pk_add_f32 v[96:97], v[70:71], v[48:49] op_sel_hi:[0,1]
	ds_read_b128 v[48:51], v178
	ds_read_b128 v[52:55], v179
	ds_read_b128 v[64:67], v180
	ds_read_b128 v[68:71], v181
	ds_read_b128 v[72:75], v177
	s_lshl_b64 s[38:39], s[44:45], 1
	s_waitcnt lgkmcnt(4)
; __device__ __forceinline__ unsigned pk2(float lo, float hi) { f32x2 v = {lo, hi}; bf16x2_t b = __builtin_convertvector(v, bf16x2_t); return __builtin_bit_cast(unsigned, b); }
; #define LAS __attribute__((address_space(3)))
; __device__ __forceinline__ void hyena_phase(LAS unsigned char* L, const Args& a, int vcu, int G) {
;     ...
;         {
;             const float ska = skip[ca], skb = skip[ca + 1];
;             u32x4* ga = (u32x4*)(Gc + (size_t)ca * GLD + (size_t)b * SEQ); u32x4* gb = (u32x4*)(Gc + (size_t)(ca + 1) * GLD + (size_t)b * SEQ);
; #pragma unroll
;             for (int i = 0; i < 2; ++i) { const int cidx = tid + 512 * i;
;                 float ya[8], yb[8];
; #pragma unroll
;                 for (int e = 0; e < 8; e += 2) { const f32x4 y = *(LAS f32x4*)(z + PH(8 * cidx + e)); ya[e] = y[0]; yb[e] = y[1]; ya[e + 1] = y[2]; yb[e + 1] = y[3]; }
;                 u32x4 oa, ob;
;                 oa.x = pk2((ya[0] + ua[i][0] * ska) * xa[i][0], (ya[1] + ua[i][1] * ska) * xa[i][1]); oa.y = pk2((ya[2] + ua[i][2] * ska) * xa[i][2], (ya[3] + ua[i][3] * ska) * xa[i][3]);
;                 oa.z = pk2((ya[4] + ua[i][4] * ska) * xa[i][4], (ya[5] + ua[i][5] * ska) * xa[i][5]); oa.w = pk2((ya[6] + ua[i][6] * ska) * xa[i][6], (ya[7] + ua[i][7] * ska) * xa[i][7]);
;                 ob.x = pk2((yb[0] + ub[i][0] * skb) * xb[i][0], (yb[1] + ub[i][1] * skb) * xb[i][1]); ob.y = pk2((yb[2] + ub[i][2] * skb) * xb[i][2], (yb[3] + ub[i][3] * skb) * xb[i][3]);
;                 ob.z = pk2((yb[4] + ub[i][4] * skb) * xb[i][4], (yb[5] + ub[i][5] * skb) * xb[i][5]); ob.w = pk2((yb[6] + ub[i][6] * skb) * xb[i][6], (yb[7] + ub[i][7] * skb) * xb[i][7]);
;                 ga[cidx] = oa; gb[cidx] = ob; }
;         }
;         __syncthreads();
	v_mov_b32_e32 v76, v48
	v_mov_b32_e32 v77, v50
	s_waitcnt lgkmcnt(3)
	v_mov_b32_e32 v78, v52
	v_mov_b32_e32 v79, v54
	s_add_u32 s21, s60, s38
	s_waitcnt vmcnt(0)
	v_pk_fma_f32 v[76:77], v[132:133], v[88:89], v[76:77] op_sel_hi:[1,0,1]
	v_pk_fma_f32 v[78:79], v[128:129], v[88:89], v[78:79] op_sel_hi:[1,0,1]
	s_addc_u32 s23, s61, s39
	v_pk_mul_f32 v[76:77], v[82:83], v[76:77]
	v_pk_mul_f32 v[78:79], v[80:81], v[78:79]
	s_add_u32 s38, s21, s73
	v_cvt_pk_bf16_f32 v76, v76, v77
	v_cvt_pk_bf16_f32 v77, v78, v79
	s_waitcnt lgkmcnt(2)
	v_mov_b32_e32 v78, v64
	v_mov_b32_e32 v79, v66
	v_mov_b32_e32 v50, v49
	v_mov_b32_e32 v54, v53
	s_addc_u32 s39, s23, 0
	s_lshl_b64 s[40:41], s[40:41], 1
	v_pk_fma_f32 v[78:79], v[130:131], v[88:89], v[78:79] op_sel_hi:[1,0,1]
	v_pk_fma_f32 v[48:49], v[134:135], v[88:89], v[50:51] op_sel:[0,1,0]
	v_pk_fma_f32 v[50:51], v[136:137], v[88:89], v[54:55] op_sel:[0,1,0]
	s_add_u32 s21, s60, s40
	v_pk_mul_f32 v[78:79], v[94:95], v[78:79]
	s_waitcnt lgkmcnt(1)
	v_mov_b32_e32 v94, v68
	v_mov_b32_e32 v95, v70
	v_pk_mul_f32 v[48:49], v[84:85], v[48:49]
	v_pk_mul_f32 v[50:51], v[92:93], v[50:51]
	v_mov_b32_e32 v66, v65
	v_mov_b32_e32 v70, v69
	s_addc_u32 s23, s61, s41
	ds_read_b128 v[80:83], v210
	v_pk_fma_f32 v[94:95], v[126:127], v[88:89], v[94:95] op_sel_hi:[1,0,1]
	v_cvt_pk_bf16_f32 v48, v48, v49
	v_cvt_pk_bf16_f32 v49, v50, v51
	v_pk_fma_f32 v[50:51], v[140:141], v[88:89], v[66:67] op_sel:[0,1,0]
	v_pk_fma_f32 v[52:53], v[138:139], v[88:89], v[70:71] op_sel:[0,1,0]
	s_add_u32 s40, s21, s73
	v_pk_mul_f32 v[94:95], v[96:97], v[94:95]
	v_pk_mul_f32 v[50:51], v[86:87], v[50:51]
	v_pk_mul_f32 v[52:53], v[90:91], v[52:53]
	s_addc_u32 s41, s23, 0
	v_cvt_pk_bf16_f32 v78, v78, v79
	v_cvt_pk_bf16_f32 v79, v94, v95
	v_cvt_pk_bf16_f32 v50, v50, v51
	v_cvt_pk_bf16_f32 v51, v52, v53
	global_store_dwordx4 v124, v[76:79], s[38:39]
	global_store_dwordx4 v124, v[48:51], s[40:41]
	s_waitcnt lgkmcnt(1)
	v_mov_b32_e32 v64, v72
	v_mov_b32_e32 v65, v74
	ds_read_b128 v[48:51], v211
	ds_read_b128 v[52:55], v212
	v_pk_fma_f32 v[64:65], v[142:143], v[88:89], v[64:65] op_sel_hi:[1,0,1]
	v_mov_b32_e32 v74, v73
	v_pk_mul_f32 v[62:63], v[62:63], v[64:65]
	s_waitcnt lgkmcnt(2)
	v_mov_b32_e32 v64, v80
	v_mov_b32_e32 v65, v82
	v_pk_fma_f32 v[64:65], v[144:145], v[88:89], v[64:65] op_sel_hi:[1,0,1]
	v_cvt_pk_bf16_f32 v62, v62, v63
	v_pk_mul_f32 v[60:61], v[60:61], v[64:65]
	v_mov_b32_e32 v82, v81
	v_cvt_pk_bf16_f32 v63, v60, v61
	s_waitcnt lgkmcnt(1)
	v_mov_b32_e32 v60, v48
	v_mov_b32_e32 v61, v50
	v_pk_fma_f32 v[60:61], v[148:149], v[88:89], v[60:61] op_sel_hi:[1,0,1]
	v_mov_b32_e32 v50, v49
	v_pk_mul_f32 v[56:57], v[56:57], v[60:61]
	v_mov_b32_e32 v125, v117
	v_cvt_pk_bf16_f32 v64, v56, v57
	s_waitcnt lgkmcnt(0)
	v_mov_b32_e32 v56, v52
	v_mov_b32_e32 v57, v54
	v_pk_fma_f32 v[56:57], v[146:147], v[88:89], v[56:57] op_sel_hi:[1,0,1]
	v_mov_b32_e32 v54, v53
	v_pk_mul_f32 v[56:57], v[58:59], v[56:57]
	v_lshl_add_u64 v[66:67], s[38:39], 0, v[124:125]
	v_cvt_pk_bf16_f32 v65, v56, v57
	v_pk_fma_f32 v[56:57], v[150:151], v[88:89], v[74:75] op_sel:[0,1,0]
	v_lshl_add_u64 v[68:69], s[40:41], 0, v[124:125]
	v_pk_mul_f32 v[42:43], v[42:43], v[56:57]
	s_nop 0
	v_cvt_pk_bf16_f32 v56, v42, v43
	v_pk_fma_f32 v[42:43], v[154:155], v[88:89], v[82:83] op_sel:[0,1,0]
	s_nop 0
	v_pk_mul_f32 v[38:39], v[38:39], v[42:43]
	s_nop 0
	v_cvt_pk_bf16_f32 v57, v38, v39
	v_pk_fma_f32 v[38:39], v[158:159], v[88:89], v[50:51] op_sel:[0,1,0]
	s_nop 0
	v_pk_mul_f32 v[22:23], v[22:23], v[38:39]
	s_nop 0
	v_cvt_pk_bf16_f32 v58, v22, v23
	v_pk_fma_f32 v[22:23], v[156:157], v[88:89], v[54:55] op_sel:[0,1,0]
	s_nop 0
	v_pk_mul_f32 v[22:23], v[30:31], v[22:23]
	s_nop 0
	v_cvt_pk_bf16_f32 v59, v22, v23
	v_add_co_u32_e32 v22, vcc, s72, v66
	s_nop 1
	v_addc_co_u32_e32 v23, vcc, 0, v67, vcc
	global_store_dwordx4 v[22:23], v[62:65], off
	v_add_co_u32_e32 v22, vcc, 0x2000, v68
	s_nop 1
	v_addc_co_u32_e32 v23, vcc, 0, v69, vcc
	s_andn2_b64 vcc, exec, s[42:43]
	global_store_dwordx4 v[22:23], v[56:59], off
	s_barrier
	s_cbranch_vccnz .LBB0_1019
	v_lshrrev_b32_e32 v228, 6, v152
